# residual-store whole-line exchange done with exec-masked v_swap instead of 16 v_cndmask per row group; on top of the stacked version
# speedup vs baseline: 1.0001x; 1.0001x over previous
;     DI void operator()(AccRef acc, const Unit& u, int wr, int wc, int fr, int fq) const {
;     ...
; #pragma unroll
;         for (int ai = 0; ai < 2; ++ai) {
;             const int rb = u.pm * 256 + ai * 128 + wr * 64 + fr;
;             int mb, pos0, kv0; row_info(rb, mb, pos0, kv0);
;             f32x4 gt[2][2], gs[2][2];
; #pragma unroll
;             for (int bj = 0; bj < 2; ++bj)
; #pragma unroll
;                 for (int n = 0; n < 2; ++n) {
;                     const int c = u.pn * 256 + bj * 128 + cl + 4 * n;
;                     gt[bj][n] = *(const f32x4*)(gate + (size_t)mb * 6144 + c);
;                     if (ap) { const f32x4 g = *(const f32x4*)(gn + c), s = *(const f32x4*)(scn + (size_t)mb * 6144 + c); gs[bj][n] = g * (s + 1.f); }
;                 }
; #pragma unroll
;             for (int m = 0; m < 4; ++m) {
;                 const int row = rb + 16 * m;
;                 const float* xi = row < MP ? xin_p + (size_t)row * 1024 : xin_s + (size_t)(row - MP) * 1024;
.LBB0_1094:
	v_readlane_b32 s3, v253, 32
	v_mbcnt_lo_u32_b32 v100, -1, 0
	v_mbcnt_hi_u32_b32 v100, -1, v100
	s_mov_b32 s3, s30
	v_and_b32_e32 v202, 15, v100
	v_bfe_u32 v204, v100, 4, 2
	s_mov_b32 s12, s36
	s_lshl_b32 s16, s16, 8
	s_lshl_b32 s3, s3, 6
	s_add_i32 s3, s3, s16
	v_add_u32_e32 v192, s3, v202
	s_lshl_b32 s13, s12, 5
	s_lshl_b32 s3, s2, 8
	v_add_u32_e32 v224, 0xffffc000, v192
	s_add_i32 s13, s13, s3
	v_lshrrev_b32_e32 v101, 6, v224
	v_lshl_add_u32 v188, v204, 3, s13
	v_ashrrev_i32_e32 v100, 11, v192
	v_add_u32_e32 v101, 8, v101
	v_cmp_gt_i32_e32 vcc, s94, v192
	v_mov_b64_e32 v[102:103], s[60:61]
	v_ashrrev_i32_e32 v189, 31, v188
	v_cndmask_b32_e32 v104, v101, v100, vcc
	v_mov_b64_e32 v[100:101], s[8:9]
	v_mad_i64_i32 v[100:101], s[16:17], v104, s75, v[100:101]
	v_mad_i64_i32 v[102:103], s[16:17], v104, s75, v[102:103]
	v_lshlrev_b64 v[190:191], 2, v[188:189]
	v_lshl_add_u64 v[104:105], v[100:101], 0, v[190:191]
	v_lshl_add_u64 v[194:195], s[72:73], 0, v[190:191]
	v_lshl_add_u64 v[168:169], v[102:103], 0, v[190:191]
	global_load_dwordx4 v[108:111], v[104:105], off offset:16
	global_load_dwordx4 v[116:119], v[104:105], off
	global_load_dwordx4 v[148:151], v[194:195], off offset:16
	global_load_dwordx4 v[164:167], v[194:195], off
	global_load_dwordx4 v[160:163], v[168:169], off offset:16
	global_load_dwordx4 v[172:175], v[168:169], off
	global_load_dwordx4 v[100:103], v[104:105], off offset:528
	s_nop 0
	global_load_dwordx4 v[104:107], v[104:105], off offset:512
	s_nop 0
	global_load_dwordx4 v[144:147], v[194:195], off offset:528
	global_load_dwordx4 v[156:159], v[194:195], off offset:512
	global_load_dwordx4 v[152:155], v[168:169], off offset:528
	s_nop 0
	global_load_dwordx4 v[168:171], v[168:169], off offset:512
	s_movk_i32 s3, 0x3fff
	v_cmp_lt_i32_e32 vcc, s3, v192
	s_and_saveexec_b64 s[16:17], vcc
	s_xor_b64 s[16:17], exec, s[16:17]
	v_lshlrev_b64 v[196:197], 12, v[224:225]
	v_mov_b32_e32 v193, v225
	v_lshl_add_u64 v[198:199], s[20:21], 0, v[196:197]
	v_lshlrev_b64 v[196:197], 12, v[192:193]
	s_andn2_saveexec_b64 s[16:17], s[16:17]
	v_ashrrev_i32_e32 v193, 31, v192
	v_lshlrev_b64 v[196:197], 12, v[192:193]
	v_lshl_add_u64 v[198:199], s[42:43], 0, v[196:197]
	s_or_b64 exec, exec, s[16:17]
	s_mov_b32 s18, 0xff00ff
	s_mov_b32 s19, 0xff00ff
	s_sub_u32 s82, s20, 0x4000000
	s_subb_u32 s83, s21, 0
	s_cmp_ge_u32 s16, 0x4000
	s_cselect_b32 s82, s82, s42
	s_cselect_b32 s83, s83, s43
	v_lshl_add_u32 v206, v192, 12, v190
	v_lshlrev_b32_e32 v213, 4, v204
	v_sub_u32_e32 v206, v206, v213
	v_lshlrev_b32_e32 v213, 11, v192
	v_lshlrev_b32_e32 v209, 6, v192
	v_mov_b32_e32 v207, v206
	v_lshl_add_u32 v208, v188, 1, v213
	global_load_dwordx4 v[232:235], v206, s[82:83] offset:64
	global_load_dwordx4 v[240:243], v206, s[82:83] offset:576
	global_load_dwordx4 v[228:231], v206, s[82:83]
	global_load_dwordx4 v[236:239], v206, s[82:83] offset:512
	v_add_u32_e32 v206, 0x10000, v206
	global_load_dwordx4 v[248:251], v206, s[82:83] offset:64
	global_load_dwordx4 v[220:223], v206, s[82:83] offset:576
	global_load_dwordx4 v[244:247], v206, s[82:83]
	global_load_dwordx4 v[216:219], v206, s[82:83] offset:512
	v_add_u32_e32 v206, 0x10000, v206
	s_waitcnt vmcnt(8)
	v_pk_add_f32 v[172:173], v[172:173], 1.0 op_sel_hi:[1,0]
	v_pk_add_f32 v[154:155], v[154:155], 1.0 op_sel_hi:[1,0]
	v_pk_mul_f32 v[164:165], v[164:165], v[172:173]
	v_pk_add_f32 v[172:173], v[160:161], 1.0 op_sel_hi:[1,0]
	v_pk_add_f32 v[160:161], v[162:163], 1.0 op_sel_hi:[1,0]
	v_pk_mul_f32 v[162:163], v[148:149], v[172:173]
	v_pk_mul_f32 v[160:161], v[150:151], v[160:161]
	v_pk_add_f32 v[148:149], v[170:171], 1.0 op_sel_hi:[1,0]
	v_pk_add_f32 v[150:151], v[168:169], 1.0 op_sel_hi:[1,0]
	v_pk_mul_f32 v[146:147], v[146:147], v[154:155]
	v_lshl_add_u64 v[154:155], v[198:199], 0, v[190:191]
	v_pk_mul_f32 v[148:149], v[158:159], v[148:149]
	v_pk_mul_f32 v[150:151], v[156:157], v[150:151]
	v_pk_add_f32 v[174:175], v[174:175], 1.0 op_sel_hi:[1,0]
	v_pk_add_f32 v[152:153], v[152:153], 1.0 op_sel_hi:[1,0]
	v_pk_mul_f32 v[166:167], v[166:167], v[174:175]
	v_pk_mul_f32 v[144:145], v[144:145], v[152:153]
	v_lshlrev_b64 v[152:153], 11, v[192:193]
	v_lshl_add_u64 v[152:153], s[64:65], 0, v[152:153]
	v_lshlrev_b32_e32 v202, 2, v202
	v_lshl_add_u32 v202, v204, 6, v202
	v_xor_b32_e32 v203, 64, v202
	s_lshl_b32 s2, s2, 2
	v_xor_b32_e32 v202, 0x80, v202
	s_ashr_i32 s3, s2, 31
	s_ashr_i32 s13, s12, 31
	s_lshl_b64 s[2:3], s[2:3], 2
	s_add_u32 s16, s39, s2
	s_addc_u32 s17, s40, s3
	s_lshl_b64 s[2:3], s[12:13], 2
	s_add_u32 s90, s16, s2
	v_cmp_eq_u32_e32 vcc, 0, v204
	s_addc_u32 s91, s17, s3
	s_waitcnt vmcnt(4)
; DI u32x4 pack8(const float* v) { u32x4 w; w.x = pk2(v[0], v[1]); w.y = pk2(v[2], v[3]); w.z = pk2(v[4], v[5]); w.w = pk2(v[6], v[7]); return w; }
; #define xor16_32(s) xor16_32_l((s), fr + 16 * fq)
;     DI void operator()(AccRef acc, const Unit& u, int wr, int wc, int fr, int fq) const {
;     ...
; #pragma unroll
;                 for (int bj = 0; bj < 2; ++bj) {
;                     const int c = u.pn * 256 + bj * 128 + cl;
;                     float v[8];
; #pragma unroll
;                     for (int n = 0; n < 2; ++n) {
;                         const f32x4 x = *(const f32x4*)(xi + c + 4 * n);
;                         const f32x4 y = x + gt[bj][n] * acc[ai][bj][m][n];
;                         *(f32x4*)(xout + (size_t)row * 1024 + c + 4 * n) = y;
; #pragma unroll
;                         for (int j = 0; j < 4; ++j) { s += y[j] * y[j]; v[4 * n + j] = ap ? y[j] * gs[bj][n][j] : 0.f; }
;                     }
;                     if (ap) *(u32x4*)(ap + (size_t)row * 1024 + c) = pack8(v);
;                 }
;                 s = xor16_32(s);
;                 if (fq == 0) ssq[(size_t)row * 16 + u.pn * 4 + wc] = s;
	v_permlane32_swap_b32_e32 v228, v232
	v_permlane32_swap_b32_e32 v229, v233
	v_permlane32_swap_b32_e32 v230, v234
	v_permlane32_swap_b32_e32 v231, v235
	v_permlane32_swap_b32_e32 v236, v240
	v_permlane32_swap_b32_e32 v237, v241
	v_permlane32_swap_b32_e32 v238, v242
	v_permlane32_swap_b32_e32 v239, v243
	v_permlane16_swap_b32_e32 v228, v232
	v_permlane16_swap_b32_e32 v229, v233
	v_permlane16_swap_b32_e32 v230, v234
	v_permlane16_swap_b32_e32 v231, v235
	v_permlane16_swap_b32_e32 v236, v240
	v_permlane16_swap_b32_e32 v237, v241
	v_permlane16_swap_b32_e32 v238, v242
	v_permlane16_swap_b32_e32 v239, v243
	v_pk_fma_f32 v[140:141], v[140:141], v[116:117], v[228:229]
	v_pk_fma_f32 v[142:143], v[142:143], v[118:119], v[230:231]
	v_mul_f32_e32 v210, v141, v141
	v_fmac_f32_e32 v210, v140, v140
	v_fmac_f32_e32 v210, v142, v142
	v_fmac_f32_e32 v210, v143, v143
	v_pk_mul_f32 v[228:229], v[164:165], v[140:141]
	v_pk_mul_f32 v[230:231], v[166:167], v[142:143]
	v_pk_fma_f32 v[136:137], v[136:137], v[108:109], v[232:233]
	v_pk_fma_f32 v[138:139], v[138:139], v[110:111], v[234:235]
	v_fmac_f32_e32 v210, v136, v136
	v_fmac_f32_e32 v210, v137, v137
	v_fmac_f32_e32 v210, v138, v138
	v_fmac_f32_e32 v210, v139, v139
	v_pk_mul_f32 v[232:233], v[162:163], v[136:137]
	v_pk_mul_f32 v[234:235], v[160:161], v[138:139]
	v_cvt_pk_bf16_f32 v228, v228, v229
	v_cvt_pk_bf16_f32 v229, v230, v231
	v_cvt_pk_bf16_f32 v230, v232, v233
	v_cvt_pk_bf16_f32 v231, v234, v235
	global_store_dwordx4 v208, v[228:231], s[64:65]
	v_pk_fma_f32 v[132:133], v[132:133], v[104:105], v[236:237]
	v_pk_fma_f32 v[134:135], v[134:135], v[106:107], v[238:239]
	v_fmac_f32_e32 v210, v132, v132
	v_fmac_f32_e32 v210, v133, v133
	v_fmac_f32_e32 v210, v134, v134
	v_fmac_f32_e32 v210, v135, v135
	v_pk_mul_f32 v[236:237], v[150:151], v[132:133]
	v_pk_mul_f32 v[238:239], v[148:149], v[134:135]
	v_pk_fma_f32 v[128:129], v[128:129], v[100:101], v[240:241]
	v_pk_fma_f32 v[130:131], v[130:131], v[102:103], v[242:243]
	v_fmac_f32_e32 v210, v128, v128
	v_fmac_f32_e32 v210, v129, v129
	v_fmac_f32_e32 v210, v130, v130
	v_fmac_f32_e32 v210, v131, v131
	v_pk_mul_f32 v[240:241], v[144:145], v[128:129]
	v_pk_mul_f32 v[242:243], v[146:147], v[130:131]
	v_cvt_pk_bf16_f32 v236, v236, v237
	v_cvt_pk_bf16_f32 v237, v238, v239
	v_cvt_pk_bf16_f32 v238, v240, v241
	v_cvt_pk_bf16_f32 v239, v242, v243
	global_store_dwordx4 v208, v[236:239], s[64:65] offset:256
	ds_bpermute_b32 v211, v203, v210
	v_permlane16_swap_b32_e32 v140, v136
	v_permlane16_swap_b32_e32 v141, v137
	v_permlane16_swap_b32_e32 v142, v138
	v_permlane16_swap_b32_e32 v143, v139
	v_permlane16_swap_b32_e32 v132, v128
	v_permlane16_swap_b32_e32 v133, v129
	v_permlane16_swap_b32_e32 v134, v130
	v_permlane16_swap_b32_e32 v135, v131
	v_permlane32_swap_b32_e32 v140, v136
	v_permlane32_swap_b32_e32 v141, v137
	v_permlane32_swap_b32_e32 v142, v138
	v_permlane32_swap_b32_e32 v143, v139
	v_permlane32_swap_b32_e32 v132, v128
	v_permlane32_swap_b32_e32 v133, v129
	v_permlane32_swap_b32_e32 v134, v130
	v_permlane32_swap_b32_e32 v135, v131
	s_nop 1
	v_mov_b32_dpp v232, v136 row_ror:8 row_mask:0xf bank_mask:0xf
	v_mov_b32_dpp v233, v137 row_ror:8 row_mask:0xf bank_mask:0xf
	v_mov_b32_dpp v234, v138 row_ror:8 row_mask:0xf bank_mask:0xf
	v_mov_b32_dpp v235, v139 row_ror:8 row_mask:0xf bank_mask:0xf
	v_mov_b32_dpp v240, v128 row_ror:8 row_mask:0xf bank_mask:0xf
	v_mov_b32_dpp v241, v129 row_ror:8 row_mask:0xf bank_mask:0xf
	v_mov_b32_dpp v242, v130 row_ror:8 row_mask:0xf bank_mask:0xf
	v_mov_b32_dpp v243, v131 row_ror:8 row_mask:0xf bank_mask:0xf
	s_mov_b32 vcc_lo, 0xff00ff
	s_mov_b32 vcc_hi, 0xff00ff
	v_mov_b32_e32 v205, 0xffff8040
	v_mov_b32_e32 v214, 0x8040
	v_cndmask_b32_e64 v205, v205, 0, vcc
	v_cndmask_b32_e64 v214, 0, v214, vcc
	v_add_u32_e32 v205, v205, v207
	v_add_u32_e32 v214, v214, v207
	s_mov_b32 exec_lo, 0xff00ff00
	s_mov_b32 exec_hi, 0xff00ff00
	v_swap_b32 v140, v232
	v_swap_b32 v141, v233
	v_swap_b32 v142, v234
	v_swap_b32 v143, v235
	v_swap_b32 v132, v240
	v_swap_b32 v133, v241
	v_swap_b32 v134, v242
	v_swap_b32 v135, v243
	s_mov_b64 exec, -1
	global_store_dwordx4 v205, v[140:143], s[92:93]
	global_store_dwordx4 v205, v[132:135], s[92:93] offset:512
	global_store_dwordx4 v214, v[232:235], s[92:93]
	global_store_dwordx4 v214, v[240:243], s[92:93] offset:512
	v_add_u32_e32 v207, 0x10000, v207
	global_load_dwordx4 v[232:235], v206, s[82:83] offset:64
	global_load_dwordx4 v[240:243], v206, s[82:83] offset:576
	global_load_dwordx4 v[228:231], v206, s[82:83]
	global_load_dwordx4 v[236:239], v206, s[82:83] offset:512
	s_waitcnt lgkmcnt(0)
	v_add_f32_e32 v211, v210, v211
	ds_bpermute_b32 v212, v202, v211
	v_add_u32_e32 v208, 0x8000, v208
	s_waitcnt lgkmcnt(0)
	v_add_f32_e32 v211, v211, v212
	s_mov_b64 exec, 0xffff
	global_store_dword v209, v211, s[90:91]
	s_mov_b64 exec, -1
	v_add_u32_e32 v209, 0x400, v209
	s_waitcnt vmcnt(11)
; DI u32x4 pack8(const float* v) { u32x4 w; w.x = pk2(v[0], v[1]); w.y = pk2(v[2], v[3]); w.z = pk2(v[4], v[5]); w.w = pk2(v[6], v[7]); return w; }
; #define xor16_32(s) xor16_32_l((s), fr + 16 * fq)
;     DI void operator()(AccRef acc, const Unit& u, int wr, int wc, int fr, int fq) const {
;     ...
; #pragma unroll
;                 for (int bj = 0; bj < 2; ++bj) {
;                     const int c = u.pn * 256 + bj * 128 + cl;
;                     float v[8];
; #pragma unroll
;                     for (int n = 0; n < 2; ++n) {
;                         const f32x4 x = *(const f32x4*)(xi + c + 4 * n);
;                         const f32x4 y = x + gt[bj][n] * acc[ai][bj][m][n];
;                         *(f32x4*)(xout + (size_t)row * 1024 + c + 4 * n) = y;
; #pragma unroll
;                         for (int j = 0; j < 4; ++j) { s += y[j] * y[j]; v[4 * n + j] = ap ? y[j] * gs[bj][n][j] : 0.f; }
;                     }
;                     if (ap) *(u32x4*)(ap + (size_t)row * 1024 + c) = pack8(v);
;                 }
;                 s = xor16_32(s);
;                 if (fq == 0) ssq[(size_t)row * 16 + u.pn * 4 + wc] = s;
	v_permlane32_swap_b32_e32 v244, v248
	v_permlane32_swap_b32_e32 v245, v249
	v_permlane32_swap_b32_e32 v246, v250
	v_permlane32_swap_b32_e32 v247, v251
	v_permlane32_swap_b32_e32 v216, v220
	v_permlane32_swap_b32_e32 v217, v221
	v_permlane32_swap_b32_e32 v218, v222
	v_permlane32_swap_b32_e32 v219, v223
	v_permlane16_swap_b32_e32 v244, v248
	v_permlane16_swap_b32_e32 v245, v249
	v_permlane16_swap_b32_e32 v246, v250
	v_permlane16_swap_b32_e32 v247, v251
	v_permlane16_swap_b32_e32 v216, v220
	v_permlane16_swap_b32_e32 v217, v221
	v_permlane16_swap_b32_e32 v218, v222
	v_permlane16_swap_b32_e32 v219, v223
	v_pk_fma_f32 v[124:125], v[124:125], v[116:117], v[244:245]
	v_pk_fma_f32 v[126:127], v[126:127], v[118:119], v[246:247]
	v_mul_f32_e32 v210, v125, v125
	v_fmac_f32_e32 v210, v124, v124
	v_fmac_f32_e32 v210, v126, v126
	v_fmac_f32_e32 v210, v127, v127
	v_pk_mul_f32 v[244:245], v[164:165], v[124:125]
	v_pk_mul_f32 v[246:247], v[166:167], v[126:127]
	v_pk_fma_f32 v[120:121], v[120:121], v[108:109], v[248:249]
	v_pk_fma_f32 v[122:123], v[122:123], v[110:111], v[250:251]
	v_fmac_f32_e32 v210, v120, v120
	v_fmac_f32_e32 v210, v121, v121
	v_fmac_f32_e32 v210, v122, v122
	v_fmac_f32_e32 v210, v123, v123
	v_pk_mul_f32 v[248:249], v[162:163], v[120:121]
	v_pk_mul_f32 v[250:251], v[160:161], v[122:123]
	v_cvt_pk_bf16_f32 v244, v244, v245
	v_cvt_pk_bf16_f32 v245, v246, v247
	v_cvt_pk_bf16_f32 v246, v248, v249
	v_cvt_pk_bf16_f32 v247, v250, v251
	global_store_dwordx4 v208, v[244:247], s[64:65]
	v_pk_fma_f32 v[112:113], v[112:113], v[104:105], v[216:217]
	v_pk_fma_f32 v[114:115], v[114:115], v[106:107], v[218:219]
	v_fmac_f32_e32 v210, v112, v112
	v_fmac_f32_e32 v210, v113, v113
	v_fmac_f32_e32 v210, v114, v114
	v_fmac_f32_e32 v210, v115, v115
	v_pk_mul_f32 v[216:217], v[150:151], v[112:113]
	v_pk_mul_f32 v[218:219], v[148:149], v[114:115]
	v_pk_fma_f32 v[96:97], v[96:97], v[100:101], v[220:221]
	v_pk_fma_f32 v[98:99], v[98:99], v[102:103], v[222:223]
	v_fmac_f32_e32 v210, v96, v96
	v_fmac_f32_e32 v210, v97, v97
	v_fmac_f32_e32 v210, v98, v98
	v_fmac_f32_e32 v210, v99, v99
	v_pk_mul_f32 v[220:221], v[144:145], v[96:97]
	v_pk_mul_f32 v[222:223], v[146:147], v[98:99]
	v_cvt_pk_bf16_f32 v216, v216, v217
	v_cvt_pk_bf16_f32 v217, v218, v219
	v_cvt_pk_bf16_f32 v218, v220, v221
	v_cvt_pk_bf16_f32 v219, v222, v223
	global_store_dwordx4 v208, v[216:219], s[64:65] offset:256
	ds_bpermute_b32 v211, v203, v210
	v_permlane16_swap_b32_e32 v124, v120
	v_permlane16_swap_b32_e32 v125, v121
	v_permlane16_swap_b32_e32 v126, v122
	v_permlane16_swap_b32_e32 v127, v123
	v_permlane16_swap_b32_e32 v112, v96
	v_permlane16_swap_b32_e32 v113, v97
	v_permlane16_swap_b32_e32 v114, v98
	v_permlane16_swap_b32_e32 v115, v99
	v_permlane32_swap_b32_e32 v124, v120
	v_permlane32_swap_b32_e32 v125, v121
	v_permlane32_swap_b32_e32 v126, v122
	v_permlane32_swap_b32_e32 v127, v123
	v_permlane32_swap_b32_e32 v112, v96
	v_permlane32_swap_b32_e32 v113, v97
	v_permlane32_swap_b32_e32 v114, v98
	v_permlane32_swap_b32_e32 v115, v99
	s_nop 1
	v_mov_b32_dpp v248, v120 row_ror:8 row_mask:0xf bank_mask:0xf
	v_mov_b32_dpp v249, v121 row_ror:8 row_mask:0xf bank_mask:0xf
	v_mov_b32_dpp v250, v122 row_ror:8 row_mask:0xf bank_mask:0xf
	v_mov_b32_dpp v251, v123 row_ror:8 row_mask:0xf bank_mask:0xf
	v_mov_b32_dpp v220, v96 row_ror:8 row_mask:0xf bank_mask:0xf
	v_mov_b32_dpp v221, v97 row_ror:8 row_mask:0xf bank_mask:0xf
	v_mov_b32_dpp v222, v98 row_ror:8 row_mask:0xf bank_mask:0xf
	v_mov_b32_dpp v223, v99 row_ror:8 row_mask:0xf bank_mask:0xf
	s_mov_b32 vcc_lo, 0xff00ff
	s_mov_b32 vcc_hi, 0xff00ff
	v_mov_b32_e32 v205, 0xffff8040
	v_mov_b32_e32 v214, 0x8040
	v_cndmask_b32_e64 v205, v205, 0, vcc
	v_cndmask_b32_e64 v214, 0, v214, vcc
	v_add_u32_e32 v205, v205, v207
	v_add_u32_e32 v214, v214, v207
	s_mov_b32 exec_lo, 0xff00ff00
	s_mov_b32 exec_hi, 0xff00ff00
	v_swap_b32 v124, v248
	v_swap_b32 v125, v249
	v_swap_b32 v126, v250
	v_swap_b32 v127, v251
	v_swap_b32 v112, v220
	v_swap_b32 v113, v221
	v_swap_b32 v114, v222
	v_swap_b32 v115, v223
	s_mov_b64 exec, -1
	global_store_dwordx4 v205, v[124:127], s[92:93]
	global_store_dwordx4 v205, v[112:115], s[92:93] offset:512
	global_store_dwordx4 v214, v[248:251], s[92:93]
	global_store_dwordx4 v214, v[220:223], s[92:93] offset:512
	v_add_u32_e32 v207, 0x10000, v207
	v_add_u32_e32 v206, 0x10000, v206
	global_load_dwordx4 v[248:251], v206, s[82:83] offset:64
	global_load_dwordx4 v[220:223], v206, s[82:83] offset:576
	global_load_dwordx4 v[244:247], v206, s[82:83]
	global_load_dwordx4 v[216:219], v206, s[82:83] offset:512
	s_waitcnt lgkmcnt(0)
	v_add_f32_e32 v211, v210, v211
	ds_bpermute_b32 v212, v202, v211
	v_add_u32_e32 v208, 0x8000, v208
	s_waitcnt lgkmcnt(0)
	v_add_f32_e32 v211, v211, v212
	s_mov_b64 exec, 0xffff
	global_store_dword v209, v211, s[90:91]
	s_mov_b64 exec, -1
	v_add_u32_e32 v209, 0x400, v209
	s_waitcnt vmcnt(12)
; DI u32x4 pack8(const float* v) { u32x4 w; w.x = pk2(v[0], v[1]); w.y = pk2(v[2], v[3]); w.z = pk2(v[4], v[5]); w.w = pk2(v[6], v[7]); return w; }
; #define xor16_32(s) xor16_32_l((s), fr + 16 * fq)
;     DI void operator()(AccRef acc, const Unit& u, int wr, int wc, int fr, int fq) const {
;     ...
; #pragma unroll
;                 for (int bj = 0; bj < 2; ++bj) {
;                     const int c = u.pn * 256 + bj * 128 + cl;
;                     float v[8];
; #pragma unroll
;                     for (int n = 0; n < 2; ++n) {
;                         const f32x4 x = *(const f32x4*)(xi + c + 4 * n);
;                         const f32x4 y = x + gt[bj][n] * acc[ai][bj][m][n];
;                         *(f32x4*)(xout + (size_t)row * 1024 + c + 4 * n) = y;
; #pragma unroll
;                         for (int j = 0; j < 4; ++j) { s += y[j] * y[j]; v[4 * n + j] = ap ? y[j] * gs[bj][n][j] : 0.f; }
;                     }
;                     if (ap) *(u32x4*)(ap + (size_t)row * 1024 + c) = pack8(v);
;                 }
;                 s = xor16_32(s);
;                 if (fq == 0) ssq[(size_t)row * 16 + u.pn * 4 + wc] = s;
	v_permlane32_swap_b32_e32 v228, v232
	v_permlane32_swap_b32_e32 v229, v233
	v_permlane32_swap_b32_e32 v230, v234
	v_permlane32_swap_b32_e32 v231, v235
	v_permlane32_swap_b32_e32 v236, v240
	v_permlane32_swap_b32_e32 v237, v241
	v_permlane32_swap_b32_e32 v238, v242
	v_permlane32_swap_b32_e32 v239, v243
	v_permlane16_swap_b32_e32 v228, v232
	v_permlane16_swap_b32_e32 v229, v233
	v_permlane16_swap_b32_e32 v230, v234
	v_permlane16_swap_b32_e32 v231, v235
	v_permlane16_swap_b32_e32 v236, v240
	v_permlane16_swap_b32_e32 v237, v241
	v_permlane16_swap_b32_e32 v238, v242
	v_permlane16_swap_b32_e32 v239, v243
	v_pk_fma_f32 v[92:93], v[92:93], v[116:117], v[228:229]
	v_pk_fma_f32 v[94:95], v[94:95], v[118:119], v[230:231]
	v_mul_f32_e32 v210, v93, v93
	v_fmac_f32_e32 v210, v92, v92
	v_fmac_f32_e32 v210, v94, v94
	v_fmac_f32_e32 v210, v95, v95
	v_pk_mul_f32 v[228:229], v[164:165], v[92:93]
	v_pk_mul_f32 v[230:231], v[166:167], v[94:95]
	v_pk_fma_f32 v[88:89], v[88:89], v[108:109], v[232:233]
	v_pk_fma_f32 v[90:91], v[90:91], v[110:111], v[234:235]
	v_fmac_f32_e32 v210, v88, v88
	v_fmac_f32_e32 v210, v89, v89
	v_fmac_f32_e32 v210, v90, v90
	v_fmac_f32_e32 v210, v91, v91
	v_pk_mul_f32 v[232:233], v[162:163], v[88:89]
	v_pk_mul_f32 v[234:235], v[160:161], v[90:91]
	v_cvt_pk_bf16_f32 v228, v228, v229
	v_cvt_pk_bf16_f32 v229, v230, v231
	v_cvt_pk_bf16_f32 v230, v232, v233
	v_cvt_pk_bf16_f32 v231, v234, v235
	global_store_dwordx4 v208, v[228:231], s[64:65]
	v_pk_fma_f32 v[84:85], v[84:85], v[104:105], v[236:237]
	v_pk_fma_f32 v[86:87], v[86:87], v[106:107], v[238:239]
	v_fmac_f32_e32 v210, v84, v84
	v_fmac_f32_e32 v210, v85, v85
	v_fmac_f32_e32 v210, v86, v86
	v_fmac_f32_e32 v210, v87, v87
	v_pk_mul_f32 v[236:237], v[150:151], v[84:85]
	v_pk_mul_f32 v[238:239], v[148:149], v[86:87]
	v_pk_fma_f32 v[80:81], v[80:81], v[100:101], v[240:241]
	v_pk_fma_f32 v[82:83], v[82:83], v[102:103], v[242:243]
	v_fmac_f32_e32 v210, v80, v80
	v_fmac_f32_e32 v210, v81, v81
	v_fmac_f32_e32 v210, v82, v82
	v_fmac_f32_e32 v210, v83, v83
	v_pk_mul_f32 v[240:241], v[144:145], v[80:81]
	v_pk_mul_f32 v[242:243], v[146:147], v[82:83]
	v_cvt_pk_bf16_f32 v236, v236, v237
	v_cvt_pk_bf16_f32 v237, v238, v239
	v_cvt_pk_bf16_f32 v238, v240, v241
	v_cvt_pk_bf16_f32 v239, v242, v243
	global_store_dwordx4 v208, v[236:239], s[64:65] offset:256
	ds_bpermute_b32 v211, v203, v210
	v_permlane16_swap_b32_e32 v92, v88
	v_permlane16_swap_b32_e32 v93, v89
	v_permlane16_swap_b32_e32 v94, v90
	v_permlane16_swap_b32_e32 v95, v91
	v_permlane16_swap_b32_e32 v84, v80
	v_permlane16_swap_b32_e32 v85, v81
	v_permlane16_swap_b32_e32 v86, v82
	v_permlane16_swap_b32_e32 v87, v83
	v_permlane32_swap_b32_e32 v92, v88
	v_permlane32_swap_b32_e32 v93, v89
	v_permlane32_swap_b32_e32 v94, v90
	v_permlane32_swap_b32_e32 v95, v91
	v_permlane32_swap_b32_e32 v84, v80
	v_permlane32_swap_b32_e32 v85, v81
	v_permlane32_swap_b32_e32 v86, v82
	v_permlane32_swap_b32_e32 v87, v83
	s_nop 1
	v_mov_b32_dpp v232, v88 row_ror:8 row_mask:0xf bank_mask:0xf
	v_mov_b32_dpp v233, v89 row_ror:8 row_mask:0xf bank_mask:0xf
	v_mov_b32_dpp v234, v90 row_ror:8 row_mask:0xf bank_mask:0xf
	v_mov_b32_dpp v235, v91 row_ror:8 row_mask:0xf bank_mask:0xf
	v_mov_b32_dpp v240, v80 row_ror:8 row_mask:0xf bank_mask:0xf
	v_mov_b32_dpp v241, v81 row_ror:8 row_mask:0xf bank_mask:0xf
	v_mov_b32_dpp v242, v82 row_ror:8 row_mask:0xf bank_mask:0xf
	v_mov_b32_dpp v243, v83 row_ror:8 row_mask:0xf bank_mask:0xf
	s_mov_b32 vcc_lo, 0xff00ff
	s_mov_b32 vcc_hi, 0xff00ff
	v_mov_b32_e32 v205, 0xffff8040
	v_mov_b32_e32 v214, 0x8040
	v_cndmask_b32_e64 v205, v205, 0, vcc
	v_cndmask_b32_e64 v214, 0, v214, vcc
	v_add_u32_e32 v205, v205, v207
	v_add_u32_e32 v214, v214, v207
	s_mov_b32 exec_lo, 0xff00ff00
	s_mov_b32 exec_hi, 0xff00ff00
	v_swap_b32 v92, v232
	v_swap_b32 v93, v233
	v_swap_b32 v94, v234
	v_swap_b32 v95, v235
	v_swap_b32 v84, v240
	v_swap_b32 v85, v241
	v_swap_b32 v86, v242
	v_swap_b32 v87, v243
	s_mov_b64 exec, -1
	global_store_dwordx4 v205, v[92:95], s[92:93]
	global_store_dwordx4 v205, v[84:87], s[92:93] offset:512
	global_store_dwordx4 v214, v[232:235], s[92:93]
	global_store_dwordx4 v214, v[240:243], s[92:93] offset:512
	v_add_u32_e32 v207, 0x10000, v207
	v_add_u32_e32 v206, 0x50000, v206
	global_load_dwordx4 v[232:235], v206, s[82:83] offset:64
	global_load_dwordx4 v[240:243], v206, s[82:83] offset:576
	global_load_dwordx4 v[228:231], v206, s[82:83]
	global_load_dwordx4 v[236:239], v206, s[82:83] offset:512
	s_waitcnt lgkmcnt(0)
	v_add_f32_e32 v211, v210, v211
	ds_bpermute_b32 v212, v202, v211
	v_add_u32_e32 v208, 0x8000, v208
	s_waitcnt lgkmcnt(0)
	v_add_f32_e32 v211, v211, v212
	s_mov_b64 exec, 0xffff
	global_store_dword v209, v211, s[90:91]
	s_mov_b64 exec, -1
	v_add_u32_e32 v209, 0x400, v209
	s_waitcnt vmcnt(12)
; DI u32x4 pack8(const float* v) { u32x4 w; w.x = pk2(v[0], v[1]); w.y = pk2(v[2], v[3]); w.z = pk2(v[4], v[5]); w.w = pk2(v[6], v[7]); return w; }
; #define xor16_32(s) xor16_32_l((s), fr + 16 * fq)
;     DI void operator()(AccRef acc, const Unit& u, int wr, int wc, int fr, int fq) const {
;     ...
; #pragma unroll
;                 for (int bj = 0; bj < 2; ++bj) {
;                     const int c = u.pn * 256 + bj * 128 + cl;
;                     float v[8];
; #pragma unroll
;                     for (int n = 0; n < 2; ++n) {
;                         const f32x4 x = *(const f32x4*)(xi + c + 4 * n);
;                         const f32x4 y = x + gt[bj][n] * acc[ai][bj][m][n];
;                         *(f32x4*)(xout + (size_t)row * 1024 + c + 4 * n) = y;
; #pragma unroll
;                         for (int j = 0; j < 4; ++j) { s += y[j] * y[j]; v[4 * n + j] = ap ? y[j] * gs[bj][n][j] : 0.f; }
;                     }
;                     if (ap) *(u32x4*)(ap + (size_t)row * 1024 + c) = pack8(v);
;                 }
;                 s = xor16_32(s);
;                 if (fq == 0) ssq[(size_t)row * 16 + u.pn * 4 + wc] = s;
	v_permlane32_swap_b32_e32 v244, v248
	v_permlane32_swap_b32_e32 v245, v249
	v_permlane32_swap_b32_e32 v246, v250
	v_permlane32_swap_b32_e32 v247, v251
	v_permlane32_swap_b32_e32 v216, v220
	v_permlane32_swap_b32_e32 v217, v221
	v_permlane32_swap_b32_e32 v218, v222
	v_permlane32_swap_b32_e32 v219, v223
	v_permlane16_swap_b32_e32 v244, v248
	v_permlane16_swap_b32_e32 v245, v249
	v_permlane16_swap_b32_e32 v246, v250
	v_permlane16_swap_b32_e32 v247, v251
	v_permlane16_swap_b32_e32 v216, v220
	v_permlane16_swap_b32_e32 v217, v221
	v_permlane16_swap_b32_e32 v218, v222
	v_permlane16_swap_b32_e32 v219, v223
	v_pk_fma_f32 v[76:77], v[76:77], v[116:117], v[244:245]
	v_pk_fma_f32 v[78:79], v[78:79], v[118:119], v[246:247]
	v_mul_f32_e32 v210, v77, v77
	v_fmac_f32_e32 v210, v76, v76
	v_fmac_f32_e32 v210, v78, v78
	v_fmac_f32_e32 v210, v79, v79
	v_pk_mul_f32 v[244:245], v[164:165], v[76:77]
	v_pk_mul_f32 v[246:247], v[166:167], v[78:79]
	v_pk_fma_f32 v[72:73], v[72:73], v[108:109], v[248:249]
	v_pk_fma_f32 v[74:75], v[74:75], v[110:111], v[250:251]
	v_fmac_f32_e32 v210, v72, v72
	v_fmac_f32_e32 v210, v73, v73
	v_fmac_f32_e32 v210, v74, v74
	v_fmac_f32_e32 v210, v75, v75
	v_pk_mul_f32 v[248:249], v[162:163], v[72:73]
	v_pk_mul_f32 v[250:251], v[160:161], v[74:75]
	v_cvt_pk_bf16_f32 v244, v244, v245
	v_cvt_pk_bf16_f32 v245, v246, v247
	v_cvt_pk_bf16_f32 v246, v248, v249
	v_cvt_pk_bf16_f32 v247, v250, v251
	global_store_dwordx4 v208, v[244:247], s[64:65]
	v_pk_fma_f32 v[68:69], v[68:69], v[104:105], v[216:217]
	v_pk_fma_f32 v[70:71], v[70:71], v[106:107], v[218:219]
	v_fmac_f32_e32 v210, v68, v68
	v_fmac_f32_e32 v210, v69, v69
	v_fmac_f32_e32 v210, v70, v70
	v_fmac_f32_e32 v210, v71, v71
	v_pk_mul_f32 v[216:217], v[150:151], v[68:69]
	v_pk_mul_f32 v[218:219], v[148:149], v[70:71]
	v_pk_fma_f32 v[64:65], v[64:65], v[100:101], v[220:221]
	v_pk_fma_f32 v[66:67], v[66:67], v[102:103], v[222:223]
	v_fmac_f32_e32 v210, v64, v64
	v_fmac_f32_e32 v210, v65, v65
	v_fmac_f32_e32 v210, v66, v66
	v_fmac_f32_e32 v210, v67, v67
	v_pk_mul_f32 v[220:221], v[144:145], v[64:65]
	v_pk_mul_f32 v[222:223], v[146:147], v[66:67]
	v_cvt_pk_bf16_f32 v216, v216, v217
	v_cvt_pk_bf16_f32 v217, v218, v219
	v_cvt_pk_bf16_f32 v218, v220, v221
	v_cvt_pk_bf16_f32 v219, v222, v223
	global_store_dwordx4 v208, v[216:219], s[64:65] offset:256
	ds_bpermute_b32 v211, v203, v210
	v_permlane16_swap_b32_e32 v76, v72
	v_permlane16_swap_b32_e32 v77, v73
	v_permlane16_swap_b32_e32 v78, v74
	v_permlane16_swap_b32_e32 v79, v75
	v_permlane16_swap_b32_e32 v68, v64
	v_permlane16_swap_b32_e32 v69, v65
	v_permlane16_swap_b32_e32 v70, v66
	v_permlane16_swap_b32_e32 v71, v67
	v_permlane32_swap_b32_e32 v76, v72
	v_permlane32_swap_b32_e32 v77, v73
	v_permlane32_swap_b32_e32 v78, v74
	v_permlane32_swap_b32_e32 v79, v75
	v_permlane32_swap_b32_e32 v68, v64
	v_permlane32_swap_b32_e32 v69, v65
	v_permlane32_swap_b32_e32 v70, v66
	v_permlane32_swap_b32_e32 v71, v67
	s_nop 1
	v_mov_b32_dpp v248, v72 row_ror:8 row_mask:0xf bank_mask:0xf
	v_mov_b32_dpp v249, v73 row_ror:8 row_mask:0xf bank_mask:0xf
	v_mov_b32_dpp v250, v74 row_ror:8 row_mask:0xf bank_mask:0xf
	v_mov_b32_dpp v251, v75 row_ror:8 row_mask:0xf bank_mask:0xf
	v_mov_b32_dpp v220, v64 row_ror:8 row_mask:0xf bank_mask:0xf
	v_mov_b32_dpp v221, v65 row_ror:8 row_mask:0xf bank_mask:0xf
	v_mov_b32_dpp v222, v66 row_ror:8 row_mask:0xf bank_mask:0xf
	v_mov_b32_dpp v223, v67 row_ror:8 row_mask:0xf bank_mask:0xf
	s_mov_b32 vcc_lo, 0xff00ff
	s_mov_b32 vcc_hi, 0xff00ff
	v_mov_b32_e32 v205, 0xffff8040
	v_mov_b32_e32 v214, 0x8040
	v_cndmask_b32_e64 v205, v205, 0, vcc
	v_cndmask_b32_e64 v214, 0, v214, vcc
	v_add_u32_e32 v205, v205, v207
	v_add_u32_e32 v214, v214, v207
	s_mov_b32 exec_lo, 0xff00ff00
	s_mov_b32 exec_hi, 0xff00ff00
	v_swap_b32 v76, v248
	v_swap_b32 v77, v249
	v_swap_b32 v78, v250
	v_swap_b32 v79, v251
	v_swap_b32 v68, v220
	v_swap_b32 v69, v221
	v_swap_b32 v70, v222
	v_swap_b32 v71, v223
	s_mov_b64 exec, -1
	global_store_dwordx4 v205, v[76:79], s[92:93]
	global_store_dwordx4 v205, v[68:71], s[92:93] offset:512
	global_store_dwordx4 v214, v[248:251], s[92:93]
	global_store_dwordx4 v214, v[220:223], s[92:93] offset:512
	v_add_u32_e32 v207, 0x50000, v207
	v_add_u32_e32 v206, 0x10000, v206
	global_load_dwordx4 v[248:251], v206, s[82:83] offset:64
	global_load_dwordx4 v[220:223], v206, s[82:83] offset:576
	global_load_dwordx4 v[244:247], v206, s[82:83]
	global_load_dwordx4 v[216:219], v206, s[82:83] offset:512
	s_waitcnt lgkmcnt(0)
	v_add_f32_e32 v211, v210, v211
	ds_bpermute_b32 v212, v202, v211
	v_add_u32_e32 v208, 0x28000, v208
	s_waitcnt lgkmcnt(0)
	v_add_f32_e32 v211, v211, v212
	s_mov_b64 exec, 0xffff
	global_store_dword v209, v211, s[90:91]
	s_mov_b64 exec, -1
	v_add_u32_e32 v209, 0x1400, v209
	v_add_u32_e32 v224, 0xffffc080, v192
	v_add_u32_e32 v112, 0x80, v192
	s_waitcnt lgkmcnt(0)
;     DI void operator()(AccRef acc, const Unit& u, int wr, int wc, int fr, int fq) const {
;     ...
;         for (int ai = 0; ai < 2; ++ai) {
;             const int rb = u.pm * 256 + ai * 128 + wr * 64 + fr;
;             int mb, pos0, kv0; row_info(rb, mb, pos0, kv0);
;             f32x4 gt[2][2], gs[2][2];
; #pragma unroll
;             for (int bj = 0; bj < 2; ++bj)
; #pragma unroll
;                 for (int n = 0; n < 2; ++n) {
;                     const int c = u.pn * 256 + bj * 128 + cl + 4 * n;
;                     gt[bj][n] = *(const f32x4*)(gate + (size_t)mb * 6144 + c);
;                     if (ap) { const f32x4 g = *(const f32x4*)(gn + c), s = *(const f32x4*)(scn + (size_t)mb * 6144 + c); gs[bj][n] = g * (s + 1.f); }
;                 }
; #pragma unroll
;             for (int m = 0; m < 4; ++m) {
;                 const int row = rb + 16 * m;
;                 const float* xi = row < MP ? xin_p + (size_t)row * 1024 : xin_s + (size_t)(row - MP) * 1024;
;                 float s = 0.f;
; #pragma unroll
;                 for (int bj = 0; bj < 2; ++bj) {
;                     const int c = u.pn * 256 + bj * 128 + cl;
;                     float v[8];
; #pragma unroll
;                     for (int n = 0; n < 2; ++n) {
;                         const f32x4 x = *(const f32x4*)(xi + c + 4 * n);
;                         const f32x4 y = x + gt[bj][n] * acc[ai][bj][m][n];
	v_lshrrev_b32_e32 v65, 6, v224
	v_ashrrev_i32_e32 v64, 11, v112
	v_add_u32_e32 v65, 8, v65
	v_cmp_gt_i32_e64 s[2:3], s94, v112
	v_mov_b64_e32 v[66:67], s[60:61]
	s_nop 0
	v_cndmask_b32_e64 v68, v65, v64, s[2:3]
	v_mov_b64_e32 v[64:65], s[8:9]
	v_mad_i64_i32 v[64:65], s[2:3], v68, s75, v[64:65]
	v_mad_i64_i32 v[66:67], s[2:3], v68, s75, v[66:67]
	v_lshl_add_u64 v[68:69], v[64:65], 0, v[190:191]
	v_lshl_add_u64 v[104:105], v[66:67], 0, v[190:191]
	global_load_dwordx4 v[72:75], v[68:69], off offset:16
	global_load_dwordx4 v[76:79], v[68:69], off
	global_load_dwordx4 v[84:87], v[194:195], off offset:16
	global_load_dwordx4 v[100:103], v[194:195], off
	global_load_dwordx4 v[96:99], v[104:105], off offset:16
	global_load_dwordx4 v[108:111], v[104:105], off
	global_load_dwordx4 v[64:67], v[68:69], off offset:528
	s_nop 0
	global_load_dwordx4 v[68:71], v[68:69], off offset:512
	s_nop 0
	global_load_dwordx4 v[80:83], v[194:195], off offset:528
	global_load_dwordx4 v[92:95], v[194:195], off offset:512
	global_load_dwordx4 v[88:91], v[104:105], off offset:528
	s_nop 0
	global_load_dwordx4 v[104:107], v[104:105], off offset:512
	s_movk_i32 s2, 0x3fff
	v_cmp_lt_i32_e64 s[2:3], s2, v112
	s_and_saveexec_b64 s[12:13], s[2:3]
	s_xor_b64 s[2:3], exec, s[12:13]
	v_lshlrev_b64 v[114:115], 12, v[224:225]
	v_mov_b32_e32 v113, v225
	v_lshl_add_u64 v[116:117], s[20:21], 0, v[114:115]
	v_lshlrev_b64 v[114:115], 12, v[112:113]
	s_andn2_saveexec_b64 s[2:3], s[2:3]
	v_ashrrev_i32_e32 v113, 31, v112
	v_lshlrev_b64 v[114:115], 12, v[112:113]
	v_lshl_add_u64 v[116:117], s[42:43], 0, v[114:115]
	s_or_b64 exec, exec, s[2:3]
	s_waitcnt vmcnt(6)
	v_pk_add_f32 v[108:109], v[108:109], 1.0 op_sel_hi:[1,0]
	s_waitcnt vmcnt(1)
	v_pk_add_f32 v[90:91], v[90:91], 1.0 op_sel_hi:[1,0]
	v_pk_mul_f32 v[100:101], v[100:101], v[108:109]
	v_pk_add_f32 v[108:109], v[96:97], 1.0 op_sel_hi:[1,0]
	v_pk_add_f32 v[96:97], v[98:99], 1.0 op_sel_hi:[1,0]
	v_pk_mul_f32 v[98:99], v[84:85], v[108:109]
	v_pk_mul_f32 v[96:97], v[86:87], v[96:97]
	s_waitcnt vmcnt(0)
	v_pk_add_f32 v[84:85], v[106:107], 1.0 op_sel_hi:[1,0]
	v_pk_add_f32 v[86:87], v[104:105], 1.0 op_sel_hi:[1,0]
	v_pk_mul_f32 v[82:83], v[82:83], v[90:91]
	v_lshl_add_u64 v[90:91], v[116:117], 0, v[190:191]
	v_pk_mul_f32 v[84:85], v[94:95], v[84:85]
	v_pk_mul_f32 v[86:87], v[92:93], v[86:87]
	v_pk_add_f32 v[110:111], v[110:111], 1.0 op_sel_hi:[1,0]
	v_pk_add_f32 v[88:89], v[88:89], 1.0 op_sel_hi:[1,0]
	v_pk_mul_f32 v[102:103], v[102:103], v[110:111]
	v_pk_mul_f32 v[80:81], v[80:81], v[88:89]
	v_lshlrev_b64 v[88:89], 11, v[112:113]
	v_lshl_add_u64 v[88:89], s[64:65], 0, v[88:89]
	v_permlane32_swap_b32_e32 v228, v232
	v_permlane32_swap_b32_e32 v229, v233
	v_permlane32_swap_b32_e32 v230, v234
	v_permlane32_swap_b32_e32 v231, v235
	v_permlane32_swap_b32_e32 v236, v240
	v_permlane32_swap_b32_e32 v237, v241
	v_permlane32_swap_b32_e32 v238, v242
	v_permlane32_swap_b32_e32 v239, v243
	v_permlane16_swap_b32_e32 v228, v232
	v_permlane16_swap_b32_e32 v229, v233
	v_permlane16_swap_b32_e32 v230, v234
	v_permlane16_swap_b32_e32 v231, v235
	v_permlane16_swap_b32_e32 v236, v240
	v_permlane16_swap_b32_e32 v237, v241
	v_permlane16_swap_b32_e32 v238, v242
	v_permlane16_swap_b32_e32 v239, v243
	v_pk_fma_f32 v[60:61], v[60:61], v[76:77], v[228:229]
	v_pk_fma_f32 v[62:63], v[62:63], v[78:79], v[230:231]
	v_mul_f32_e32 v210, v61, v61
	v_fmac_f32_e32 v210, v60, v60
	v_fmac_f32_e32 v210, v62, v62
	v_fmac_f32_e32 v210, v63, v63
	v_pk_mul_f32 v[228:229], v[100:101], v[60:61]
	v_pk_mul_f32 v[230:231], v[102:103], v[62:63]
	v_pk_fma_f32 v[56:57], v[56:57], v[72:73], v[232:233]
	v_pk_fma_f32 v[58:59], v[58:59], v[74:75], v[234:235]
	v_fmac_f32_e32 v210, v56, v56
	v_fmac_f32_e32 v210, v57, v57
	v_fmac_f32_e32 v210, v58, v58
	v_fmac_f32_e32 v210, v59, v59
	v_pk_mul_f32 v[232:233], v[98:99], v[56:57]
	v_pk_mul_f32 v[234:235], v[96:97], v[58:59]
	v_cvt_pk_bf16_f32 v228, v228, v229
	v_cvt_pk_bf16_f32 v229, v230, v231
	v_cvt_pk_bf16_f32 v230, v232, v233
	v_cvt_pk_bf16_f32 v231, v234, v235
	global_store_dwordx4 v208, v[228:231], s[64:65]
	v_pk_fma_f32 v[52:53], v[52:53], v[68:69], v[236:237]
	v_pk_fma_f32 v[54:55], v[54:55], v[70:71], v[238:239]
	v_fmac_f32_e32 v210, v52, v52
	v_fmac_f32_e32 v210, v53, v53
	v_fmac_f32_e32 v210, v54, v54
	v_fmac_f32_e32 v210, v55, v55
	v_pk_mul_f32 v[236:237], v[86:87], v[52:53]
	v_pk_mul_f32 v[238:239], v[84:85], v[54:55]
	v_pk_fma_f32 v[48:49], v[48:49], v[64:65], v[240:241]
	v_pk_fma_f32 v[50:51], v[50:51], v[66:67], v[242:243]
	v_fmac_f32_e32 v210, v48, v48
	v_fmac_f32_e32 v210, v49, v49
	v_fmac_f32_e32 v210, v50, v50
	v_fmac_f32_e32 v210, v51, v51
	v_pk_mul_f32 v[240:241], v[80:81], v[48:49]
	v_pk_mul_f32 v[242:243], v[82:83], v[50:51]
	v_cvt_pk_bf16_f32 v236, v236, v237
	v_cvt_pk_bf16_f32 v237, v238, v239
	v_cvt_pk_bf16_f32 v238, v240, v241
	v_cvt_pk_bf16_f32 v239, v242, v243
	global_store_dwordx4 v208, v[236:239], s[64:65] offset:256
	ds_bpermute_b32 v211, v203, v210
	v_permlane16_swap_b32_e32 v60, v56
	v_permlane16_swap_b32_e32 v61, v57
	v_permlane16_swap_b32_e32 v62, v58
	v_permlane16_swap_b32_e32 v63, v59
	v_permlane16_swap_b32_e32 v52, v48
	v_permlane16_swap_b32_e32 v53, v49
	v_permlane16_swap_b32_e32 v54, v50
	v_permlane16_swap_b32_e32 v55, v51
	v_permlane32_swap_b32_e32 v60, v56
	v_permlane32_swap_b32_e32 v61, v57
	v_permlane32_swap_b32_e32 v62, v58
	v_permlane32_swap_b32_e32 v63, v59
	v_permlane32_swap_b32_e32 v52, v48
	v_permlane32_swap_b32_e32 v53, v49
	v_permlane32_swap_b32_e32 v54, v50
	v_permlane32_swap_b32_e32 v55, v51
	s_nop 1
	v_mov_b32_dpp v232, v56 row_ror:8 row_mask:0xf bank_mask:0xf
; DI u32x4 pack8(const float* v) { u32x4 w; w.x = pk2(v[0], v[1]); w.y = pk2(v[2], v[3]); w.z = pk2(v[4], v[5]); w.w = pk2(v[6], v[7]); return w; }
; #define xor16_32(s) xor16_32_l((s), fr + 16 * fq)
;     DI void operator()(AccRef acc, const Unit& u, int wr, int wc, int fr, int fq) const {
;     ...
; #pragma unroll
;                 for (int bj = 0; bj < 2; ++bj) {
;                     const int c = u.pn * 256 + bj * 128 + cl;
;                     float v[8];
; #pragma unroll
;                     for (int n = 0; n < 2; ++n) {
;                         const f32x4 x = *(const f32x4*)(xi + c + 4 * n);
;                         const f32x4 y = x + gt[bj][n] * acc[ai][bj][m][n];
;                         *(f32x4*)(xout + (size_t)row * 1024 + c + 4 * n) = y;
; #pragma unroll
;                         for (int j = 0; j < 4; ++j) { s += y[j] * y[j]; v[4 * n + j] = ap ? y[j] * gs[bj][n][j] : 0.f; }
;                     }
;                     if (ap) *(u32x4*)(ap + (size_t)row * 1024 + c) = pack8(v);
;                 }
;                 s = xor16_32(s);
;                 if (fq == 0) ssq[(size_t)row * 16 + u.pn * 4 + wc] = s;
	v_mov_b32_dpp v233, v57 row_ror:8 row_mask:0xf bank_mask:0xf
	v_mov_b32_dpp v234, v58 row_ror:8 row_mask:0xf bank_mask:0xf
	v_mov_b32_dpp v235, v59 row_ror:8 row_mask:0xf bank_mask:0xf
	v_mov_b32_dpp v240, v48 row_ror:8 row_mask:0xf bank_mask:0xf
	v_mov_b32_dpp v241, v49 row_ror:8 row_mask:0xf bank_mask:0xf
	v_mov_b32_dpp v242, v50 row_ror:8 row_mask:0xf bank_mask:0xf
	v_mov_b32_dpp v243, v51 row_ror:8 row_mask:0xf bank_mask:0xf
	s_mov_b32 vcc_lo, 0xff00ff
	s_mov_b32 vcc_hi, 0xff00ff
	v_mov_b32_e32 v205, 0xffff8040
	v_mov_b32_e32 v214, 0x8040
	v_cndmask_b32_e64 v205, v205, 0, vcc
	v_cndmask_b32_e64 v214, 0, v214, vcc
	v_add_u32_e32 v205, v205, v207
	v_add_u32_e32 v214, v214, v207
	s_mov_b32 exec_lo, 0xff00ff00
	s_mov_b32 exec_hi, 0xff00ff00
	v_swap_b32 v60, v232
	v_swap_b32 v61, v233
	v_swap_b32 v62, v234
	v_swap_b32 v63, v235
	v_swap_b32 v52, v240
	v_swap_b32 v53, v241
	v_swap_b32 v54, v242
	v_swap_b32 v55, v243
	s_mov_b64 exec, -1
	global_store_dwordx4 v205, v[60:63], s[92:93]
	global_store_dwordx4 v205, v[52:55], s[92:93] offset:512
	global_store_dwordx4 v214, v[232:235], s[92:93]
	global_store_dwordx4 v214, v[240:243], s[92:93] offset:512
	v_add_u32_e32 v207, 0x10000, v207
	v_add_u32_e32 v206, 0x10000, v206
	global_load_dwordx4 v[232:235], v206, s[82:83] offset:64
	global_load_dwordx4 v[240:243], v206, s[82:83] offset:576
	global_load_dwordx4 v[228:231], v206, s[82:83]
	global_load_dwordx4 v[236:239], v206, s[82:83] offset:512
	s_waitcnt lgkmcnt(0)
	v_add_f32_e32 v211, v210, v211
	ds_bpermute_b32 v212, v202, v211
	v_add_u32_e32 v208, 0x8000, v208
	s_waitcnt lgkmcnt(0)
	v_add_f32_e32 v211, v211, v212
	s_mov_b64 exec, 0xffff
	global_store_dword v209, v211, s[90:91]
	s_mov_b64 exec, -1
	v_add_u32_e32 v209, 0x400, v209
	v_permlane32_swap_b32_e32 v244, v248
	v_permlane32_swap_b32_e32 v245, v249
	v_permlane32_swap_b32_e32 v246, v250
	v_permlane32_swap_b32_e32 v247, v251
	v_permlane32_swap_b32_e32 v216, v220
	v_permlane32_swap_b32_e32 v217, v221
	v_permlane32_swap_b32_e32 v218, v222
	v_permlane32_swap_b32_e32 v219, v223
	v_permlane16_swap_b32_e32 v244, v248
	v_permlane16_swap_b32_e32 v245, v249
	v_permlane16_swap_b32_e32 v246, v250
	v_permlane16_swap_b32_e32 v247, v251
	v_permlane16_swap_b32_e32 v216, v220
	v_permlane16_swap_b32_e32 v217, v221
	v_permlane16_swap_b32_e32 v218, v222
	v_permlane16_swap_b32_e32 v219, v223
	v_pk_fma_f32 v[44:45], v[44:45], v[76:77], v[244:245]
	v_pk_fma_f32 v[46:47], v[46:47], v[78:79], v[246:247]
	v_mul_f32_e32 v210, v45, v45
	v_fmac_f32_e32 v210, v44, v44
	v_fmac_f32_e32 v210, v46, v46
	v_fmac_f32_e32 v210, v47, v47
	v_pk_mul_f32 v[244:245], v[100:101], v[44:45]
	v_pk_mul_f32 v[246:247], v[102:103], v[46:47]
	v_pk_fma_f32 v[40:41], v[40:41], v[72:73], v[248:249]
	v_pk_fma_f32 v[42:43], v[42:43], v[74:75], v[250:251]
	v_fmac_f32_e32 v210, v40, v40
	v_fmac_f32_e32 v210, v41, v41
	v_fmac_f32_e32 v210, v42, v42
	v_fmac_f32_e32 v210, v43, v43
	v_pk_mul_f32 v[248:249], v[98:99], v[40:41]
	v_pk_mul_f32 v[250:251], v[96:97], v[42:43]
	v_cvt_pk_bf16_f32 v244, v244, v245
	v_cvt_pk_bf16_f32 v245, v246, v247
	v_cvt_pk_bf16_f32 v246, v248, v249
	v_cvt_pk_bf16_f32 v247, v250, v251
	global_store_dwordx4 v208, v[244:247], s[64:65]
	v_pk_fma_f32 v[36:37], v[36:37], v[68:69], v[216:217]
	v_pk_fma_f32 v[38:39], v[38:39], v[70:71], v[218:219]
	v_fmac_f32_e32 v210, v36, v36
	v_fmac_f32_e32 v210, v37, v37
	v_fmac_f32_e32 v210, v38, v38
	v_fmac_f32_e32 v210, v39, v39
	v_pk_mul_f32 v[216:217], v[86:87], v[36:37]
	v_pk_mul_f32 v[218:219], v[84:85], v[38:39]
	v_pk_fma_f32 v[32:33], v[32:33], v[64:65], v[220:221]
	v_pk_fma_f32 v[34:35], v[34:35], v[66:67], v[222:223]
	v_fmac_f32_e32 v210, v32, v32
	v_fmac_f32_e32 v210, v33, v33
	v_fmac_f32_e32 v210, v34, v34
	v_fmac_f32_e32 v210, v35, v35
	v_pk_mul_f32 v[220:221], v[80:81], v[32:33]
	v_pk_mul_f32 v[222:223], v[82:83], v[34:35]
	v_cvt_pk_bf16_f32 v216, v216, v217
	v_cvt_pk_bf16_f32 v217, v218, v219
	v_cvt_pk_bf16_f32 v218, v220, v221
	v_cvt_pk_bf16_f32 v219, v222, v223
	global_store_dwordx4 v208, v[216:219], s[64:65] offset:256
	ds_bpermute_b32 v211, v203, v210
	v_permlane16_swap_b32_e32 v44, v40
	v_permlane16_swap_b32_e32 v45, v41
	v_permlane16_swap_b32_e32 v46, v42
	v_permlane16_swap_b32_e32 v47, v43
	v_permlane16_swap_b32_e32 v36, v32
	v_permlane16_swap_b32_e32 v37, v33
	v_permlane16_swap_b32_e32 v38, v34
	v_permlane16_swap_b32_e32 v39, v35
	v_permlane32_swap_b32_e32 v44, v40
	v_permlane32_swap_b32_e32 v45, v41
	v_permlane32_swap_b32_e32 v46, v42
	v_permlane32_swap_b32_e32 v47, v43
	v_permlane32_swap_b32_e32 v36, v32
	v_permlane32_swap_b32_e32 v37, v33
	v_permlane32_swap_b32_e32 v38, v34
	v_permlane32_swap_b32_e32 v39, v35
	s_nop 1
	v_mov_b32_dpp v248, v40 row_ror:8 row_mask:0xf bank_mask:0xf
	v_mov_b32_dpp v249, v41 row_ror:8 row_mask:0xf bank_mask:0xf
	v_mov_b32_dpp v250, v42 row_ror:8 row_mask:0xf bank_mask:0xf
	v_mov_b32_dpp v251, v43 row_ror:8 row_mask:0xf bank_mask:0xf
	v_mov_b32_dpp v220, v32 row_ror:8 row_mask:0xf bank_mask:0xf
	v_mov_b32_dpp v221, v33 row_ror:8 row_mask:0xf bank_mask:0xf
	v_mov_b32_dpp v222, v34 row_ror:8 row_mask:0xf bank_mask:0xf
	v_mov_b32_dpp v223, v35 row_ror:8 row_mask:0xf bank_mask:0xf
	s_mov_b32 vcc_lo, 0xff00ff
	s_mov_b32 vcc_hi, 0xff00ff
	v_mov_b32_e32 v205, 0xffff8040
	v_mov_b32_e32 v214, 0x8040
	v_cndmask_b32_e64 v205, v205, 0, vcc
	v_cndmask_b32_e64 v214, 0, v214, vcc
	v_add_u32_e32 v205, v205, v207
	v_add_u32_e32 v214, v214, v207
	s_mov_b32 exec_lo, 0xff00ff00
	s_mov_b32 exec_hi, 0xff00ff00
	v_swap_b32 v44, v248
	v_swap_b32 v45, v249
	v_swap_b32 v46, v250
	v_swap_b32 v47, v251
	v_swap_b32 v36, v220
	v_swap_b32 v37, v221
	v_swap_b32 v38, v222
	v_swap_b32 v39, v223
	s_mov_b64 exec, -1
	global_store_dwordx4 v205, v[44:47], s[92:93]
	global_store_dwordx4 v205, v[36:39], s[92:93] offset:512
	global_store_dwordx4 v214, v[248:251], s[92:93]
	global_store_dwordx4 v214, v[220:223], s[92:93] offset:512
	v_add_u32_e32 v207, 0x10000, v207
	v_add_u32_e32 v206, 0x10000, v206
	global_load_dwordx4 v[248:251], v206, s[82:83] offset:64
	global_load_dwordx4 v[220:223], v206, s[82:83] offset:576
	global_load_dwordx4 v[244:247], v206, s[82:83]
	global_load_dwordx4 v[216:219], v206, s[82:83] offset:512
	s_waitcnt lgkmcnt(0)
; DI u32x4 pack8(const float* v) { u32x4 w; w.x = pk2(v[0], v[1]); w.y = pk2(v[2], v[3]); w.z = pk2(v[4], v[5]); w.w = pk2(v[6], v[7]); return w; }
; #define xor16_32(s) xor16_32_l((s), fr + 16 * fq)
;     DI void operator()(AccRef acc, const Unit& u, int wr, int wc, int fr, int fq) const {
;     ...
; #pragma unroll
;                 for (int bj = 0; bj < 2; ++bj) {
;                     const int c = u.pn * 256 + bj * 128 + cl;
;                     float v[8];
; #pragma unroll
;                     for (int n = 0; n < 2; ++n) {
;                         const f32x4 x = *(const f32x4*)(xi + c + 4 * n);
;                         const f32x4 y = x + gt[bj][n] * acc[ai][bj][m][n];
;                         *(f32x4*)(xout + (size_t)row * 1024 + c + 4 * n) = y;
; #pragma unroll
;                         for (int j = 0; j < 4; ++j) { s += y[j] * y[j]; v[4 * n + j] = ap ? y[j] * gs[bj][n][j] : 0.f; }
;                     }
;                     if (ap) *(u32x4*)(ap + (size_t)row * 1024 + c) = pack8(v);
;                 }
;                 s = xor16_32(s);
;                 if (fq == 0) ssq[(size_t)row * 16 + u.pn * 4 + wc] = s;
	v_add_f32_e32 v211, v210, v211
	ds_bpermute_b32 v212, v202, v211
	v_add_u32_e32 v208, 0x8000, v208
	s_waitcnt lgkmcnt(0)
	v_add_f32_e32 v211, v211, v212
	s_mov_b64 exec, 0xffff
	global_store_dword v209, v211, s[90:91]
	s_mov_b64 exec, -1
	v_add_u32_e32 v209, 0x400, v209
	s_waitcnt vmcnt(12)
	v_permlane32_swap_b32_e32 v228, v232
	v_permlane32_swap_b32_e32 v229, v233
	v_permlane32_swap_b32_e32 v230, v234
	v_permlane32_swap_b32_e32 v231, v235
	v_permlane32_swap_b32_e32 v236, v240
	v_permlane32_swap_b32_e32 v237, v241
	v_permlane32_swap_b32_e32 v238, v242
	v_permlane32_swap_b32_e32 v239, v243
	v_permlane16_swap_b32_e32 v228, v232
	v_permlane16_swap_b32_e32 v229, v233
	v_permlane16_swap_b32_e32 v230, v234
	v_permlane16_swap_b32_e32 v231, v235
	v_permlane16_swap_b32_e32 v236, v240
	v_permlane16_swap_b32_e32 v237, v241
	v_permlane16_swap_b32_e32 v238, v242
	v_permlane16_swap_b32_e32 v239, v243
	v_pk_fma_f32 v[28:29], v[28:29], v[76:77], v[228:229]
	v_pk_fma_f32 v[30:31], v[30:31], v[78:79], v[230:231]
	v_mul_f32_e32 v210, v29, v29
	v_fmac_f32_e32 v210, v28, v28
	v_fmac_f32_e32 v210, v30, v30
	v_fmac_f32_e32 v210, v31, v31
	v_pk_mul_f32 v[228:229], v[100:101], v[28:29]
	v_pk_mul_f32 v[230:231], v[102:103], v[30:31]
	v_pk_fma_f32 v[24:25], v[24:25], v[72:73], v[232:233]
	v_pk_fma_f32 v[26:27], v[26:27], v[74:75], v[234:235]
	v_fmac_f32_e32 v210, v24, v24
	v_fmac_f32_e32 v210, v25, v25
	v_fmac_f32_e32 v210, v26, v26
	v_fmac_f32_e32 v210, v27, v27
	v_pk_mul_f32 v[232:233], v[98:99], v[24:25]
	v_pk_mul_f32 v[234:235], v[96:97], v[26:27]
	v_cvt_pk_bf16_f32 v228, v228, v229
	v_cvt_pk_bf16_f32 v229, v230, v231
	v_cvt_pk_bf16_f32 v230, v232, v233
	v_cvt_pk_bf16_f32 v231, v234, v235
	global_store_dwordx4 v208, v[228:231], s[64:65]
	v_pk_fma_f32 v[20:21], v[20:21], v[68:69], v[236:237]
	v_pk_fma_f32 v[22:23], v[22:23], v[70:71], v[238:239]
	v_fmac_f32_e32 v210, v20, v20
	v_fmac_f32_e32 v210, v21, v21
	v_fmac_f32_e32 v210, v22, v22
	v_fmac_f32_e32 v210, v23, v23
	v_pk_mul_f32 v[236:237], v[86:87], v[20:21]
	v_pk_mul_f32 v[238:239], v[84:85], v[22:23]
	v_pk_fma_f32 v[16:17], v[16:17], v[64:65], v[240:241]
	v_pk_fma_f32 v[18:19], v[18:19], v[66:67], v[242:243]
	v_fmac_f32_e32 v210, v16, v16
	v_fmac_f32_e32 v210, v17, v17
	v_fmac_f32_e32 v210, v18, v18
	v_fmac_f32_e32 v210, v19, v19
	v_pk_mul_f32 v[240:241], v[80:81], v[16:17]
	v_pk_mul_f32 v[242:243], v[82:83], v[18:19]
	v_cvt_pk_bf16_f32 v236, v236, v237
	v_cvt_pk_bf16_f32 v237, v238, v239
	v_cvt_pk_bf16_f32 v238, v240, v241
	v_cvt_pk_bf16_f32 v239, v242, v243
	global_store_dwordx4 v208, v[236:239], s[64:65] offset:256
	ds_bpermute_b32 v211, v203, v210
	v_permlane16_swap_b32_e32 v28, v24
	v_permlane16_swap_b32_e32 v29, v25
	v_permlane16_swap_b32_e32 v30, v26
	v_permlane16_swap_b32_e32 v31, v27
	v_permlane16_swap_b32_e32 v20, v16
	v_permlane16_swap_b32_e32 v21, v17
	v_permlane16_swap_b32_e32 v22, v18
	v_permlane16_swap_b32_e32 v23, v19
	v_permlane32_swap_b32_e32 v28, v24
	v_permlane32_swap_b32_e32 v29, v25
	v_permlane32_swap_b32_e32 v30, v26
	v_permlane32_swap_b32_e32 v31, v27
	v_permlane32_swap_b32_e32 v20, v16
	v_permlane32_swap_b32_e32 v21, v17
	v_permlane32_swap_b32_e32 v22, v18
	v_permlane32_swap_b32_e32 v23, v19
	s_nop 1
	v_mov_b32_dpp v232, v24 row_ror:8 row_mask:0xf bank_mask:0xf
	v_mov_b32_dpp v233, v25 row_ror:8 row_mask:0xf bank_mask:0xf
	v_mov_b32_dpp v234, v26 row_ror:8 row_mask:0xf bank_mask:0xf
	v_mov_b32_dpp v235, v27 row_ror:8 row_mask:0xf bank_mask:0xf
	v_mov_b32_dpp v240, v16 row_ror:8 row_mask:0xf bank_mask:0xf
	v_mov_b32_dpp v241, v17 row_ror:8 row_mask:0xf bank_mask:0xf
	v_mov_b32_dpp v242, v18 row_ror:8 row_mask:0xf bank_mask:0xf
	v_mov_b32_dpp v243, v19 row_ror:8 row_mask:0xf bank_mask:0xf
	s_mov_b32 vcc_lo, 0xff00ff
	s_mov_b32 vcc_hi, 0xff00ff
	v_mov_b32_e32 v205, 0xffff8040
	v_mov_b32_e32 v214, 0x8040
	v_cndmask_b32_e64 v205, v205, 0, vcc
	v_cndmask_b32_e64 v214, 0, v214, vcc
	v_add_u32_e32 v205, v205, v207
	v_add_u32_e32 v214, v214, v207
	s_mov_b32 exec_lo, 0xff00ff00
	s_mov_b32 exec_hi, 0xff00ff00
	v_swap_b32 v28, v232
	v_swap_b32 v29, v233
	v_swap_b32 v30, v234
	v_swap_b32 v31, v235
	v_swap_b32 v20, v240
	v_swap_b32 v21, v241
	v_swap_b32 v22, v242
	v_swap_b32 v23, v243
	s_mov_b64 exec, -1
	global_store_dwordx4 v205, v[28:31], s[92:93]
	global_store_dwordx4 v205, v[20:23], s[92:93] offset:512
	global_store_dwordx4 v214, v[232:235], s[92:93]
	global_store_dwordx4 v214, v[240:243], s[92:93] offset:512
	v_add_u32_e32 v207, 0x10000, v207
	s_waitcnt lgkmcnt(0)
	v_add_f32_e32 v211, v210, v211
	ds_bpermute_b32 v212, v202, v211
	v_add_u32_e32 v208, 0x8000, v208
	s_waitcnt lgkmcnt(0)
; DI u32x4 pack8(const float* v) { u32x4 w; w.x = pk2(v[0], v[1]); w.y = pk2(v[2], v[3]); w.z = pk2(v[4], v[5]); w.w = pk2(v[6], v[7]); return w; }
; #define xor16_32(s) xor16_32_l((s), fr + 16 * fq)
;     DI void operator()(AccRef acc, const Unit& u, int wr, int wc, int fr, int fq) const {
;     ...
; #pragma unroll
;                 for (int bj = 0; bj < 2; ++bj) {
;                     const int c = u.pn * 256 + bj * 128 + cl;
;                     float v[8];
; #pragma unroll
;                     for (int n = 0; n < 2; ++n) {
;                         const f32x4 x = *(const f32x4*)(xi + c + 4 * n);
;                         const f32x4 y = x + gt[bj][n] * acc[ai][bj][m][n];
;                         *(f32x4*)(xout + (size_t)row * 1024 + c + 4 * n) = y;
; #pragma unroll
;                         for (int j = 0; j < 4; ++j) { s += y[j] * y[j]; v[4 * n + j] = ap ? y[j] * gs[bj][n][j] : 0.f; }
;                     }
;                     if (ap) *(u32x4*)(ap + (size_t)row * 1024 + c) = pack8(v);
;                 }
;                 s = xor16_32(s);
;                 if (fq == 0) ssq[(size_t)row * 16 + u.pn * 4 + wc] = s;
	v_add_f32_e32 v211, v211, v212
	s_mov_b64 exec, 0xffff
	global_store_dword v209, v211, s[90:91]
	s_mov_b64 exec, -1
	v_add_u32_e32 v209, 0x400, v209
	s_waitcnt vmcnt(8)
	v_permlane32_swap_b32_e32 v244, v248
	v_permlane32_swap_b32_e32 v245, v249
	v_permlane32_swap_b32_e32 v246, v250
	v_permlane32_swap_b32_e32 v247, v251
	v_permlane32_swap_b32_e32 v216, v220
	v_permlane32_swap_b32_e32 v217, v221
	v_permlane32_swap_b32_e32 v218, v222
	v_permlane32_swap_b32_e32 v219, v223
	v_permlane16_swap_b32_e32 v244, v248
	v_permlane16_swap_b32_e32 v245, v249
	v_permlane16_swap_b32_e32 v246, v250
	v_permlane16_swap_b32_e32 v247, v251
	v_permlane16_swap_b32_e32 v216, v220
	v_permlane16_swap_b32_e32 v217, v221
	v_permlane16_swap_b32_e32 v218, v222
	v_permlane16_swap_b32_e32 v219, v223
	v_pk_fma_f32 v[12:13], v[12:13], v[76:77], v[244:245]
	v_pk_fma_f32 v[14:15], v[14:15], v[78:79], v[246:247]
	v_mul_f32_e32 v210, v13, v13
	v_fmac_f32_e32 v210, v12, v12
	v_fmac_f32_e32 v210, v14, v14
	v_fmac_f32_e32 v210, v15, v15
	v_pk_mul_f32 v[244:245], v[100:101], v[12:13]
	v_pk_mul_f32 v[246:247], v[102:103], v[14:15]
	v_pk_fma_f32 v[8:9], v[8:9], v[72:73], v[248:249]
	v_pk_fma_f32 v[10:11], v[10:11], v[74:75], v[250:251]
	v_fmac_f32_e32 v210, v8, v8
	v_fmac_f32_e32 v210, v9, v9
	v_fmac_f32_e32 v210, v10, v10
	v_fmac_f32_e32 v210, v11, v11
	v_pk_mul_f32 v[248:249], v[98:99], v[8:9]
	v_pk_mul_f32 v[250:251], v[96:97], v[10:11]
	v_cvt_pk_bf16_f32 v244, v244, v245
	v_cvt_pk_bf16_f32 v245, v246, v247
	v_cvt_pk_bf16_f32 v246, v248, v249
	v_cvt_pk_bf16_f32 v247, v250, v251
	global_store_dwordx4 v208, v[244:247], s[64:65]
	v_pk_fma_f32 v[4:5], v[4:5], v[68:69], v[216:217]
	v_pk_fma_f32 v[6:7], v[6:7], v[70:71], v[218:219]
	v_fmac_f32_e32 v210, v4, v4
	v_fmac_f32_e32 v210, v5, v5
	v_fmac_f32_e32 v210, v6, v6
	v_fmac_f32_e32 v210, v7, v7
	v_pk_mul_f32 v[216:217], v[86:87], v[4:5]
	v_pk_mul_f32 v[218:219], v[84:85], v[6:7]
	v_pk_fma_f32 v[0:1], v[0:1], v[64:65], v[220:221]
	v_pk_fma_f32 v[2:3], v[2:3], v[66:67], v[222:223]
	v_fmac_f32_e32 v210, v0, v0
	v_fmac_f32_e32 v210, v1, v1
	v_fmac_f32_e32 v210, v2, v2
	v_fmac_f32_e32 v210, v3, v3
	v_pk_mul_f32 v[220:221], v[80:81], v[0:1]
	v_pk_mul_f32 v[222:223], v[82:83], v[2:3]
	v_cvt_pk_bf16_f32 v216, v216, v217
	v_cvt_pk_bf16_f32 v217, v218, v219
	v_cvt_pk_bf16_f32 v218, v220, v221
	v_cvt_pk_bf16_f32 v219, v222, v223
	global_store_dwordx4 v208, v[216:219], s[64:65] offset:256
	ds_bpermute_b32 v211, v203, v210
	v_permlane16_swap_b32_e32 v12, v8
	v_permlane16_swap_b32_e32 v13, v9
	v_permlane16_swap_b32_e32 v14, v10
	v_permlane16_swap_b32_e32 v15, v11
	v_permlane16_swap_b32_e32 v4, v0
	v_permlane16_swap_b32_e32 v5, v1
	v_permlane16_swap_b32_e32 v6, v2
	v_permlane16_swap_b32_e32 v7, v3
	v_permlane32_swap_b32_e32 v12, v8
	v_permlane32_swap_b32_e32 v13, v9
	v_permlane32_swap_b32_e32 v14, v10
	v_permlane32_swap_b32_e32 v15, v11
	v_permlane32_swap_b32_e32 v4, v0
	v_permlane32_swap_b32_e32 v5, v1
	v_permlane32_swap_b32_e32 v6, v2
	v_permlane32_swap_b32_e32 v7, v3
	s_nop 1
	v_mov_b32_dpp v248, v8 row_ror:8 row_mask:0xf bank_mask:0xf
	v_mov_b32_dpp v249, v9 row_ror:8 row_mask:0xf bank_mask:0xf
	v_mov_b32_dpp v250, v10 row_ror:8 row_mask:0xf bank_mask:0xf
	v_mov_b32_dpp v251, v11 row_ror:8 row_mask:0xf bank_mask:0xf
	v_mov_b32_dpp v220, v0 row_ror:8 row_mask:0xf bank_mask:0xf
	v_mov_b32_dpp v221, v1 row_ror:8 row_mask:0xf bank_mask:0xf
	v_mov_b32_dpp v222, v2 row_ror:8 row_mask:0xf bank_mask:0xf
	v_mov_b32_dpp v223, v3 row_ror:8 row_mask:0xf bank_mask:0xf
	s_mov_b32 vcc_lo, 0xff00ff
	s_mov_b32 vcc_hi, 0xff00ff
	v_mov_b32_e32 v205, 0xffff8040
	v_mov_b32_e32 v214, 0x8040
	v_cndmask_b32_e64 v205, v205, 0, vcc
	v_cndmask_b32_e64 v214, 0, v214, vcc
	v_add_u32_e32 v205, v205, v207
	v_add_u32_e32 v214, v214, v207
	s_mov_b32 exec_lo, 0xff00ff00
	s_mov_b32 exec_hi, 0xff00ff00
	v_swap_b32 v12, v248
	v_swap_b32 v13, v249
	v_swap_b32 v14, v250
	v_swap_b32 v15, v251
	v_swap_b32 v4, v220
	v_swap_b32 v5, v221
	v_swap_b32 v6, v222
	v_swap_b32 v7, v223
	s_mov_b64 exec, -1
	global_store_dwordx4 v205, v[12:15], s[92:93]
	global_store_dwordx4 v205, v[4:7], s[92:93] offset:512
	global_store_dwordx4 v214, v[248:251], s[92:93]
	global_store_dwordx4 v214, v[220:223], s[92:93] offset:512
	s_waitcnt lgkmcnt(0)
	v_add_f32_e32 v211, v210, v211
	ds_bpermute_b32 v212, v202, v211
	s_waitcnt lgkmcnt(0)
	v_add_f32_e32 v211, v211, v212
	s_mov_b64 exec, 0xffff
	global_store_dword v209, v211, s[90:91]
	s_mov_b64 exec, -1
	s_andn2_b64 vcc, exec, s[0:1]
	s_mov_b64 s[0:1], -1
	s_cbranch_vccnz .LBB0_1083
	s_andn2_b64 vcc, exec, s[4:5]
	s_cbranch_vccnz .LBB0_1082
	s_barrier
	s_branch .LBB0_1082

;     DI void operator()(AccRef acc, const Unit& u, int wr, int wc, int fr, int fq) const {
;     ...
; #pragma unroll
;         for (int ai = 0; ai < 2; ++ai) {
;             const int rb = u.pm * 256 + ai * 128 + wr * 64 + fr;
;             int mb, pos0, kv0; row_info(rb, mb, pos0, kv0);
;             f32x4 gt[2][2], gs[2][2];
; #pragma unroll
;             for (int bj = 0; bj < 2; ++bj)
; #pragma unroll
;                 for (int n = 0; n < 2; ++n) {
;                     const int c = u.pn * 256 + bj * 128 + cl + 4 * n;
;                     gt[bj][n] = *(const f32x4*)(gate + (size_t)mb * 6144 + c);
;                     if (ap) { const f32x4 g = *(const f32x4*)(gn + c), s = *(const f32x4*)(scn + (size_t)mb * 6144 + c); gs[bj][n] = g * (s + 1.f); }
;                 }
; #pragma unroll
;             for (int m = 0; m < 4; ++m) {
;                 const int row = rb + 16 * m;
;                 const float* xi = row < MP ? xin_p + (size_t)row * 1024 : xin_s + (size_t)(row - MP) * 1024;
.LBB0_1303:
	v_readlane_b32 s1, v253, 32
	v_mbcnt_lo_u32_b32 v100, -1, 0
	v_mbcnt_hi_u32_b32 v100, -1, v100
	s_mov_b32 s1, s28
	v_and_b32_e32 v202, 15, v100
	v_bfe_u32 v204, v100, 4, 2
	s_mov_b32 s12, s34
	s_lshl_b32 s16, s16, 8
	s_lshl_b32 s1, s1, 6
	s_add_i32 s1, s1, s16
	v_add_u32_e32 v192, s1, v202
	s_lshl_b32 s13, s12, 5
	s_lshl_b32 s1, s0, 8
	v_add_u32_e32 v224, 0xffffc000, v192
	s_add_i32 s13, s13, s1
	v_lshrrev_b32_e32 v101, 6, v224
	v_lshl_add_u32 v188, v204, 3, s13
	v_ashrrev_i32_e32 v100, 11, v192
	v_add_u32_e32 v101, 8, v101
	v_cmp_gt_i32_e32 vcc, s94, v192
	v_mov_b64_e32 v[102:103], s[56:57]
	v_ashrrev_i32_e32 v189, 31, v188
	v_cndmask_b32_e32 v104, v101, v100, vcc
	v_mov_b64_e32 v[100:101], s[6:7]
	v_mad_i64_i32 v[100:101], s[16:17], v104, s75, v[100:101]
	v_mad_i64_i32 v[102:103], s[16:17], v104, s75, v[102:103]
	v_lshlrev_b64 v[190:191], 2, v[188:189]
	v_lshl_add_u64 v[104:105], v[100:101], 0, v[190:191]
	v_lshl_add_u64 v[194:195], s[72:73], 0, v[190:191]
	v_lshl_add_u64 v[168:169], v[102:103], 0, v[190:191]
	global_load_dwordx4 v[108:111], v[104:105], off offset:16
	global_load_dwordx4 v[116:119], v[104:105], off
	global_load_dwordx4 v[148:151], v[194:195], off offset:16
	global_load_dwordx4 v[164:167], v[194:195], off
	global_load_dwordx4 v[160:163], v[168:169], off offset:16
	global_load_dwordx4 v[172:175], v[168:169], off
	global_load_dwordx4 v[100:103], v[104:105], off offset:528
	s_nop 0
	global_load_dwordx4 v[104:107], v[104:105], off offset:512
	s_nop 0
	global_load_dwordx4 v[144:147], v[194:195], off offset:528
	global_load_dwordx4 v[156:159], v[194:195], off offset:512
	global_load_dwordx4 v[152:155], v[168:169], off offset:528
	s_nop 0
	global_load_dwordx4 v[168:171], v[168:169], off offset:512
	s_movk_i32 s1, 0x3fff
	v_cmp_lt_i32_e32 vcc, s1, v192
	s_and_saveexec_b64 s[16:17], vcc
	s_xor_b64 s[16:17], exec, s[16:17]
	v_lshlrev_b64 v[196:197], 12, v[224:225]
	v_mov_b32_e32 v193, v225
	v_lshl_add_u64 v[198:199], s[20:21], 0, v[196:197]
	v_lshlrev_b64 v[196:197], 12, v[192:193]
	s_andn2_saveexec_b64 s[16:17], s[16:17]
	v_ashrrev_i32_e32 v193, 31, v192
	v_lshlrev_b64 v[196:197], 12, v[192:193]
	v_lshl_add_u64 v[198:199], s[42:43], 0, v[196:197]
	s_or_b64 exec, exec, s[16:17]
	s_mov_b32 s18, 0xff00ff
	s_mov_b32 s19, 0xff00ff
	s_sub_u32 s82, s20, 0x4000000
	s_subb_u32 s83, s21, 0
	s_cmp_ge_u32 s16, 0x4000
	s_cselect_b32 s82, s82, s42
	s_cselect_b32 s83, s83, s43
	v_lshl_add_u32 v206, v192, 12, v190
	v_lshlrev_b32_e32 v213, 4, v204
	v_sub_u32_e32 v206, v206, v213
	v_lshlrev_b32_e32 v213, 11, v192
	v_lshlrev_b32_e32 v209, 6, v192
	v_mov_b32_e32 v207, v206
	v_lshl_add_u32 v208, v188, 1, v213
	global_load_dwordx4 v[232:235], v206, s[82:83] offset:64
	global_load_dwordx4 v[240:243], v206, s[82:83] offset:576
	global_load_dwordx4 v[228:231], v206, s[82:83]
	global_load_dwordx4 v[236:239], v206, s[82:83] offset:512
	v_add_u32_e32 v206, 0x10000, v206
	global_load_dwordx4 v[248:251], v206, s[82:83] offset:64
	global_load_dwordx4 v[220:223], v206, s[82:83] offset:576
	global_load_dwordx4 v[244:247], v206, s[82:83]
	global_load_dwordx4 v[216:219], v206, s[82:83] offset:512
	v_add_u32_e32 v206, 0x10000, v206
	s_waitcnt vmcnt(8)
	v_pk_add_f32 v[172:173], v[172:173], 1.0 op_sel_hi:[1,0]
	v_pk_add_f32 v[154:155], v[154:155], 1.0 op_sel_hi:[1,0]
	v_pk_mul_f32 v[164:165], v[164:165], v[172:173]
	v_pk_add_f32 v[172:173], v[160:161], 1.0 op_sel_hi:[1,0]
	v_pk_add_f32 v[160:161], v[162:163], 1.0 op_sel_hi:[1,0]
	v_pk_mul_f32 v[162:163], v[148:149], v[172:173]
	v_pk_mul_f32 v[160:161], v[150:151], v[160:161]
	v_pk_add_f32 v[148:149], v[170:171], 1.0 op_sel_hi:[1,0]
	v_pk_add_f32 v[150:151], v[168:169], 1.0 op_sel_hi:[1,0]
	v_pk_mul_f32 v[146:147], v[146:147], v[154:155]
	v_lshl_add_u64 v[154:155], v[198:199], 0, v[190:191]
	v_pk_mul_f32 v[148:149], v[158:159], v[148:149]
	v_pk_mul_f32 v[150:151], v[156:157], v[150:151]
	v_pk_add_f32 v[174:175], v[174:175], 1.0 op_sel_hi:[1,0]
	v_pk_add_f32 v[152:153], v[152:153], 1.0 op_sel_hi:[1,0]
	v_pk_mul_f32 v[166:167], v[166:167], v[174:175]
	v_pk_mul_f32 v[144:145], v[144:145], v[152:153]
	v_lshlrev_b64 v[152:153], 11, v[192:193]
	v_lshl_add_u64 v[152:153], s[58:59], 0, v[152:153]
	v_lshlrev_b32_e32 v202, 2, v202
	v_lshl_add_u32 v202, v204, 6, v202
	v_xor_b32_e32 v203, 64, v202
	s_lshl_b32 s0, s0, 2
	v_xor_b32_e32 v202, 0x80, v202
	s_ashr_i32 s1, s0, 31
	s_ashr_i32 s13, s12, 31
	s_lshl_b64 s[0:1], s[0:1], 2
	s_add_u32 s16, s37, s0
	s_addc_u32 s17, s38, s1
	s_lshl_b64 s[0:1], s[12:13], 2
	s_add_u32 s90, s16, s0
	v_cmp_eq_u32_e32 vcc, 0, v204
	s_addc_u32 s91, s17, s1
	s_waitcnt vmcnt(4)
; DI u32x4 pack8(const float* v) { u32x4 w; w.x = pk2(v[0], v[1]); w.y = pk2(v[2], v[3]); w.z = pk2(v[4], v[5]); w.w = pk2(v[6], v[7]); return w; }
; #define xor16_32(s) xor16_32_l((s), fr + 16 * fq)
;     DI void operator()(AccRef acc, const Unit& u, int wr, int wc, int fr, int fq) const {
;     ...
; #pragma unroll
;                 for (int bj = 0; bj < 2; ++bj) {
;                     const int c = u.pn * 256 + bj * 128 + cl;
;                     float v[8];
; #pragma unroll
;                     for (int n = 0; n < 2; ++n) {
;                         const f32x4 x = *(const f32x4*)(xi + c + 4 * n);
;                         const f32x4 y = x + gt[bj][n] * acc[ai][bj][m][n];
;                         *(f32x4*)(xout + (size_t)row * 1024 + c + 4 * n) = y;
; #pragma unroll
;                         for (int j = 0; j < 4; ++j) { s += y[j] * y[j]; v[4 * n + j] = ap ? y[j] * gs[bj][n][j] : 0.f; }
;                     }
;                     if (ap) *(u32x4*)(ap + (size_t)row * 1024 + c) = pack8(v);
;                 }
;                 s = xor16_32(s);
;                 if (fq == 0) ssq[(size_t)row * 16 + u.pn * 4 + wc] = s;
	v_permlane32_swap_b32_e32 v228, v232
	v_permlane32_swap_b32_e32 v229, v233
	v_permlane32_swap_b32_e32 v230, v234
	v_permlane32_swap_b32_e32 v231, v235
	v_permlane32_swap_b32_e32 v236, v240
	v_permlane32_swap_b32_e32 v237, v241
	v_permlane32_swap_b32_e32 v238, v242
	v_permlane32_swap_b32_e32 v239, v243
	v_permlane16_swap_b32_e32 v228, v232
	v_permlane16_swap_b32_e32 v229, v233
	v_permlane16_swap_b32_e32 v230, v234
	v_permlane16_swap_b32_e32 v231, v235
	v_permlane16_swap_b32_e32 v236, v240
	v_permlane16_swap_b32_e32 v237, v241
	v_permlane16_swap_b32_e32 v238, v242
	v_permlane16_swap_b32_e32 v239, v243
	v_pk_fma_f32 v[140:141], v[140:141], v[116:117], v[228:229]
	v_pk_fma_f32 v[142:143], v[142:143], v[118:119], v[230:231]
	v_mul_f32_e32 v210, v141, v141
	v_fmac_f32_e32 v210, v140, v140
	v_fmac_f32_e32 v210, v142, v142
	v_fmac_f32_e32 v210, v143, v143
	v_pk_mul_f32 v[228:229], v[164:165], v[140:141]
	v_pk_mul_f32 v[230:231], v[166:167], v[142:143]
	v_pk_fma_f32 v[136:137], v[136:137], v[108:109], v[232:233]
	v_pk_fma_f32 v[138:139], v[138:139], v[110:111], v[234:235]
	v_fmac_f32_e32 v210, v136, v136
	v_fmac_f32_e32 v210, v137, v137
	v_fmac_f32_e32 v210, v138, v138
	v_fmac_f32_e32 v210, v139, v139
	v_pk_mul_f32 v[232:233], v[162:163], v[136:137]
	v_pk_mul_f32 v[234:235], v[160:161], v[138:139]
	v_cvt_pk_bf16_f32 v228, v228, v229
	v_cvt_pk_bf16_f32 v229, v230, v231
	v_cvt_pk_bf16_f32 v230, v232, v233
	v_cvt_pk_bf16_f32 v231, v234, v235
	global_store_dwordx4 v208, v[228:231], s[58:59]
	v_pk_fma_f32 v[132:133], v[132:133], v[104:105], v[236:237]
	v_pk_fma_f32 v[134:135], v[134:135], v[106:107], v[238:239]
	v_fmac_f32_e32 v210, v132, v132
	v_fmac_f32_e32 v210, v133, v133
	v_fmac_f32_e32 v210, v134, v134
	v_fmac_f32_e32 v210, v135, v135
	v_pk_mul_f32 v[236:237], v[150:151], v[132:133]
	v_pk_mul_f32 v[238:239], v[148:149], v[134:135]
	v_pk_fma_f32 v[128:129], v[128:129], v[100:101], v[240:241]
	v_pk_fma_f32 v[130:131], v[130:131], v[102:103], v[242:243]
	v_fmac_f32_e32 v210, v128, v128
	v_fmac_f32_e32 v210, v129, v129
	v_fmac_f32_e32 v210, v130, v130
	v_fmac_f32_e32 v210, v131, v131
	v_pk_mul_f32 v[240:241], v[144:145], v[128:129]
	v_pk_mul_f32 v[242:243], v[146:147], v[130:131]
	v_cvt_pk_bf16_f32 v236, v236, v237
	v_cvt_pk_bf16_f32 v237, v238, v239
	v_cvt_pk_bf16_f32 v238, v240, v241
	v_cvt_pk_bf16_f32 v239, v242, v243
	global_store_dwordx4 v208, v[236:239], s[58:59] offset:256
	ds_bpermute_b32 v211, v203, v210
	v_permlane16_swap_b32_e32 v140, v136
	v_permlane16_swap_b32_e32 v141, v137
	v_permlane16_swap_b32_e32 v142, v138
	v_permlane16_swap_b32_e32 v143, v139
	v_permlane16_swap_b32_e32 v132, v128
	v_permlane16_swap_b32_e32 v133, v129
	v_permlane16_swap_b32_e32 v134, v130
	v_permlane16_swap_b32_e32 v135, v131
	v_permlane32_swap_b32_e32 v140, v136
	v_permlane32_swap_b32_e32 v141, v137
	v_permlane32_swap_b32_e32 v142, v138
	v_permlane32_swap_b32_e32 v143, v139
	v_permlane32_swap_b32_e32 v132, v128
	v_permlane32_swap_b32_e32 v133, v129
	v_permlane32_swap_b32_e32 v134, v130
	v_permlane32_swap_b32_e32 v135, v131
	s_nop 1
	v_mov_b32_dpp v232, v136 row_ror:8 row_mask:0xf bank_mask:0xf
	v_mov_b32_dpp v233, v137 row_ror:8 row_mask:0xf bank_mask:0xf
	v_mov_b32_dpp v234, v138 row_ror:8 row_mask:0xf bank_mask:0xf
	v_mov_b32_dpp v235, v139 row_ror:8 row_mask:0xf bank_mask:0xf
	v_mov_b32_dpp v240, v128 row_ror:8 row_mask:0xf bank_mask:0xf
	v_mov_b32_dpp v241, v129 row_ror:8 row_mask:0xf bank_mask:0xf
	v_mov_b32_dpp v242, v130 row_ror:8 row_mask:0xf bank_mask:0xf
	v_mov_b32_dpp v243, v131 row_ror:8 row_mask:0xf bank_mask:0xf
	s_mov_b32 vcc_lo, 0xff00ff
	s_mov_b32 vcc_hi, 0xff00ff
	v_mov_b32_e32 v205, 0xffff8040
	v_mov_b32_e32 v214, 0x8040
	v_cndmask_b32_e64 v205, v205, 0, vcc
	v_cndmask_b32_e64 v214, 0, v214, vcc
	v_add_u32_e32 v205, v205, v207
	v_add_u32_e32 v214, v214, v207
	s_mov_b32 exec_lo, 0xff00ff00
	s_mov_b32 exec_hi, 0xff00ff00
	v_swap_b32 v140, v232
	v_swap_b32 v141, v233
	v_swap_b32 v142, v234
	v_swap_b32 v143, v235
	v_swap_b32 v132, v240
	v_swap_b32 v133, v241
	v_swap_b32 v134, v242
	v_swap_b32 v135, v243
	s_mov_b64 exec, -1
	global_store_dwordx4 v205, v[140:143], s[92:93]
	global_store_dwordx4 v205, v[132:135], s[92:93] offset:512
	global_store_dwordx4 v214, v[232:235], s[92:93]
	global_store_dwordx4 v214, v[240:243], s[92:93] offset:512
	v_add_u32_e32 v207, 0x10000, v207
	global_load_dwordx4 v[232:235], v206, s[82:83] offset:64
	global_load_dwordx4 v[240:243], v206, s[82:83] offset:576
	global_load_dwordx4 v[228:231], v206, s[82:83]
	global_load_dwordx4 v[236:239], v206, s[82:83] offset:512
	s_waitcnt lgkmcnt(0)
	v_add_f32_e32 v211, v210, v211
	ds_bpermute_b32 v212, v202, v211
	v_add_u32_e32 v208, 0x8000, v208
	s_waitcnt lgkmcnt(0)
	v_add_f32_e32 v211, v211, v212
	s_mov_b64 exec, 0xffff
	global_store_dword v209, v211, s[90:91]
	s_mov_b64 exec, -1
	v_add_u32_e32 v209, 0x400, v209
	s_waitcnt vmcnt(11)
; DI u32x4 pack8(const float* v) { u32x4 w; w.x = pk2(v[0], v[1]); w.y = pk2(v[2], v[3]); w.z = pk2(v[4], v[5]); w.w = pk2(v[6], v[7]); return w; }
; #define xor16_32(s) xor16_32_l((s), fr + 16 * fq)
;     DI void operator()(AccRef acc, const Unit& u, int wr, int wc, int fr, int fq) const {
;     ...
; #pragma unroll
;                 for (int bj = 0; bj < 2; ++bj) {
;                     const int c = u.pn * 256 + bj * 128 + cl;
;                     float v[8];
; #pragma unroll
;                     for (int n = 0; n < 2; ++n) {
;                         const f32x4 x = *(const f32x4*)(xi + c + 4 * n);
;                         const f32x4 y = x + gt[bj][n] * acc[ai][bj][m][n];
;                         *(f32x4*)(xout + (size_t)row * 1024 + c + 4 * n) = y;
; #pragma unroll
;                         for (int j = 0; j < 4; ++j) { s += y[j] * y[j]; v[4 * n + j] = ap ? y[j] * gs[bj][n][j] : 0.f; }
;                     }
;                     if (ap) *(u32x4*)(ap + (size_t)row * 1024 + c) = pack8(v);
;                 }
;                 s = xor16_32(s);
;                 if (fq == 0) ssq[(size_t)row * 16 + u.pn * 4 + wc] = s;
	v_permlane32_swap_b32_e32 v244, v248
	v_permlane32_swap_b32_e32 v245, v249
	v_permlane32_swap_b32_e32 v246, v250
	v_permlane32_swap_b32_e32 v247, v251
	v_permlane32_swap_b32_e32 v216, v220
	v_permlane32_swap_b32_e32 v217, v221
	v_permlane32_swap_b32_e32 v218, v222
	v_permlane32_swap_b32_e32 v219, v223
	v_permlane16_swap_b32_e32 v244, v248
	v_permlane16_swap_b32_e32 v245, v249
	v_permlane16_swap_b32_e32 v246, v250
	v_permlane16_swap_b32_e32 v247, v251
	v_permlane16_swap_b32_e32 v216, v220
	v_permlane16_swap_b32_e32 v217, v221
	v_permlane16_swap_b32_e32 v218, v222
	v_permlane16_swap_b32_e32 v219, v223
	v_pk_fma_f32 v[124:125], v[124:125], v[116:117], v[244:245]
	v_pk_fma_f32 v[126:127], v[126:127], v[118:119], v[246:247]
	v_mul_f32_e32 v210, v125, v125
	v_fmac_f32_e32 v210, v124, v124
	v_fmac_f32_e32 v210, v126, v126
	v_fmac_f32_e32 v210, v127, v127
	v_pk_mul_f32 v[244:245], v[164:165], v[124:125]
	v_pk_mul_f32 v[246:247], v[166:167], v[126:127]
	v_pk_fma_f32 v[120:121], v[120:121], v[108:109], v[248:249]
	v_pk_fma_f32 v[122:123], v[122:123], v[110:111], v[250:251]
	v_fmac_f32_e32 v210, v120, v120
	v_fmac_f32_e32 v210, v121, v121
	v_fmac_f32_e32 v210, v122, v122
	v_fmac_f32_e32 v210, v123, v123
	v_pk_mul_f32 v[248:249], v[162:163], v[120:121]
	v_pk_mul_f32 v[250:251], v[160:161], v[122:123]
	v_cvt_pk_bf16_f32 v244, v244, v245
	v_cvt_pk_bf16_f32 v245, v246, v247
	v_cvt_pk_bf16_f32 v246, v248, v249
	v_cvt_pk_bf16_f32 v247, v250, v251
	global_store_dwordx4 v208, v[244:247], s[58:59]
	v_pk_fma_f32 v[112:113], v[112:113], v[104:105], v[216:217]
	v_pk_fma_f32 v[114:115], v[114:115], v[106:107], v[218:219]
	v_fmac_f32_e32 v210, v112, v112
	v_fmac_f32_e32 v210, v113, v113
	v_fmac_f32_e32 v210, v114, v114
	v_fmac_f32_e32 v210, v115, v115
	v_pk_mul_f32 v[216:217], v[150:151], v[112:113]
	v_pk_mul_f32 v[218:219], v[148:149], v[114:115]
	v_pk_fma_f32 v[96:97], v[96:97], v[100:101], v[220:221]
	v_pk_fma_f32 v[98:99], v[98:99], v[102:103], v[222:223]
	v_fmac_f32_e32 v210, v96, v96
	v_fmac_f32_e32 v210, v97, v97
	v_fmac_f32_e32 v210, v98, v98
	v_fmac_f32_e32 v210, v99, v99
	v_pk_mul_f32 v[220:221], v[144:145], v[96:97]
	v_pk_mul_f32 v[222:223], v[146:147], v[98:99]
	v_cvt_pk_bf16_f32 v216, v216, v217
	v_cvt_pk_bf16_f32 v217, v218, v219
	v_cvt_pk_bf16_f32 v218, v220, v221
	v_cvt_pk_bf16_f32 v219, v222, v223
	global_store_dwordx4 v208, v[216:219], s[58:59] offset:256
	ds_bpermute_b32 v211, v203, v210
	v_permlane16_swap_b32_e32 v124, v120
	v_permlane16_swap_b32_e32 v125, v121
	v_permlane16_swap_b32_e32 v126, v122
	v_permlane16_swap_b32_e32 v127, v123
	v_permlane16_swap_b32_e32 v112, v96
	v_permlane16_swap_b32_e32 v113, v97
	v_permlane16_swap_b32_e32 v114, v98
	v_permlane16_swap_b32_e32 v115, v99
	v_permlane32_swap_b32_e32 v124, v120
	v_permlane32_swap_b32_e32 v125, v121
	v_permlane32_swap_b32_e32 v126, v122
	v_permlane32_swap_b32_e32 v127, v123
	v_permlane32_swap_b32_e32 v112, v96
	v_permlane32_swap_b32_e32 v113, v97
	v_permlane32_swap_b32_e32 v114, v98
	v_permlane32_swap_b32_e32 v115, v99
	s_nop 1
	v_mov_b32_dpp v248, v120 row_ror:8 row_mask:0xf bank_mask:0xf
	v_mov_b32_dpp v249, v121 row_ror:8 row_mask:0xf bank_mask:0xf
	v_mov_b32_dpp v250, v122 row_ror:8 row_mask:0xf bank_mask:0xf
	v_mov_b32_dpp v251, v123 row_ror:8 row_mask:0xf bank_mask:0xf
	v_mov_b32_dpp v220, v96 row_ror:8 row_mask:0xf bank_mask:0xf
	v_mov_b32_dpp v221, v97 row_ror:8 row_mask:0xf bank_mask:0xf
	v_mov_b32_dpp v222, v98 row_ror:8 row_mask:0xf bank_mask:0xf
	v_mov_b32_dpp v223, v99 row_ror:8 row_mask:0xf bank_mask:0xf
	s_mov_b32 vcc_lo, 0xff00ff
	s_mov_b32 vcc_hi, 0xff00ff
	v_mov_b32_e32 v205, 0xffff8040
	v_mov_b32_e32 v214, 0x8040
	v_cndmask_b32_e64 v205, v205, 0, vcc
	v_cndmask_b32_e64 v214, 0, v214, vcc
	v_add_u32_e32 v205, v205, v207
	v_add_u32_e32 v214, v214, v207
	s_mov_b32 exec_lo, 0xff00ff00
	s_mov_b32 exec_hi, 0xff00ff00
	v_swap_b32 v124, v248
	v_swap_b32 v125, v249
	v_swap_b32 v126, v250
	v_swap_b32 v127, v251
	v_swap_b32 v112, v220
	v_swap_b32 v113, v221
	v_swap_b32 v114, v222
	v_swap_b32 v115, v223
	s_mov_b64 exec, -1
	global_store_dwordx4 v205, v[124:127], s[92:93]
	global_store_dwordx4 v205, v[112:115], s[92:93] offset:512
	global_store_dwordx4 v214, v[248:251], s[92:93]
	global_store_dwordx4 v214, v[220:223], s[92:93] offset:512
	v_add_u32_e32 v207, 0x10000, v207
	v_add_u32_e32 v206, 0x10000, v206
	global_load_dwordx4 v[248:251], v206, s[82:83] offset:64
	global_load_dwordx4 v[220:223], v206, s[82:83] offset:576
	global_load_dwordx4 v[244:247], v206, s[82:83]
	global_load_dwordx4 v[216:219], v206, s[82:83] offset:512
	s_waitcnt lgkmcnt(0)
	v_add_f32_e32 v211, v210, v211
	ds_bpermute_b32 v212, v202, v211
	v_add_u32_e32 v208, 0x8000, v208
	s_waitcnt lgkmcnt(0)
	v_add_f32_e32 v211, v211, v212
	s_mov_b64 exec, 0xffff
	global_store_dword v209, v211, s[90:91]
	s_mov_b64 exec, -1
	v_add_u32_e32 v209, 0x400, v209
	s_waitcnt vmcnt(12)
; DI u32x4 pack8(const float* v) { u32x4 w; w.x = pk2(v[0], v[1]); w.y = pk2(v[2], v[3]); w.z = pk2(v[4], v[5]); w.w = pk2(v[6], v[7]); return w; }
; #define xor16_32(s) xor16_32_l((s), fr + 16 * fq)
;     DI void operator()(AccRef acc, const Unit& u, int wr, int wc, int fr, int fq) const {
;     ...
; #pragma unroll
;                 for (int bj = 0; bj < 2; ++bj) {
;                     const int c = u.pn * 256 + bj * 128 + cl;
;                     float v[8];
; #pragma unroll
;                     for (int n = 0; n < 2; ++n) {
;                         const f32x4 x = *(const f32x4*)(xi + c + 4 * n);
;                         const f32x4 y = x + gt[bj][n] * acc[ai][bj][m][n];
;                         *(f32x4*)(xout + (size_t)row * 1024 + c + 4 * n) = y;
; #pragma unroll
;                         for (int j = 0; j < 4; ++j) { s += y[j] * y[j]; v[4 * n + j] = ap ? y[j] * gs[bj][n][j] : 0.f; }
;                     }
;                     if (ap) *(u32x4*)(ap + (size_t)row * 1024 + c) = pack8(v);
;                 }
;                 s = xor16_32(s);
;                 if (fq == 0) ssq[(size_t)row * 16 + u.pn * 4 + wc] = s;
	v_permlane32_swap_b32_e32 v228, v232
	v_permlane32_swap_b32_e32 v229, v233
	v_permlane32_swap_b32_e32 v230, v234
	v_permlane32_swap_b32_e32 v231, v235
	v_permlane32_swap_b32_e32 v236, v240
	v_permlane32_swap_b32_e32 v237, v241
	v_permlane32_swap_b32_e32 v238, v242
	v_permlane32_swap_b32_e32 v239, v243
	v_permlane16_swap_b32_e32 v228, v232
	v_permlane16_swap_b32_e32 v229, v233
	v_permlane16_swap_b32_e32 v230, v234
	v_permlane16_swap_b32_e32 v231, v235
	v_permlane16_swap_b32_e32 v236, v240
	v_permlane16_swap_b32_e32 v237, v241
	v_permlane16_swap_b32_e32 v238, v242
	v_permlane16_swap_b32_e32 v239, v243
	v_pk_fma_f32 v[92:93], v[92:93], v[116:117], v[228:229]
	v_pk_fma_f32 v[94:95], v[94:95], v[118:119], v[230:231]
	v_mul_f32_e32 v210, v93, v93
	v_fmac_f32_e32 v210, v92, v92
	v_fmac_f32_e32 v210, v94, v94
	v_fmac_f32_e32 v210, v95, v95
	v_pk_mul_f32 v[228:229], v[164:165], v[92:93]
	v_pk_mul_f32 v[230:231], v[166:167], v[94:95]
	v_pk_fma_f32 v[88:89], v[88:89], v[108:109], v[232:233]
	v_pk_fma_f32 v[90:91], v[90:91], v[110:111], v[234:235]
	v_fmac_f32_e32 v210, v88, v88
	v_fmac_f32_e32 v210, v89, v89
	v_fmac_f32_e32 v210, v90, v90
	v_fmac_f32_e32 v210, v91, v91
	v_pk_mul_f32 v[232:233], v[162:163], v[88:89]
	v_pk_mul_f32 v[234:235], v[160:161], v[90:91]
	v_cvt_pk_bf16_f32 v228, v228, v229
	v_cvt_pk_bf16_f32 v229, v230, v231
	v_cvt_pk_bf16_f32 v230, v232, v233
	v_cvt_pk_bf16_f32 v231, v234, v235
	global_store_dwordx4 v208, v[228:231], s[58:59]
	v_pk_fma_f32 v[84:85], v[84:85], v[104:105], v[236:237]
	v_pk_fma_f32 v[86:87], v[86:87], v[106:107], v[238:239]
	v_fmac_f32_e32 v210, v84, v84
	v_fmac_f32_e32 v210, v85, v85
	v_fmac_f32_e32 v210, v86, v86
	v_fmac_f32_e32 v210, v87, v87
	v_pk_mul_f32 v[236:237], v[150:151], v[84:85]
	v_pk_mul_f32 v[238:239], v[148:149], v[86:87]
	v_pk_fma_f32 v[80:81], v[80:81], v[100:101], v[240:241]
	v_pk_fma_f32 v[82:83], v[82:83], v[102:103], v[242:243]
	v_fmac_f32_e32 v210, v80, v80
	v_fmac_f32_e32 v210, v81, v81
	v_fmac_f32_e32 v210, v82, v82
	v_fmac_f32_e32 v210, v83, v83
	v_pk_mul_f32 v[240:241], v[144:145], v[80:81]
	v_pk_mul_f32 v[242:243], v[146:147], v[82:83]
	v_cvt_pk_bf16_f32 v236, v236, v237
	v_cvt_pk_bf16_f32 v237, v238, v239
	v_cvt_pk_bf16_f32 v238, v240, v241
	v_cvt_pk_bf16_f32 v239, v242, v243
	global_store_dwordx4 v208, v[236:239], s[58:59] offset:256
	ds_bpermute_b32 v211, v203, v210
	v_permlane16_swap_b32_e32 v92, v88
	v_permlane16_swap_b32_e32 v93, v89
	v_permlane16_swap_b32_e32 v94, v90
	v_permlane16_swap_b32_e32 v95, v91
	v_permlane16_swap_b32_e32 v84, v80
	v_permlane16_swap_b32_e32 v85, v81
	v_permlane16_swap_b32_e32 v86, v82
	v_permlane16_swap_b32_e32 v87, v83
	v_permlane32_swap_b32_e32 v92, v88
	v_permlane32_swap_b32_e32 v93, v89
	v_permlane32_swap_b32_e32 v94, v90
	v_permlane32_swap_b32_e32 v95, v91
	v_permlane32_swap_b32_e32 v84, v80
	v_permlane32_swap_b32_e32 v85, v81
	v_permlane32_swap_b32_e32 v86, v82
	v_permlane32_swap_b32_e32 v87, v83
	s_nop 1
	v_mov_b32_dpp v232, v88 row_ror:8 row_mask:0xf bank_mask:0xf
	v_mov_b32_dpp v233, v89 row_ror:8 row_mask:0xf bank_mask:0xf
	v_mov_b32_dpp v234, v90 row_ror:8 row_mask:0xf bank_mask:0xf
	v_mov_b32_dpp v235, v91 row_ror:8 row_mask:0xf bank_mask:0xf
	v_mov_b32_dpp v240, v80 row_ror:8 row_mask:0xf bank_mask:0xf
	v_mov_b32_dpp v241, v81 row_ror:8 row_mask:0xf bank_mask:0xf
	v_mov_b32_dpp v242, v82 row_ror:8 row_mask:0xf bank_mask:0xf
	v_mov_b32_dpp v243, v83 row_ror:8 row_mask:0xf bank_mask:0xf
	s_mov_b32 vcc_lo, 0xff00ff
	s_mov_b32 vcc_hi, 0xff00ff
	v_mov_b32_e32 v205, 0xffff8040
	v_mov_b32_e32 v214, 0x8040
	v_cndmask_b32_e64 v205, v205, 0, vcc
	v_cndmask_b32_e64 v214, 0, v214, vcc
	v_add_u32_e32 v205, v205, v207
	v_add_u32_e32 v214, v214, v207
	s_mov_b32 exec_lo, 0xff00ff00
	s_mov_b32 exec_hi, 0xff00ff00
	v_swap_b32 v92, v232
	v_swap_b32 v93, v233
	v_swap_b32 v94, v234
	v_swap_b32 v95, v235
	v_swap_b32 v84, v240
	v_swap_b32 v85, v241
	v_swap_b32 v86, v242
	v_swap_b32 v87, v243
	s_mov_b64 exec, -1
	global_store_dwordx4 v205, v[92:95], s[92:93]
	global_store_dwordx4 v205, v[84:87], s[92:93] offset:512
	global_store_dwordx4 v214, v[232:235], s[92:93]
	global_store_dwordx4 v214, v[240:243], s[92:93] offset:512
	v_add_u32_e32 v207, 0x10000, v207
	v_add_u32_e32 v206, 0x50000, v206
	global_load_dwordx4 v[232:235], v206, s[82:83] offset:64
	global_load_dwordx4 v[240:243], v206, s[82:83] offset:576
	global_load_dwordx4 v[228:231], v206, s[82:83]
	global_load_dwordx4 v[236:239], v206, s[82:83] offset:512
	s_waitcnt lgkmcnt(0)
	v_add_f32_e32 v211, v210, v211
	ds_bpermute_b32 v212, v202, v211
	v_add_u32_e32 v208, 0x8000, v208
	s_waitcnt lgkmcnt(0)
	v_add_f32_e32 v211, v211, v212
	s_mov_b64 exec, 0xffff
	global_store_dword v209, v211, s[90:91]
	s_mov_b64 exec, -1
	v_add_u32_e32 v209, 0x400, v209
	s_waitcnt vmcnt(12)
; DI u32x4 pack8(const float* v) { u32x4 w; w.x = pk2(v[0], v[1]); w.y = pk2(v[2], v[3]); w.z = pk2(v[4], v[5]); w.w = pk2(v[6], v[7]); return w; }
; #define xor16_32(s) xor16_32_l((s), fr + 16 * fq)
;     DI void operator()(AccRef acc, const Unit& u, int wr, int wc, int fr, int fq) const {
;     ...
; #pragma unroll
;                 for (int bj = 0; bj < 2; ++bj) {
;                     const int c = u.pn * 256 + bj * 128 + cl;
;                     float v[8];
; #pragma unroll
;                     for (int n = 0; n < 2; ++n) {
;                         const f32x4 x = *(const f32x4*)(xi + c + 4 * n);
;                         const f32x4 y = x + gt[bj][n] * acc[ai][bj][m][n];
;                         *(f32x4*)(xout + (size_t)row * 1024 + c + 4 * n) = y;
; #pragma unroll
;                         for (int j = 0; j < 4; ++j) { s += y[j] * y[j]; v[4 * n + j] = ap ? y[j] * gs[bj][n][j] : 0.f; }
;                     }
;                     if (ap) *(u32x4*)(ap + (size_t)row * 1024 + c) = pack8(v);
;                 }
;                 s = xor16_32(s);
;                 if (fq == 0) ssq[(size_t)row * 16 + u.pn * 4 + wc] = s;
	v_permlane32_swap_b32_e32 v244, v248
	v_permlane32_swap_b32_e32 v245, v249
	v_permlane32_swap_b32_e32 v246, v250
	v_permlane32_swap_b32_e32 v247, v251
	v_permlane32_swap_b32_e32 v216, v220
	v_permlane32_swap_b32_e32 v217, v221
	v_permlane32_swap_b32_e32 v218, v222
	v_permlane32_swap_b32_e32 v219, v223
	v_permlane16_swap_b32_e32 v244, v248
	v_permlane16_swap_b32_e32 v245, v249
	v_permlane16_swap_b32_e32 v246, v250
	v_permlane16_swap_b32_e32 v247, v251
	v_permlane16_swap_b32_e32 v216, v220
	v_permlane16_swap_b32_e32 v217, v221
	v_permlane16_swap_b32_e32 v218, v222
	v_permlane16_swap_b32_e32 v219, v223
	v_pk_fma_f32 v[76:77], v[76:77], v[116:117], v[244:245]
	v_pk_fma_f32 v[78:79], v[78:79], v[118:119], v[246:247]
	v_mul_f32_e32 v210, v77, v77
	v_fmac_f32_e32 v210, v76, v76
	v_fmac_f32_e32 v210, v78, v78
	v_fmac_f32_e32 v210, v79, v79
	v_pk_mul_f32 v[244:245], v[164:165], v[76:77]
	v_pk_mul_f32 v[246:247], v[166:167], v[78:79]
	v_pk_fma_f32 v[72:73], v[72:73], v[108:109], v[248:249]
	v_pk_fma_f32 v[74:75], v[74:75], v[110:111], v[250:251]
	v_fmac_f32_e32 v210, v72, v72
	v_fmac_f32_e32 v210, v73, v73
	v_fmac_f32_e32 v210, v74, v74
	v_fmac_f32_e32 v210, v75, v75
	v_pk_mul_f32 v[248:249], v[162:163], v[72:73]
	v_pk_mul_f32 v[250:251], v[160:161], v[74:75]
	v_cvt_pk_bf16_f32 v244, v244, v245
	v_cvt_pk_bf16_f32 v245, v246, v247
	v_cvt_pk_bf16_f32 v246, v248, v249
	v_cvt_pk_bf16_f32 v247, v250, v251
	global_store_dwordx4 v208, v[244:247], s[58:59]
	v_pk_fma_f32 v[68:69], v[68:69], v[104:105], v[216:217]
	v_pk_fma_f32 v[70:71], v[70:71], v[106:107], v[218:219]
	v_fmac_f32_e32 v210, v68, v68
	v_fmac_f32_e32 v210, v69, v69
	v_fmac_f32_e32 v210, v70, v70
	v_fmac_f32_e32 v210, v71, v71
	v_pk_mul_f32 v[216:217], v[150:151], v[68:69]
	v_pk_mul_f32 v[218:219], v[148:149], v[70:71]
	v_pk_fma_f32 v[64:65], v[64:65], v[100:101], v[220:221]
	v_pk_fma_f32 v[66:67], v[66:67], v[102:103], v[222:223]
	v_fmac_f32_e32 v210, v64, v64
	v_fmac_f32_e32 v210, v65, v65
	v_fmac_f32_e32 v210, v66, v66
	v_fmac_f32_e32 v210, v67, v67
	v_pk_mul_f32 v[220:221], v[144:145], v[64:65]
	v_pk_mul_f32 v[222:223], v[146:147], v[66:67]
	v_cvt_pk_bf16_f32 v216, v216, v217
	v_cvt_pk_bf16_f32 v217, v218, v219
	v_cvt_pk_bf16_f32 v218, v220, v221
	v_cvt_pk_bf16_f32 v219, v222, v223
	global_store_dwordx4 v208, v[216:219], s[58:59] offset:256
	ds_bpermute_b32 v211, v203, v210
	v_permlane16_swap_b32_e32 v76, v72
	v_permlane16_swap_b32_e32 v77, v73
	v_permlane16_swap_b32_e32 v78, v74
	v_permlane16_swap_b32_e32 v79, v75
	v_permlane16_swap_b32_e32 v68, v64
	v_permlane16_swap_b32_e32 v69, v65
	v_permlane16_swap_b32_e32 v70, v66
	v_permlane16_swap_b32_e32 v71, v67
	v_permlane32_swap_b32_e32 v76, v72
	v_permlane32_swap_b32_e32 v77, v73
	v_permlane32_swap_b32_e32 v78, v74
	v_permlane32_swap_b32_e32 v79, v75
	v_permlane32_swap_b32_e32 v68, v64
	v_permlane32_swap_b32_e32 v69, v65
	v_permlane32_swap_b32_e32 v70, v66
	v_permlane32_swap_b32_e32 v71, v67
	s_nop 1
	v_mov_b32_dpp v248, v72 row_ror:8 row_mask:0xf bank_mask:0xf
	v_mov_b32_dpp v249, v73 row_ror:8 row_mask:0xf bank_mask:0xf
	v_mov_b32_dpp v250, v74 row_ror:8 row_mask:0xf bank_mask:0xf
	v_mov_b32_dpp v251, v75 row_ror:8 row_mask:0xf bank_mask:0xf
	v_mov_b32_dpp v220, v64 row_ror:8 row_mask:0xf bank_mask:0xf
	v_mov_b32_dpp v221, v65 row_ror:8 row_mask:0xf bank_mask:0xf
	v_mov_b32_dpp v222, v66 row_ror:8 row_mask:0xf bank_mask:0xf
	v_mov_b32_dpp v223, v67 row_ror:8 row_mask:0xf bank_mask:0xf
	s_mov_b32 vcc_lo, 0xff00ff
	s_mov_b32 vcc_hi, 0xff00ff
	v_mov_b32_e32 v205, 0xffff8040
	v_mov_b32_e32 v214, 0x8040
	v_cndmask_b32_e64 v205, v205, 0, vcc
	v_cndmask_b32_e64 v214, 0, v214, vcc
	v_add_u32_e32 v205, v205, v207
	v_add_u32_e32 v214, v214, v207
	s_mov_b32 exec_lo, 0xff00ff00
	s_mov_b32 exec_hi, 0xff00ff00
	v_swap_b32 v76, v248
	v_swap_b32 v77, v249
	v_swap_b32 v78, v250
	v_swap_b32 v79, v251
	v_swap_b32 v68, v220
	v_swap_b32 v69, v221
	v_swap_b32 v70, v222
	v_swap_b32 v71, v223
	s_mov_b64 exec, -1
	global_store_dwordx4 v205, v[76:79], s[92:93]
	global_store_dwordx4 v205, v[68:71], s[92:93] offset:512
	global_store_dwordx4 v214, v[248:251], s[92:93]
	global_store_dwordx4 v214, v[220:223], s[92:93] offset:512
	v_add_u32_e32 v207, 0x50000, v207
	v_add_u32_e32 v206, 0x10000, v206
	global_load_dwordx4 v[248:251], v206, s[82:83] offset:64
	global_load_dwordx4 v[220:223], v206, s[82:83] offset:576
	global_load_dwordx4 v[244:247], v206, s[82:83]
	global_load_dwordx4 v[216:219], v206, s[82:83] offset:512
	s_waitcnt lgkmcnt(0)
	v_add_f32_e32 v211, v210, v211
	ds_bpermute_b32 v212, v202, v211
	v_add_u32_e32 v208, 0x28000, v208
	s_waitcnt lgkmcnt(0)
	v_add_f32_e32 v211, v211, v212
	s_mov_b64 exec, 0xffff
	global_store_dword v209, v211, s[90:91]
	s_mov_b64 exec, -1
	v_add_u32_e32 v209, 0x1400, v209
	v_add_u32_e32 v224, 0xffffc080, v192
	v_add_u32_e32 v112, 0x80, v192
	s_waitcnt lgkmcnt(0)
;     DI void operator()(AccRef acc, const Unit& u, int wr, int wc, int fr, int fq) const {
;     ...
;         for (int ai = 0; ai < 2; ++ai) {
;             const int rb = u.pm * 256 + ai * 128 + wr * 64 + fr;
;             int mb, pos0, kv0; row_info(rb, mb, pos0, kv0);
;             f32x4 gt[2][2], gs[2][2];
; #pragma unroll
;             for (int bj = 0; bj < 2; ++bj)
; #pragma unroll
;                 for (int n = 0; n < 2; ++n) {
;                     const int c = u.pn * 256 + bj * 128 + cl + 4 * n;
;                     gt[bj][n] = *(const f32x4*)(gate + (size_t)mb * 6144 + c);
;                     if (ap) { const f32x4 g = *(const f32x4*)(gn + c), s = *(const f32x4*)(scn + (size_t)mb * 6144 + c); gs[bj][n] = g * (s + 1.f); }
;                 }
; #pragma unroll
;             for (int m = 0; m < 4; ++m) {
;                 const int row = rb + 16 * m;
;                 const float* xi = row < MP ? xin_p + (size_t)row * 1024 : xin_s + (size_t)(row - MP) * 1024;
;                 float s = 0.f;
; #pragma unroll
;                 for (int bj = 0; bj < 2; ++bj) {
;                     const int c = u.pn * 256 + bj * 128 + cl;
;                     float v[8];
; #pragma unroll
;                     for (int n = 0; n < 2; ++n) {
;                         const f32x4 x = *(const f32x4*)(xi + c + 4 * n);
;                         const f32x4 y = x + gt[bj][n] * acc[ai][bj][m][n];
	v_lshrrev_b32_e32 v65, 6, v224
	v_ashrrev_i32_e32 v64, 11, v112
	v_add_u32_e32 v65, 8, v65
	v_cmp_gt_i32_e64 s[0:1], s94, v112
	v_mov_b64_e32 v[66:67], s[56:57]
	s_nop 0
	v_cndmask_b32_e64 v68, v65, v64, s[0:1]
	v_mov_b64_e32 v[64:65], s[6:7]
	v_mad_i64_i32 v[64:65], s[0:1], v68, s75, v[64:65]
	v_mad_i64_i32 v[66:67], s[0:1], v68, s75, v[66:67]
	v_lshl_add_u64 v[68:69], v[64:65], 0, v[190:191]
	v_lshl_add_u64 v[104:105], v[66:67], 0, v[190:191]
	global_load_dwordx4 v[72:75], v[68:69], off offset:16
	global_load_dwordx4 v[76:79], v[68:69], off
	global_load_dwordx4 v[84:87], v[194:195], off offset:16
	global_load_dwordx4 v[100:103], v[194:195], off
	global_load_dwordx4 v[96:99], v[104:105], off offset:16
	global_load_dwordx4 v[108:111], v[104:105], off
	global_load_dwordx4 v[64:67], v[68:69], off offset:528
	s_nop 0
	global_load_dwordx4 v[68:71], v[68:69], off offset:512
	s_nop 0
	global_load_dwordx4 v[80:83], v[194:195], off offset:528
	global_load_dwordx4 v[92:95], v[194:195], off offset:512
	global_load_dwordx4 v[88:91], v[104:105], off offset:528
	s_nop 0
	global_load_dwordx4 v[104:107], v[104:105], off offset:512
	s_movk_i32 s0, 0x3fff
	v_cmp_lt_i32_e64 s[0:1], s0, v112
	s_and_saveexec_b64 s[12:13], s[0:1]
	s_xor_b64 s[0:1], exec, s[12:13]
	v_lshlrev_b64 v[114:115], 12, v[224:225]
	v_mov_b32_e32 v113, v225
	v_lshl_add_u64 v[116:117], s[20:21], 0, v[114:115]
	v_lshlrev_b64 v[114:115], 12, v[112:113]
	s_andn2_saveexec_b64 s[0:1], s[0:1]
	v_ashrrev_i32_e32 v113, 31, v112
	v_lshlrev_b64 v[114:115], 12, v[112:113]
	v_lshl_add_u64 v[116:117], s[42:43], 0, v[114:115]
	s_or_b64 exec, exec, s[0:1]
	s_waitcnt vmcnt(6)
	v_pk_add_f32 v[108:109], v[108:109], 1.0 op_sel_hi:[1,0]
	s_waitcnt vmcnt(1)
	v_pk_add_f32 v[90:91], v[90:91], 1.0 op_sel_hi:[1,0]
	v_pk_mul_f32 v[100:101], v[100:101], v[108:109]
	v_pk_add_f32 v[108:109], v[96:97], 1.0 op_sel_hi:[1,0]
	v_pk_add_f32 v[96:97], v[98:99], 1.0 op_sel_hi:[1,0]
	v_pk_mul_f32 v[98:99], v[84:85], v[108:109]
	v_pk_mul_f32 v[96:97], v[86:87], v[96:97]
	s_waitcnt vmcnt(0)
	v_pk_add_f32 v[84:85], v[106:107], 1.0 op_sel_hi:[1,0]
	v_pk_add_f32 v[86:87], v[104:105], 1.0 op_sel_hi:[1,0]
	v_pk_mul_f32 v[82:83], v[82:83], v[90:91]
	v_lshl_add_u64 v[90:91], v[116:117], 0, v[190:191]
	v_pk_mul_f32 v[84:85], v[94:95], v[84:85]
	v_pk_mul_f32 v[86:87], v[92:93], v[86:87]
	v_pk_add_f32 v[110:111], v[110:111], 1.0 op_sel_hi:[1,0]
	v_pk_add_f32 v[88:89], v[88:89], 1.0 op_sel_hi:[1,0]
	v_pk_mul_f32 v[102:103], v[102:103], v[110:111]
	v_pk_mul_f32 v[80:81], v[80:81], v[88:89]
	v_lshlrev_b64 v[88:89], 11, v[112:113]
	v_lshl_add_u64 v[88:89], s[58:59], 0, v[88:89]
	v_permlane32_swap_b32_e32 v228, v232
	v_permlane32_swap_b32_e32 v229, v233
	v_permlane32_swap_b32_e32 v230, v234
	v_permlane32_swap_b32_e32 v231, v235
	v_permlane32_swap_b32_e32 v236, v240
	v_permlane32_swap_b32_e32 v237, v241
	v_permlane32_swap_b32_e32 v238, v242
	v_permlane32_swap_b32_e32 v239, v243
	v_permlane16_swap_b32_e32 v228, v232
	v_permlane16_swap_b32_e32 v229, v233
	v_permlane16_swap_b32_e32 v230, v234
	v_permlane16_swap_b32_e32 v231, v235
	v_permlane16_swap_b32_e32 v236, v240
	v_permlane16_swap_b32_e32 v237, v241
	v_permlane16_swap_b32_e32 v238, v242
	v_permlane16_swap_b32_e32 v239, v243
	v_pk_fma_f32 v[60:61], v[60:61], v[76:77], v[228:229]
	v_pk_fma_f32 v[62:63], v[62:63], v[78:79], v[230:231]
	v_mul_f32_e32 v210, v61, v61
	v_fmac_f32_e32 v210, v60, v60
	v_fmac_f32_e32 v210, v62, v62
	v_fmac_f32_e32 v210, v63, v63
	v_pk_mul_f32 v[228:229], v[100:101], v[60:61]
	v_pk_mul_f32 v[230:231], v[102:103], v[62:63]
	v_pk_fma_f32 v[56:57], v[56:57], v[72:73], v[232:233]
	v_pk_fma_f32 v[58:59], v[58:59], v[74:75], v[234:235]
	v_fmac_f32_e32 v210, v56, v56
	v_fmac_f32_e32 v210, v57, v57
	v_fmac_f32_e32 v210, v58, v58
	v_fmac_f32_e32 v210, v59, v59
	v_pk_mul_f32 v[232:233], v[98:99], v[56:57]
	v_pk_mul_f32 v[234:235], v[96:97], v[58:59]
	v_cvt_pk_bf16_f32 v228, v228, v229
	v_cvt_pk_bf16_f32 v229, v230, v231
	v_cvt_pk_bf16_f32 v230, v232, v233
	v_cvt_pk_bf16_f32 v231, v234, v235
	global_store_dwordx4 v208, v[228:231], s[58:59]
	v_pk_fma_f32 v[52:53], v[52:53], v[68:69], v[236:237]
	v_pk_fma_f32 v[54:55], v[54:55], v[70:71], v[238:239]
	v_fmac_f32_e32 v210, v52, v52
	v_fmac_f32_e32 v210, v53, v53
	v_fmac_f32_e32 v210, v54, v54
	v_fmac_f32_e32 v210, v55, v55
	v_pk_mul_f32 v[236:237], v[86:87], v[52:53]
	v_pk_mul_f32 v[238:239], v[84:85], v[54:55]
	v_pk_fma_f32 v[48:49], v[48:49], v[64:65], v[240:241]
	v_pk_fma_f32 v[50:51], v[50:51], v[66:67], v[242:243]
	v_fmac_f32_e32 v210, v48, v48
	v_fmac_f32_e32 v210, v49, v49
	v_fmac_f32_e32 v210, v50, v50
	v_fmac_f32_e32 v210, v51, v51
	v_pk_mul_f32 v[240:241], v[80:81], v[48:49]
	v_pk_mul_f32 v[242:243], v[82:83], v[50:51]
	v_cvt_pk_bf16_f32 v236, v236, v237
	v_cvt_pk_bf16_f32 v237, v238, v239
	v_cvt_pk_bf16_f32 v238, v240, v241
	v_cvt_pk_bf16_f32 v239, v242, v243
	global_store_dwordx4 v208, v[236:239], s[58:59] offset:256
	ds_bpermute_b32 v211, v203, v210
	v_permlane16_swap_b32_e32 v60, v56
	v_permlane16_swap_b32_e32 v61, v57
	v_permlane16_swap_b32_e32 v62, v58
	v_permlane16_swap_b32_e32 v63, v59
	v_permlane16_swap_b32_e32 v52, v48
	v_permlane16_swap_b32_e32 v53, v49
	v_permlane16_swap_b32_e32 v54, v50
	v_permlane16_swap_b32_e32 v55, v51
	v_permlane32_swap_b32_e32 v60, v56
	v_permlane32_swap_b32_e32 v61, v57
	v_permlane32_swap_b32_e32 v62, v58
	v_permlane32_swap_b32_e32 v63, v59
	v_permlane32_swap_b32_e32 v52, v48
	v_permlane32_swap_b32_e32 v53, v49
	v_permlane32_swap_b32_e32 v54, v50
	v_permlane32_swap_b32_e32 v55, v51
	s_nop 1
	v_mov_b32_dpp v232, v56 row_ror:8 row_mask:0xf bank_mask:0xf
; DI u32x4 pack8(const float* v) { u32x4 w; w.x = pk2(v[0], v[1]); w.y = pk2(v[2], v[3]); w.z = pk2(v[4], v[5]); w.w = pk2(v[6], v[7]); return w; }
; #define xor16_32(s) xor16_32_l((s), fr + 16 * fq)
;     DI void operator()(AccRef acc, const Unit& u, int wr, int wc, int fr, int fq) const {
;     ...
; #pragma unroll
;                 for (int bj = 0; bj < 2; ++bj) {
;                     const int c = u.pn * 256 + bj * 128 + cl;
;                     float v[8];
; #pragma unroll
;                     for (int n = 0; n < 2; ++n) {
;                         const f32x4 x = *(const f32x4*)(xi + c + 4 * n);
;                         const f32x4 y = x + gt[bj][n] * acc[ai][bj][m][n];
;                         *(f32x4*)(xout + (size_t)row * 1024 + c + 4 * n) = y;
; #pragma unroll
;                         for (int j = 0; j < 4; ++j) { s += y[j] * y[j]; v[4 * n + j] = ap ? y[j] * gs[bj][n][j] : 0.f; }
;                     }
;                     if (ap) *(u32x4*)(ap + (size_t)row * 1024 + c) = pack8(v);
;                 }
;                 s = xor16_32(s);
;                 if (fq == 0) ssq[(size_t)row * 16 + u.pn * 4 + wc] = s;
	v_mov_b32_dpp v233, v57 row_ror:8 row_mask:0xf bank_mask:0xf
	v_mov_b32_dpp v234, v58 row_ror:8 row_mask:0xf bank_mask:0xf
	v_mov_b32_dpp v235, v59 row_ror:8 row_mask:0xf bank_mask:0xf
	v_mov_b32_dpp v240, v48 row_ror:8 row_mask:0xf bank_mask:0xf
	v_mov_b32_dpp v241, v49 row_ror:8 row_mask:0xf bank_mask:0xf
	v_mov_b32_dpp v242, v50 row_ror:8 row_mask:0xf bank_mask:0xf
	v_mov_b32_dpp v243, v51 row_ror:8 row_mask:0xf bank_mask:0xf
	s_mov_b32 vcc_lo, 0xff00ff
	s_mov_b32 vcc_hi, 0xff00ff
	v_mov_b32_e32 v205, 0xffff8040
	v_mov_b32_e32 v214, 0x8040
	v_cndmask_b32_e64 v205, v205, 0, vcc
	v_cndmask_b32_e64 v214, 0, v214, vcc
	v_add_u32_e32 v205, v205, v207
	v_add_u32_e32 v214, v214, v207
	s_mov_b32 exec_lo, 0xff00ff00
	s_mov_b32 exec_hi, 0xff00ff00
	v_swap_b32 v60, v232
	v_swap_b32 v61, v233
	v_swap_b32 v62, v234
	v_swap_b32 v63, v235
	v_swap_b32 v52, v240
	v_swap_b32 v53, v241
	v_swap_b32 v54, v242
	v_swap_b32 v55, v243
	s_mov_b64 exec, -1
	global_store_dwordx4 v205, v[60:63], s[92:93]
	global_store_dwordx4 v205, v[52:55], s[92:93] offset:512
	global_store_dwordx4 v214, v[232:235], s[92:93]
	global_store_dwordx4 v214, v[240:243], s[92:93] offset:512
	v_add_u32_e32 v207, 0x10000, v207
	v_add_u32_e32 v206, 0x10000, v206
	global_load_dwordx4 v[232:235], v206, s[82:83] offset:64
	global_load_dwordx4 v[240:243], v206, s[82:83] offset:576
	global_load_dwordx4 v[228:231], v206, s[82:83]
	global_load_dwordx4 v[236:239], v206, s[82:83] offset:512
	s_waitcnt lgkmcnt(0)
	v_add_f32_e32 v211, v210, v211
	ds_bpermute_b32 v212, v202, v211
	v_add_u32_e32 v208, 0x8000, v208
	s_waitcnt lgkmcnt(0)
	v_add_f32_e32 v211, v211, v212
	s_mov_b64 exec, 0xffff
	global_store_dword v209, v211, s[90:91]
	s_mov_b64 exec, -1
	v_add_u32_e32 v209, 0x400, v209
	v_permlane32_swap_b32_e32 v244, v248
	v_permlane32_swap_b32_e32 v245, v249
	v_permlane32_swap_b32_e32 v246, v250
	v_permlane32_swap_b32_e32 v247, v251
	v_permlane32_swap_b32_e32 v216, v220
	v_permlane32_swap_b32_e32 v217, v221
	v_permlane32_swap_b32_e32 v218, v222
	v_permlane32_swap_b32_e32 v219, v223
	v_permlane16_swap_b32_e32 v244, v248
	v_permlane16_swap_b32_e32 v245, v249
	v_permlane16_swap_b32_e32 v246, v250
	v_permlane16_swap_b32_e32 v247, v251
	v_permlane16_swap_b32_e32 v216, v220
	v_permlane16_swap_b32_e32 v217, v221
	v_permlane16_swap_b32_e32 v218, v222
	v_permlane16_swap_b32_e32 v219, v223
	v_pk_fma_f32 v[44:45], v[44:45], v[76:77], v[244:245]
	v_pk_fma_f32 v[46:47], v[46:47], v[78:79], v[246:247]
	v_mul_f32_e32 v210, v45, v45
	v_fmac_f32_e32 v210, v44, v44
	v_fmac_f32_e32 v210, v46, v46
	v_fmac_f32_e32 v210, v47, v47
	v_pk_mul_f32 v[244:245], v[100:101], v[44:45]
	v_pk_mul_f32 v[246:247], v[102:103], v[46:47]
	v_pk_fma_f32 v[40:41], v[40:41], v[72:73], v[248:249]
	v_pk_fma_f32 v[42:43], v[42:43], v[74:75], v[250:251]
	v_fmac_f32_e32 v210, v40, v40
	v_fmac_f32_e32 v210, v41, v41
	v_fmac_f32_e32 v210, v42, v42
	v_fmac_f32_e32 v210, v43, v43
	v_pk_mul_f32 v[248:249], v[98:99], v[40:41]
	v_pk_mul_f32 v[250:251], v[96:97], v[42:43]
	v_cvt_pk_bf16_f32 v244, v244, v245
	v_cvt_pk_bf16_f32 v245, v246, v247
	v_cvt_pk_bf16_f32 v246, v248, v249
	v_cvt_pk_bf16_f32 v247, v250, v251
	global_store_dwordx4 v208, v[244:247], s[58:59]
	v_pk_fma_f32 v[36:37], v[36:37], v[68:69], v[216:217]
	v_pk_fma_f32 v[38:39], v[38:39], v[70:71], v[218:219]
	v_fmac_f32_e32 v210, v36, v36
	v_fmac_f32_e32 v210, v37, v37
	v_fmac_f32_e32 v210, v38, v38
	v_fmac_f32_e32 v210, v39, v39
	v_pk_mul_f32 v[216:217], v[86:87], v[36:37]
	v_pk_mul_f32 v[218:219], v[84:85], v[38:39]
	v_pk_fma_f32 v[32:33], v[32:33], v[64:65], v[220:221]
	v_pk_fma_f32 v[34:35], v[34:35], v[66:67], v[222:223]
	v_fmac_f32_e32 v210, v32, v32
	v_fmac_f32_e32 v210, v33, v33
	v_fmac_f32_e32 v210, v34, v34
	v_fmac_f32_e32 v210, v35, v35
	v_pk_mul_f32 v[220:221], v[80:81], v[32:33]
	v_pk_mul_f32 v[222:223], v[82:83], v[34:35]
	v_cvt_pk_bf16_f32 v216, v216, v217
	v_cvt_pk_bf16_f32 v217, v218, v219
	v_cvt_pk_bf16_f32 v218, v220, v221
	v_cvt_pk_bf16_f32 v219, v222, v223
	global_store_dwordx4 v208, v[216:219], s[58:59] offset:256
	ds_bpermute_b32 v211, v203, v210
	v_permlane16_swap_b32_e32 v44, v40
	v_permlane16_swap_b32_e32 v45, v41
	v_permlane16_swap_b32_e32 v46, v42
	v_permlane16_swap_b32_e32 v47, v43
	v_permlane16_swap_b32_e32 v36, v32
	v_permlane16_swap_b32_e32 v37, v33
	v_permlane16_swap_b32_e32 v38, v34
	v_permlane16_swap_b32_e32 v39, v35
	v_permlane32_swap_b32_e32 v44, v40
	v_permlane32_swap_b32_e32 v45, v41
	v_permlane32_swap_b32_e32 v46, v42
	v_permlane32_swap_b32_e32 v47, v43
	v_permlane32_swap_b32_e32 v36, v32
	v_permlane32_swap_b32_e32 v37, v33
	v_permlane32_swap_b32_e32 v38, v34
	v_permlane32_swap_b32_e32 v39, v35
	s_nop 1
	v_mov_b32_dpp v248, v40 row_ror:8 row_mask:0xf bank_mask:0xf
	v_mov_b32_dpp v249, v41 row_ror:8 row_mask:0xf bank_mask:0xf
	v_mov_b32_dpp v250, v42 row_ror:8 row_mask:0xf bank_mask:0xf
	v_mov_b32_dpp v251, v43 row_ror:8 row_mask:0xf bank_mask:0xf
	v_mov_b32_dpp v220, v32 row_ror:8 row_mask:0xf bank_mask:0xf
	v_mov_b32_dpp v221, v33 row_ror:8 row_mask:0xf bank_mask:0xf
	v_mov_b32_dpp v222, v34 row_ror:8 row_mask:0xf bank_mask:0xf
	v_mov_b32_dpp v223, v35 row_ror:8 row_mask:0xf bank_mask:0xf
	s_mov_b32 vcc_lo, 0xff00ff
	s_mov_b32 vcc_hi, 0xff00ff
	v_mov_b32_e32 v205, 0xffff8040
	v_mov_b32_e32 v214, 0x8040
	v_cndmask_b32_e64 v205, v205, 0, vcc
	v_cndmask_b32_e64 v214, 0, v214, vcc
	v_add_u32_e32 v205, v205, v207
	v_add_u32_e32 v214, v214, v207
	s_mov_b32 exec_lo, 0xff00ff00
	s_mov_b32 exec_hi, 0xff00ff00
	v_swap_b32 v44, v248
	v_swap_b32 v45, v249
	v_swap_b32 v46, v250
	v_swap_b32 v47, v251
	v_swap_b32 v36, v220
	v_swap_b32 v37, v221
	v_swap_b32 v38, v222
	v_swap_b32 v39, v223
	s_mov_b64 exec, -1
	global_store_dwordx4 v205, v[44:47], s[92:93]
	global_store_dwordx4 v205, v[36:39], s[92:93] offset:512
	global_store_dwordx4 v214, v[248:251], s[92:93]
	global_store_dwordx4 v214, v[220:223], s[92:93] offset:512
	v_add_u32_e32 v207, 0x10000, v207
	v_add_u32_e32 v206, 0x10000, v206
	global_load_dwordx4 v[248:251], v206, s[82:83] offset:64
	global_load_dwordx4 v[220:223], v206, s[82:83] offset:576
	global_load_dwordx4 v[244:247], v206, s[82:83]
	global_load_dwordx4 v[216:219], v206, s[82:83] offset:512
	s_waitcnt lgkmcnt(0)
; DI u32x4 pack8(const float* v) { u32x4 w; w.x = pk2(v[0], v[1]); w.y = pk2(v[2], v[3]); w.z = pk2(v[4], v[5]); w.w = pk2(v[6], v[7]); return w; }
; #define xor16_32(s) xor16_32_l((s), fr + 16 * fq)
;     DI void operator()(AccRef acc, const Unit& u, int wr, int wc, int fr, int fq) const {
;     ...
;                 float s = 0.f;
; #pragma unroll
;                 for (int bj = 0; bj < 2; ++bj) {
;                     const int c = u.pn * 256 + bj * 128 + cl;
;                     float v[8];
; #pragma unroll
;                     for (int n = 0; n < 2; ++n) {
;                         const f32x4 x = *(const f32x4*)(xi + c + 4 * n);
;                         const f32x4 y = x + gt[bj][n] * acc[ai][bj][m][n];
;                         *(f32x4*)(xout + (size_t)row * 1024 + c + 4 * n) = y;
; #pragma unroll
;                         for (int j = 0; j < 4; ++j) { s += y[j] * y[j]; v[4 * n + j] = ap ? y[j] * gs[bj][n][j] : 0.f; }
;                     }
;                     if (ap) *(u32x4*)(ap + (size_t)row * 1024 + c) = pack8(v);
;                 }
;                 s = xor16_32(s);
;                 if (fq == 0) ssq[(size_t)row * 16 + u.pn * 4 + wc] = s;
	v_add_f32_e32 v211, v210, v211
	ds_bpermute_b32 v212, v202, v211
	v_add_u32_e32 v208, 0x8000, v208
	s_waitcnt lgkmcnt(0)
	v_add_f32_e32 v211, v211, v212
	s_mov_b64 exec, 0xffff
	global_store_dword v209, v211, s[90:91]
	s_mov_b64 exec, -1
	v_add_u32_e32 v209, 0x400, v209
	s_waitcnt vmcnt(12)
	v_permlane32_swap_b32_e32 v228, v232
	v_permlane32_swap_b32_e32 v229, v233
	v_permlane32_swap_b32_e32 v230, v234
	v_permlane32_swap_b32_e32 v231, v235
	v_permlane32_swap_b32_e32 v236, v240
	v_permlane32_swap_b32_e32 v237, v241
	v_permlane32_swap_b32_e32 v238, v242
	v_permlane32_swap_b32_e32 v239, v243
	v_permlane16_swap_b32_e32 v228, v232
	v_permlane16_swap_b32_e32 v229, v233
	v_permlane16_swap_b32_e32 v230, v234
	v_permlane16_swap_b32_e32 v231, v235
	v_permlane16_swap_b32_e32 v236, v240
	v_permlane16_swap_b32_e32 v237, v241
	v_permlane16_swap_b32_e32 v238, v242
	v_permlane16_swap_b32_e32 v239, v243
	v_pk_fma_f32 v[28:29], v[28:29], v[76:77], v[228:229]
	v_pk_fma_f32 v[30:31], v[30:31], v[78:79], v[230:231]
	v_mul_f32_e32 v210, v29, v29
	v_fmac_f32_e32 v210, v28, v28
	v_fmac_f32_e32 v210, v30, v30
	v_fmac_f32_e32 v210, v31, v31
	v_pk_mul_f32 v[228:229], v[100:101], v[28:29]
	v_pk_mul_f32 v[230:231], v[102:103], v[30:31]
	v_pk_fma_f32 v[24:25], v[24:25], v[72:73], v[232:233]
	v_pk_fma_f32 v[26:27], v[26:27], v[74:75], v[234:235]
	v_fmac_f32_e32 v210, v24, v24
	v_fmac_f32_e32 v210, v25, v25
	v_fmac_f32_e32 v210, v26, v26
	v_fmac_f32_e32 v210, v27, v27
	v_pk_mul_f32 v[232:233], v[98:99], v[24:25]
	v_pk_mul_f32 v[234:235], v[96:97], v[26:27]
	v_cvt_pk_bf16_f32 v228, v228, v229
	v_cvt_pk_bf16_f32 v229, v230, v231
	v_cvt_pk_bf16_f32 v230, v232, v233
	v_cvt_pk_bf16_f32 v231, v234, v235
	global_store_dwordx4 v208, v[228:231], s[58:59]
	v_pk_fma_f32 v[20:21], v[20:21], v[68:69], v[236:237]
	v_pk_fma_f32 v[22:23], v[22:23], v[70:71], v[238:239]
	v_fmac_f32_e32 v210, v20, v20
	v_fmac_f32_e32 v210, v21, v21
	v_fmac_f32_e32 v210, v22, v22
	v_fmac_f32_e32 v210, v23, v23
	v_pk_mul_f32 v[236:237], v[86:87], v[20:21]
	v_pk_mul_f32 v[238:239], v[84:85], v[22:23]
	v_pk_fma_f32 v[16:17], v[16:17], v[64:65], v[240:241]
	v_pk_fma_f32 v[18:19], v[18:19], v[66:67], v[242:243]
	v_fmac_f32_e32 v210, v16, v16
	v_fmac_f32_e32 v210, v17, v17
	v_fmac_f32_e32 v210, v18, v18
	v_fmac_f32_e32 v210, v19, v19
	v_pk_mul_f32 v[240:241], v[80:81], v[16:17]
	v_pk_mul_f32 v[242:243], v[82:83], v[18:19]
	v_cvt_pk_bf16_f32 v236, v236, v237
	v_cvt_pk_bf16_f32 v237, v238, v239
	v_cvt_pk_bf16_f32 v238, v240, v241
	v_cvt_pk_bf16_f32 v239, v242, v243
	global_store_dwordx4 v208, v[236:239], s[58:59] offset:256
	ds_bpermute_b32 v211, v203, v210
	v_permlane16_swap_b32_e32 v28, v24
	v_permlane16_swap_b32_e32 v29, v25
	v_permlane16_swap_b32_e32 v30, v26
	v_permlane16_swap_b32_e32 v31, v27
	v_permlane16_swap_b32_e32 v20, v16
	v_permlane16_swap_b32_e32 v21, v17
	v_permlane16_swap_b32_e32 v22, v18
	v_permlane16_swap_b32_e32 v23, v19
	v_permlane32_swap_b32_e32 v28, v24
	v_permlane32_swap_b32_e32 v29, v25
	v_permlane32_swap_b32_e32 v30, v26
	v_permlane32_swap_b32_e32 v31, v27
	v_permlane32_swap_b32_e32 v20, v16
	v_permlane32_swap_b32_e32 v21, v17
	v_permlane32_swap_b32_e32 v22, v18
	v_permlane32_swap_b32_e32 v23, v19
	s_nop 1
	v_mov_b32_dpp v232, v24 row_ror:8 row_mask:0xf bank_mask:0xf
	v_mov_b32_dpp v233, v25 row_ror:8 row_mask:0xf bank_mask:0xf
	v_mov_b32_dpp v234, v26 row_ror:8 row_mask:0xf bank_mask:0xf
	v_mov_b32_dpp v235, v27 row_ror:8 row_mask:0xf bank_mask:0xf
	v_mov_b32_dpp v240, v16 row_ror:8 row_mask:0xf bank_mask:0xf
	v_mov_b32_dpp v241, v17 row_ror:8 row_mask:0xf bank_mask:0xf
	v_mov_b32_dpp v242, v18 row_ror:8 row_mask:0xf bank_mask:0xf
	v_mov_b32_dpp v243, v19 row_ror:8 row_mask:0xf bank_mask:0xf
	s_mov_b32 vcc_lo, 0xff00ff
	s_mov_b32 vcc_hi, 0xff00ff
	v_mov_b32_e32 v205, 0xffff8040
	v_mov_b32_e32 v214, 0x8040
	v_cndmask_b32_e64 v205, v205, 0, vcc
	v_cndmask_b32_e64 v214, 0, v214, vcc
	v_add_u32_e32 v205, v205, v207
	v_add_u32_e32 v214, v214, v207
	s_mov_b32 exec_lo, 0xff00ff00
	s_mov_b32 exec_hi, 0xff00ff00
	v_swap_b32 v28, v232
	v_swap_b32 v29, v233
	v_swap_b32 v30, v234
	v_swap_b32 v31, v235
	v_swap_b32 v20, v240
	v_swap_b32 v21, v241
	v_swap_b32 v22, v242
	v_swap_b32 v23, v243
	s_mov_b64 exec, -1
	global_store_dwordx4 v205, v[28:31], s[92:93]
	global_store_dwordx4 v205, v[20:23], s[92:93] offset:512
	global_store_dwordx4 v214, v[232:235], s[92:93]
	global_store_dwordx4 v214, v[240:243], s[92:93] offset:512
	v_add_u32_e32 v207, 0x10000, v207
	s_waitcnt lgkmcnt(0)
	v_add_f32_e32 v211, v210, v211
	ds_bpermute_b32 v212, v202, v211
	v_add_u32_e32 v208, 0x8000, v208
	s_waitcnt lgkmcnt(0)
; DI u32x4 pack8(const float* v) { u32x4 w; w.x = pk2(v[0], v[1]); w.y = pk2(v[2], v[3]); w.z = pk2(v[4], v[5]); w.w = pk2(v[6], v[7]); return w; }
; #define xor16_32(s) xor16_32_l((s), fr + 16 * fq)
; #define PG8_BAR __builtin_amdgcn_s_barrier()
; template <class Epi, bool ALIGN_EPI, bool SP2>
; DI void gemm_phase(int g_wave, LAS unsigned char* lds, const Gemm g, const StaticOrder& S, const Epi& E) {
;     ...
;         if (!has_next) break;
; #pragma unroll
;         for (int a = 0; a < 2; ++a)
; #pragma unroll
;             for (int b = 0; b < 2; ++b)
; #pragma unroll
;                 for (int m = 0; m < 4; ++m)
; #pragma unroll
;                     for (int n = 0; n < 2; ++n) acc[a][b][m][n] = (f32x4){0.f, 0.f, 0.f, 0.f};
;         cur = nxt; cA = nA; cB = nB; ++ui;
;         if constexpr (ALIGN_EPI) { if (wr == 1) PG8_BAR; }
;     DI void operator()(AccRef acc, const Unit& u, int wr, int wc, int fr, int fq) const {
;     ...
;                 float s = 0.f;
; #pragma unroll
;                 for (int bj = 0; bj < 2; ++bj) {
;                     const int c = u.pn * 256 + bj * 128 + cl;
;                     float v[8];
; #pragma unroll
;                     for (int n = 0; n < 2; ++n) {
;                         const f32x4 x = *(const f32x4*)(xi + c + 4 * n);
;                         const f32x4 y = x + gt[bj][n] * acc[ai][bj][m][n];
;                         *(f32x4*)(xout + (size_t)row * 1024 + c + 4 * n) = y;
; #pragma unroll
;                         for (int j = 0; j < 4; ++j) { s += y[j] * y[j]; v[4 * n + j] = ap ? y[j] * gs[bj][n][j] : 0.f; }
;                     }
;                     if (ap) *(u32x4*)(ap + (size_t)row * 1024 + c) = pack8(v);
;                 }
;                 s = xor16_32(s);
;                 if (fq == 0) ssq[(size_t)row * 16 + u.pn * 4 + wc] = s;
	v_add_f32_e32 v211, v211, v212
	s_mov_b64 exec, 0xffff
	global_store_dword v209, v211, s[90:91]
	s_mov_b64 exec, -1
	v_add_u32_e32 v209, 0x400, v209
	s_waitcnt vmcnt(8)
	v_permlane32_swap_b32_e32 v244, v248
	v_permlane32_swap_b32_e32 v245, v249
	v_permlane32_swap_b32_e32 v246, v250
	v_permlane32_swap_b32_e32 v247, v251
	v_permlane32_swap_b32_e32 v216, v220
	v_permlane32_swap_b32_e32 v217, v221
	v_permlane32_swap_b32_e32 v218, v222
	v_permlane32_swap_b32_e32 v219, v223
	v_permlane16_swap_b32_e32 v244, v248
	v_permlane16_swap_b32_e32 v245, v249
	v_permlane16_swap_b32_e32 v246, v250
	v_permlane16_swap_b32_e32 v247, v251
	v_permlane16_swap_b32_e32 v216, v220
	v_permlane16_swap_b32_e32 v217, v221
	v_permlane16_swap_b32_e32 v218, v222
	v_permlane16_swap_b32_e32 v219, v223
	v_pk_fma_f32 v[12:13], v[12:13], v[76:77], v[244:245]
	v_pk_fma_f32 v[14:15], v[14:15], v[78:79], v[246:247]
	v_mul_f32_e32 v210, v13, v13
	v_fmac_f32_e32 v210, v12, v12
	v_fmac_f32_e32 v210, v14, v14
	v_fmac_f32_e32 v210, v15, v15
	v_pk_mul_f32 v[244:245], v[100:101], v[12:13]
	v_pk_mul_f32 v[246:247], v[102:103], v[14:15]
	v_pk_fma_f32 v[8:9], v[8:9], v[72:73], v[248:249]
	v_pk_fma_f32 v[10:11], v[10:11], v[74:75], v[250:251]
	v_fmac_f32_e32 v210, v8, v8
	v_fmac_f32_e32 v210, v9, v9
	v_fmac_f32_e32 v210, v10, v10
	v_fmac_f32_e32 v210, v11, v11
	v_pk_mul_f32 v[248:249], v[98:99], v[8:9]
	v_pk_mul_f32 v[250:251], v[96:97], v[10:11]
	v_cvt_pk_bf16_f32 v244, v244, v245
	v_cvt_pk_bf16_f32 v245, v246, v247
	v_cvt_pk_bf16_f32 v246, v248, v249
	v_cvt_pk_bf16_f32 v247, v250, v251
	global_store_dwordx4 v208, v[244:247], s[58:59]
	v_pk_fma_f32 v[4:5], v[4:5], v[68:69], v[216:217]
	v_pk_fma_f32 v[6:7], v[6:7], v[70:71], v[218:219]
	v_fmac_f32_e32 v210, v4, v4
	v_fmac_f32_e32 v210, v5, v5
	v_fmac_f32_e32 v210, v6, v6
	v_fmac_f32_e32 v210, v7, v7
	v_pk_mul_f32 v[216:217], v[86:87], v[4:5]
	v_pk_mul_f32 v[218:219], v[84:85], v[6:7]
	v_pk_fma_f32 v[0:1], v[0:1], v[64:65], v[220:221]
	v_pk_fma_f32 v[2:3], v[2:3], v[66:67], v[222:223]
	v_fmac_f32_e32 v210, v0, v0
	v_fmac_f32_e32 v210, v1, v1
	v_fmac_f32_e32 v210, v2, v2
	v_fmac_f32_e32 v210, v3, v3
	v_pk_mul_f32 v[220:221], v[80:81], v[0:1]
	v_pk_mul_f32 v[222:223], v[82:83], v[2:3]
	v_cvt_pk_bf16_f32 v216, v216, v217
	v_cvt_pk_bf16_f32 v217, v218, v219
	v_cvt_pk_bf16_f32 v218, v220, v221
	v_cvt_pk_bf16_f32 v219, v222, v223
	global_store_dwordx4 v208, v[216:219], s[58:59] offset:256
	ds_bpermute_b32 v211, v203, v210
	v_permlane16_swap_b32_e32 v12, v8
	v_permlane16_swap_b32_e32 v13, v9
	v_permlane16_swap_b32_e32 v14, v10
	v_permlane16_swap_b32_e32 v15, v11
	v_permlane16_swap_b32_e32 v4, v0
	v_permlane16_swap_b32_e32 v5, v1
	v_permlane16_swap_b32_e32 v6, v2
	v_permlane16_swap_b32_e32 v7, v3
	v_permlane32_swap_b32_e32 v12, v8
	v_permlane32_swap_b32_e32 v13, v9
	v_permlane32_swap_b32_e32 v14, v10
	v_permlane32_swap_b32_e32 v15, v11
	v_permlane32_swap_b32_e32 v4, v0
	v_permlane32_swap_b32_e32 v5, v1
	v_permlane32_swap_b32_e32 v6, v2
	v_permlane32_swap_b32_e32 v7, v3
	s_nop 1
	v_mov_b32_dpp v248, v8 row_ror:8 row_mask:0xf bank_mask:0xf
	v_mov_b32_dpp v249, v9 row_ror:8 row_mask:0xf bank_mask:0xf
	v_mov_b32_dpp v250, v10 row_ror:8 row_mask:0xf bank_mask:0xf
	v_mov_b32_dpp v251, v11 row_ror:8 row_mask:0xf bank_mask:0xf
	v_mov_b32_dpp v220, v0 row_ror:8 row_mask:0xf bank_mask:0xf
	v_mov_b32_dpp v221, v1 row_ror:8 row_mask:0xf bank_mask:0xf
	v_mov_b32_dpp v222, v2 row_ror:8 row_mask:0xf bank_mask:0xf
	v_mov_b32_dpp v223, v3 row_ror:8 row_mask:0xf bank_mask:0xf
	s_mov_b32 vcc_lo, 0xff00ff
	s_mov_b32 vcc_hi, 0xff00ff
	v_mov_b32_e32 v205, 0xffff8040
	v_mov_b32_e32 v214, 0x8040
	v_cndmask_b32_e64 v205, v205, 0, vcc
	v_cndmask_b32_e64 v214, 0, v214, vcc
	v_add_u32_e32 v205, v205, v207
	v_add_u32_e32 v214, v214, v207
	s_mov_b32 exec_lo, 0xff00ff00
	s_mov_b32 exec_hi, 0xff00ff00
	v_swap_b32 v12, v248
	v_swap_b32 v13, v249
	v_swap_b32 v14, v250
	v_swap_b32 v15, v251
	v_swap_b32 v4, v220
	v_swap_b32 v5, v221
	v_swap_b32 v6, v222
	v_swap_b32 v7, v223
	s_mov_b64 exec, -1
	global_store_dwordx4 v205, v[12:15], s[92:93]
	global_store_dwordx4 v205, v[4:7], s[92:93] offset:512
	global_store_dwordx4 v214, v[248:251], s[92:93]
	global_store_dwordx4 v214, v[220:223], s[92:93] offset:512
	s_waitcnt lgkmcnt(0)
	v_add_f32_e32 v211, v210, v211
	ds_bpermute_b32 v212, v202, v211
	s_waitcnt lgkmcnt(0)
	v_add_f32_e32 v211, v211, v212
	s_mov_b64 exec, 0xffff
	global_store_dword v209, v211, s[90:91]
	s_mov_b64 exec, -1
	s_andn2_b64 vcc, exec, s[8:9]
	s_mov_b64 s[0:1], -1
	s_cbranch_vccnz .LBB0_1292
	s_andn2_b64 vcc, exec, s[2:3]
	s_cbranch_vccnz .LBB0_1291
	s_barrier
	s_branch .LBB0_1291

; DI u32x4 pack8(const float* v) { u32x4 w; w.x = pk2(v[0], v[1]); w.y = pk2(v[2], v[3]); w.z = pk2(v[4], v[5]); w.w = pk2(v[6], v[7]); return w; }
; #define xor16_32(s) xor16_32_l((s), fr + 16 * fq)
;     DI void operator()(AccRef acc, const Unit& u, int wr, int wc, int fr, int fq) const {
;     ...
;                 float s = 0.f;
; #pragma unroll
;                 for (int bj = 0; bj < 2; ++bj) {
;                     const int c = u.pn * 256 + bj * 128 + cl;
;                     float v[8];
; #pragma unroll
;                     for (int n = 0; n < 2; ++n) {
;                         const f32x4 x = *(const f32x4*)(xi + c + 4 * n);
;                         const f32x4 y = x + gt[bj][n] * acc[ai][bj][m][n];
;                         *(f32x4*)(xout + (size_t)row * 1024 + c + 4 * n) = y;
; #pragma unroll
;                         for (int j = 0; j < 4; ++j) { s += y[j] * y[j]; v[4 * n + j] = ap ? y[j] * gs[bj][n][j] : 0.f; }
;                     }
;                     if (ap) *(u32x4*)(ap + (size_t)row * 1024 + c) = pack8(v);
;                 }
;                 s = xor16_32(s);
;                 if (fq == 0) ssq[(size_t)row * 16 + u.pn * 4 + wc] = s;
.Lnoap_C_1:
	ds_bpermute_b32 v211, v214, v210
	v_permlane16_swap_b32_e32 v140, v136
	v_permlane16_swap_b32_e32 v141, v137
	v_permlane16_swap_b32_e32 v142, v138
	v_permlane16_swap_b32_e32 v143, v139
	v_permlane16_swap_b32_e32 v132, v128
	v_permlane16_swap_b32_e32 v133, v129
	v_permlane16_swap_b32_e32 v134, v130
	v_permlane16_swap_b32_e32 v135, v131
	v_permlane32_swap_b32_e32 v140, v136
	v_permlane32_swap_b32_e32 v141, v137
	v_permlane32_swap_b32_e32 v142, v138
	v_permlane32_swap_b32_e32 v143, v139
	v_permlane32_swap_b32_e32 v132, v128
	v_permlane32_swap_b32_e32 v133, v129
	v_permlane32_swap_b32_e32 v134, v130
	v_permlane32_swap_b32_e32 v135, v131
	s_nop 1
	v_mov_b32_dpp v232, v136 row_ror:8 row_mask:0xf bank_mask:0xf
	v_mov_b32_dpp v233, v137 row_ror:8 row_mask:0xf bank_mask:0xf
	v_mov_b32_dpp v234, v138 row_ror:8 row_mask:0xf bank_mask:0xf
	v_mov_b32_dpp v235, v139 row_ror:8 row_mask:0xf bank_mask:0xf
	v_mov_b32_dpp v240, v128 row_ror:8 row_mask:0xf bank_mask:0xf
	v_mov_b32_dpp v241, v129 row_ror:8 row_mask:0xf bank_mask:0xf
	v_mov_b32_dpp v242, v130 row_ror:8 row_mask:0xf bank_mask:0xf
	v_mov_b32_dpp v243, v131 row_ror:8 row_mask:0xf bank_mask:0xf
	s_mov_b32 vcc_lo, 0xff00ff
	s_mov_b32 vcc_hi, 0xff00ff
	v_mov_b32_e32 v204, 0xffff8040
	v_mov_b32_e32 v205, 0x8040
	v_cndmask_b32_e64 v204, v204, 0, vcc
	v_cndmask_b32_e64 v205, 0, v205, vcc
	v_add_u32_e32 v204, v204, v207
	v_add_u32_e32 v205, v205, v207
	s_mov_b32 exec_lo, 0xff00ff00
	s_mov_b32 exec_hi, 0xff00ff00
	v_swap_b32 v140, v232
	v_swap_b32 v141, v233
	v_swap_b32 v142, v234
	v_swap_b32 v143, v235
	v_swap_b32 v132, v240
	v_swap_b32 v133, v241
	v_swap_b32 v134, v242
	v_swap_b32 v135, v243
	s_mov_b64 exec, -1
	global_store_dwordx4 v204, v[140:143], s[8:9]
	global_store_dwordx4 v204, v[132:135], s[8:9] offset:512
	global_store_dwordx4 v205, v[232:235], s[8:9]
	global_store_dwordx4 v205, v[240:243], s[8:9] offset:512
	v_add_u32_e32 v207, 0x10000, v207
	global_load_dwordx4 v[232:235], v206, s[70:71] offset:64
	global_load_dwordx4 v[240:243], v206, s[70:71] offset:576
	global_load_dwordx4 v[228:231], v206, s[70:71]
	global_load_dwordx4 v[236:239], v206, s[70:71] offset:512
	s_waitcnt lgkmcnt(0)
	v_add_f32_e32 v211, v210, v211
	ds_bpermute_b32 v212, v215, v211
	v_add_u32_e32 v208, 0x8000, v208
	s_waitcnt lgkmcnt(0)
	v_add_f32_e32 v211, v211, v212
	s_mov_b64 exec, 0xffff
	global_store_dword v209, v211, s[72:73]
	s_mov_b64 exec, -1
	v_add_u32_e32 v209, 0x400, v209
	s_waitcnt vmcnt(9)
	v_permlane32_swap_b32_e32 v244, v248
	v_permlane32_swap_b32_e32 v245, v249
	v_permlane32_swap_b32_e32 v246, v250
	v_permlane32_swap_b32_e32 v247, v251
	v_permlane32_swap_b32_e32 v216, v220
	v_permlane32_swap_b32_e32 v217, v221
	v_permlane32_swap_b32_e32 v218, v222
	v_permlane32_swap_b32_e32 v219, v223
	v_permlane16_swap_b32_e32 v244, v248
	v_permlane16_swap_b32_e32 v245, v249
	v_permlane16_swap_b32_e32 v246, v250
	v_permlane16_swap_b32_e32 v247, v251
	v_permlane16_swap_b32_e32 v216, v220
	v_permlane16_swap_b32_e32 v217, v221
	v_permlane16_swap_b32_e32 v218, v222
	v_permlane16_swap_b32_e32 v219, v223
	v_pk_fma_f32 v[124:125], v[124:125], v[144:145], v[244:245]
	v_pk_fma_f32 v[126:127], v[126:127], v[146:147], v[246:247]
	v_mul_f32_e32 v210, v125, v125
	v_fmac_f32_e32 v210, v124, v124
	v_fmac_f32_e32 v210, v126, v126
	v_fmac_f32_e32 v210, v127, v127
	v_pk_fma_f32 v[120:121], v[120:121], v[152:153], v[248:249]
	v_pk_fma_f32 v[122:123], v[122:123], v[154:155], v[250:251]
	v_fmac_f32_e32 v210, v120, v120
	v_fmac_f32_e32 v210, v121, v121
	v_fmac_f32_e32 v210, v122, v122
	v_fmac_f32_e32 v210, v123, v123
	v_pk_fma_f32 v[116:117], v[116:117], v[148:149], v[216:217]
	v_pk_fma_f32 v[118:119], v[118:119], v[150:151], v[218:219]
	v_fmac_f32_e32 v210, v116, v116
	v_fmac_f32_e32 v210, v117, v117
	v_fmac_f32_e32 v210, v118, v118
	v_fmac_f32_e32 v210, v119, v119
	v_pk_fma_f32 v[112:113], v[112:113], v[156:157], v[220:221]
	v_pk_fma_f32 v[114:115], v[114:115], v[158:159], v[222:223]
	v_fmac_f32_e32 v210, v112, v112
	v_fmac_f32_e32 v210, v113, v113
	v_fmac_f32_e32 v210, v114, v114
	v_fmac_f32_e32 v210, v115, v115
	s_cmp_lg_u64 s[2:3], 0
	s_cbranch_scc1 .Lnoap_C_2
	v_pk_mul_f32 v[244:245], v[64:65], v[124:125]
	v_pk_mul_f32 v[246:247], v[66:67], v[126:127]
	v_pk_mul_f32 v[248:249], v[72:73], v[120:121]
	v_pk_mul_f32 v[250:251], v[74:75], v[122:123]
	v_pk_mul_f32 v[216:217], v[68:69], v[116:117]
	v_pk_mul_f32 v[218:219], v[70:71], v[118:119]
	v_pk_mul_f32 v[220:221], v[76:77], v[112:113]
	v_pk_mul_f32 v[222:223], v[78:79], v[114:115]
	v_cvt_pk_bf16_f32 v244, v244, v245
	v_cvt_pk_bf16_f32 v245, v246, v247
	v_cvt_pk_bf16_f32 v246, v248, v249
	v_cvt_pk_bf16_f32 v247, v250, v251
	global_store_dwordx4 v208, v[244:247], s[42:43]
	v_cvt_pk_bf16_f32 v216, v216, v217
	v_cvt_pk_bf16_f32 v217, v218, v219
	v_cvt_pk_bf16_f32 v218, v220, v221
	v_cvt_pk_bf16_f32 v219, v222, v223
	global_store_dwordx4 v208, v[216:219], s[42:43] offset:256
; DI u32x4 pack8(const float* v) { u32x4 w; w.x = pk2(v[0], v[1]); w.y = pk2(v[2], v[3]); w.z = pk2(v[4], v[5]); w.w = pk2(v[6], v[7]); return w; }
; #define xor16_32(s) xor16_32_l((s), fr + 16 * fq)
;     DI void operator()(AccRef acc, const Unit& u, int wr, int wc, int fr, int fq) const {
;     ...
;                 float s = 0.f;
; #pragma unroll
;                 for (int bj = 0; bj < 2; ++bj) {
;                     const int c = u.pn * 256 + bj * 128 + cl;
;                     float v[8];
; #pragma unroll
;                     for (int n = 0; n < 2; ++n) {
;                         const f32x4 x = *(const f32x4*)(xi + c + 4 * n);
;                         const f32x4 y = x + gt[bj][n] * acc[ai][bj][m][n];
;                         *(f32x4*)(xout + (size_t)row * 1024 + c + 4 * n) = y;
; #pragma unroll
;                         for (int j = 0; j < 4; ++j) { s += y[j] * y[j]; v[4 * n + j] = ap ? y[j] * gs[bj][n][j] : 0.f; }
;                     }
;                     if (ap) *(u32x4*)(ap + (size_t)row * 1024 + c) = pack8(v);
;                 }
;                 s = xor16_32(s);
;                 if (fq == 0) ssq[(size_t)row * 16 + u.pn * 4 + wc] = s;
.Lnoap_C_2:
	ds_bpermute_b32 v211, v214, v210
	v_permlane16_swap_b32_e32 v124, v120
	v_permlane16_swap_b32_e32 v125, v121
	v_permlane16_swap_b32_e32 v126, v122
	v_permlane16_swap_b32_e32 v127, v123
	v_permlane16_swap_b32_e32 v116, v112
	v_permlane16_swap_b32_e32 v117, v113
	v_permlane16_swap_b32_e32 v118, v114
	v_permlane16_swap_b32_e32 v119, v115
	v_permlane32_swap_b32_e32 v124, v120
	v_permlane32_swap_b32_e32 v125, v121
	v_permlane32_swap_b32_e32 v126, v122
	v_permlane32_swap_b32_e32 v127, v123
	v_permlane32_swap_b32_e32 v116, v112
	v_permlane32_swap_b32_e32 v117, v113
	v_permlane32_swap_b32_e32 v118, v114
	v_permlane32_swap_b32_e32 v119, v115
	s_nop 1
	v_mov_b32_dpp v248, v120 row_ror:8 row_mask:0xf bank_mask:0xf
	v_mov_b32_dpp v249, v121 row_ror:8 row_mask:0xf bank_mask:0xf
	v_mov_b32_dpp v250, v122 row_ror:8 row_mask:0xf bank_mask:0xf
	v_mov_b32_dpp v251, v123 row_ror:8 row_mask:0xf bank_mask:0xf
	v_mov_b32_dpp v220, v112 row_ror:8 row_mask:0xf bank_mask:0xf
	v_mov_b32_dpp v221, v113 row_ror:8 row_mask:0xf bank_mask:0xf
	v_mov_b32_dpp v222, v114 row_ror:8 row_mask:0xf bank_mask:0xf
	v_mov_b32_dpp v223, v115 row_ror:8 row_mask:0xf bank_mask:0xf
	s_mov_b32 vcc_lo, 0xff00ff
	s_mov_b32 vcc_hi, 0xff00ff
	v_mov_b32_e32 v204, 0xffff8040
	v_mov_b32_e32 v205, 0x8040
	v_cndmask_b32_e64 v204, v204, 0, vcc
	v_cndmask_b32_e64 v205, 0, v205, vcc
	v_add_u32_e32 v204, v204, v207
	v_add_u32_e32 v205, v205, v207
	s_mov_b32 exec_lo, 0xff00ff00
	s_mov_b32 exec_hi, 0xff00ff00
	v_swap_b32 v124, v248
	v_swap_b32 v125, v249
	v_swap_b32 v126, v250
	v_swap_b32 v127, v251
	v_swap_b32 v116, v220
	v_swap_b32 v117, v221
	v_swap_b32 v118, v222
	v_swap_b32 v119, v223
	s_mov_b64 exec, -1
	global_store_dwordx4 v204, v[124:127], s[8:9]
	global_store_dwordx4 v204, v[116:119], s[8:9] offset:512
	global_store_dwordx4 v205, v[248:251], s[8:9]
	global_store_dwordx4 v205, v[220:223], s[8:9] offset:512
	v_add_u32_e32 v207, 0x10000, v207
	v_add_u32_e32 v206, 0x10000, v206
	global_load_dwordx4 v[248:251], v206, s[70:71] offset:64
	global_load_dwordx4 v[220:223], v206, s[70:71] offset:576
	global_load_dwordx4 v[244:247], v206, s[70:71]
	global_load_dwordx4 v[216:219], v206, s[70:71] offset:512
	s_waitcnt lgkmcnt(0)
	v_add_f32_e32 v211, v210, v211
	ds_bpermute_b32 v212, v215, v211
	v_add_u32_e32 v208, 0x8000, v208
	s_waitcnt lgkmcnt(0)
	v_add_f32_e32 v211, v211, v212
	s_mov_b64 exec, 0xffff
	global_store_dword v209, v211, s[72:73]
	s_mov_b64 exec, -1
	v_add_u32_e32 v209, 0x400, v209
	s_waitcnt vmcnt(10)
	v_permlane32_swap_b32_e32 v228, v232
	v_permlane32_swap_b32_e32 v229, v233
	v_permlane32_swap_b32_e32 v230, v234
	v_permlane32_swap_b32_e32 v231, v235
	v_permlane32_swap_b32_e32 v236, v240
	v_permlane32_swap_b32_e32 v237, v241
	v_permlane32_swap_b32_e32 v238, v242
	v_permlane32_swap_b32_e32 v239, v243
	v_permlane16_swap_b32_e32 v228, v232
	v_permlane16_swap_b32_e32 v229, v233
	v_permlane16_swap_b32_e32 v230, v234
	v_permlane16_swap_b32_e32 v231, v235
	v_permlane16_swap_b32_e32 v236, v240
	v_permlane16_swap_b32_e32 v237, v241
	v_permlane16_swap_b32_e32 v238, v242
	v_permlane16_swap_b32_e32 v239, v243
	v_pk_fma_f32 v[108:109], v[108:109], v[144:145], v[228:229]
	v_pk_fma_f32 v[110:111], v[110:111], v[146:147], v[230:231]
	v_mul_f32_e32 v210, v109, v109
	v_fmac_f32_e32 v210, v108, v108
	v_fmac_f32_e32 v210, v110, v110
	v_fmac_f32_e32 v210, v111, v111
	v_pk_fma_f32 v[104:105], v[104:105], v[152:153], v[232:233]
	v_pk_fma_f32 v[106:107], v[106:107], v[154:155], v[234:235]
	v_fmac_f32_e32 v210, v104, v104
	v_fmac_f32_e32 v210, v105, v105
	v_fmac_f32_e32 v210, v106, v106
	v_fmac_f32_e32 v210, v107, v107
	v_pk_fma_f32 v[100:101], v[100:101], v[148:149], v[236:237]
	v_pk_fma_f32 v[102:103], v[102:103], v[150:151], v[238:239]
	v_fmac_f32_e32 v210, v100, v100
	v_fmac_f32_e32 v210, v101, v101
	v_fmac_f32_e32 v210, v102, v102
	v_fmac_f32_e32 v210, v103, v103
	v_pk_fma_f32 v[96:97], v[96:97], v[156:157], v[240:241]
	v_pk_fma_f32 v[98:99], v[98:99], v[158:159], v[242:243]
	v_fmac_f32_e32 v210, v96, v96
	v_fmac_f32_e32 v210, v97, v97
	v_fmac_f32_e32 v210, v98, v98
	v_fmac_f32_e32 v210, v99, v99
	s_cmp_lg_u64 s[2:3], 0
	s_cbranch_scc1 .Lnoap_C_3
	v_pk_mul_f32 v[228:229], v[64:65], v[108:109]
	v_pk_mul_f32 v[230:231], v[66:67], v[110:111]
	v_pk_mul_f32 v[232:233], v[72:73], v[104:105]
	v_pk_mul_f32 v[234:235], v[74:75], v[106:107]
	v_pk_mul_f32 v[236:237], v[68:69], v[100:101]
	v_pk_mul_f32 v[238:239], v[70:71], v[102:103]
	v_pk_mul_f32 v[240:241], v[76:77], v[96:97]
	v_pk_mul_f32 v[242:243], v[78:79], v[98:99]
	v_cvt_pk_bf16_f32 v228, v228, v229
	v_cvt_pk_bf16_f32 v229, v230, v231
	v_cvt_pk_bf16_f32 v230, v232, v233
	v_cvt_pk_bf16_f32 v231, v234, v235
	global_store_dwordx4 v208, v[228:231], s[42:43]
	v_cvt_pk_bf16_f32 v236, v236, v237
	v_cvt_pk_bf16_f32 v237, v238, v239
	v_cvt_pk_bf16_f32 v238, v240, v241
	v_cvt_pk_bf16_f32 v239, v242, v243
	global_store_dwordx4 v208, v[236:239], s[42:43] offset:256
; DI u32x4 pack8(const float* v) { u32x4 w; w.x = pk2(v[0], v[1]); w.y = pk2(v[2], v[3]); w.z = pk2(v[4], v[5]); w.w = pk2(v[6], v[7]); return w; }
; #define xor16_32(s) xor16_32_l((s), fr + 16 * fq)
;     DI void operator()(AccRef acc, const Unit& u, int wr, int wc, int fr, int fq) const {
;     ...
;                 float s = 0.f;
; #pragma unroll
;                 for (int bj = 0; bj < 2; ++bj) {
;                     const int c = u.pn * 256 + bj * 128 + cl;
;                     float v[8];
; #pragma unroll
;                     for (int n = 0; n < 2; ++n) {
;                         const f32x4 x = *(const f32x4*)(xi + c + 4 * n);
;                         const f32x4 y = x + gt[bj][n] * acc[ai][bj][m][n];
;                         *(f32x4*)(xout + (size_t)row * 1024 + c + 4 * n) = y;
; #pragma unroll
;                         for (int j = 0; j < 4; ++j) { s += y[j] * y[j]; v[4 * n + j] = ap ? y[j] * gs[bj][n][j] : 0.f; }
;                     }
;                     if (ap) *(u32x4*)(ap + (size_t)row * 1024 + c) = pack8(v);
;                 }
;                 s = xor16_32(s);
;                 if (fq == 0) ssq[(size_t)row * 16 + u.pn * 4 + wc] = s;
.Lnoap_C_3:
	ds_bpermute_b32 v211, v214, v210
	v_permlane16_swap_b32_e32 v108, v104
	v_permlane16_swap_b32_e32 v109, v105
	v_permlane16_swap_b32_e32 v110, v106
	v_permlane16_swap_b32_e32 v111, v107
	v_permlane16_swap_b32_e32 v100, v96
	v_permlane16_swap_b32_e32 v101, v97
	v_permlane16_swap_b32_e32 v102, v98
	v_permlane16_swap_b32_e32 v103, v99
	v_permlane32_swap_b32_e32 v108, v104
	v_permlane32_swap_b32_e32 v109, v105
	v_permlane32_swap_b32_e32 v110, v106
	v_permlane32_swap_b32_e32 v111, v107
	v_permlane32_swap_b32_e32 v100, v96
	v_permlane32_swap_b32_e32 v101, v97
	v_permlane32_swap_b32_e32 v102, v98
	v_permlane32_swap_b32_e32 v103, v99
	s_nop 1
	v_mov_b32_dpp v232, v104 row_ror:8 row_mask:0xf bank_mask:0xf
	v_mov_b32_dpp v233, v105 row_ror:8 row_mask:0xf bank_mask:0xf
	v_mov_b32_dpp v234, v106 row_ror:8 row_mask:0xf bank_mask:0xf
	v_mov_b32_dpp v235, v107 row_ror:8 row_mask:0xf bank_mask:0xf
	v_mov_b32_dpp v240, v96 row_ror:8 row_mask:0xf bank_mask:0xf
	v_mov_b32_dpp v241, v97 row_ror:8 row_mask:0xf bank_mask:0xf
	v_mov_b32_dpp v242, v98 row_ror:8 row_mask:0xf bank_mask:0xf
	v_mov_b32_dpp v243, v99 row_ror:8 row_mask:0xf bank_mask:0xf
	s_mov_b32 vcc_lo, 0xff00ff
	s_mov_b32 vcc_hi, 0xff00ff
	v_mov_b32_e32 v204, 0xffff8040
	v_mov_b32_e32 v205, 0x8040
	v_cndmask_b32_e64 v204, v204, 0, vcc
	v_cndmask_b32_e64 v205, 0, v205, vcc
	v_add_u32_e32 v204, v204, v207
	v_add_u32_e32 v205, v205, v207
	s_mov_b32 exec_lo, 0xff00ff00
	s_mov_b32 exec_hi, 0xff00ff00
	v_swap_b32 v108, v232
	v_swap_b32 v109, v233
	v_swap_b32 v110, v234
	v_swap_b32 v111, v235
	v_swap_b32 v100, v240
	v_swap_b32 v101, v241
	v_swap_b32 v102, v242
	v_swap_b32 v103, v243
	s_mov_b64 exec, -1
	global_store_dwordx4 v204, v[108:111], s[8:9]
	global_store_dwordx4 v204, v[100:103], s[8:9] offset:512
	global_store_dwordx4 v205, v[232:235], s[8:9]
	global_store_dwordx4 v205, v[240:243], s[8:9] offset:512
	v_add_u32_e32 v207, 0x10000, v207
	v_add_u32_e32 v206, 0x50000, v206
	global_load_dwordx4 v[232:235], v206, s[70:71] offset:64
	global_load_dwordx4 v[240:243], v206, s[70:71] offset:576
	global_load_dwordx4 v[228:231], v206, s[70:71]
	global_load_dwordx4 v[236:239], v206, s[70:71] offset:512
	s_waitcnt lgkmcnt(0)
	v_add_f32_e32 v211, v210, v211
	ds_bpermute_b32 v212, v215, v211
	v_add_u32_e32 v208, 0x8000, v208
	s_waitcnt lgkmcnt(0)
	v_add_f32_e32 v211, v211, v212
	s_mov_b64 exec, 0xffff
	global_store_dword v209, v211, s[72:73]
	s_mov_b64 exec, -1
	v_add_u32_e32 v209, 0x400, v209
	s_waitcnt vmcnt(10)
	v_permlane32_swap_b32_e32 v244, v248
	v_permlane32_swap_b32_e32 v245, v249
	v_permlane32_swap_b32_e32 v246, v250
	v_permlane32_swap_b32_e32 v247, v251
	v_permlane32_swap_b32_e32 v216, v220
	v_permlane32_swap_b32_e32 v217, v221
	v_permlane32_swap_b32_e32 v218, v222
	v_permlane32_swap_b32_e32 v219, v223
	v_permlane16_swap_b32_e32 v244, v248
	v_permlane16_swap_b32_e32 v245, v249
	v_permlane16_swap_b32_e32 v246, v250
	v_permlane16_swap_b32_e32 v247, v251
	v_permlane16_swap_b32_e32 v216, v220
	v_permlane16_swap_b32_e32 v217, v221
	v_permlane16_swap_b32_e32 v218, v222
	v_permlane16_swap_b32_e32 v219, v223
	v_pk_fma_f32 v[92:93], v[92:93], v[144:145], v[244:245]
	v_pk_fma_f32 v[94:95], v[94:95], v[146:147], v[246:247]
	v_mul_f32_e32 v210, v93, v93
	v_fmac_f32_e32 v210, v92, v92
	v_fmac_f32_e32 v210, v94, v94
	v_fmac_f32_e32 v210, v95, v95
	v_pk_fma_f32 v[88:89], v[88:89], v[152:153], v[248:249]
	v_pk_fma_f32 v[90:91], v[90:91], v[154:155], v[250:251]
	v_fmac_f32_e32 v210, v88, v88
	v_fmac_f32_e32 v210, v89, v89
	v_fmac_f32_e32 v210, v90, v90
	v_fmac_f32_e32 v210, v91, v91
	v_pk_fma_f32 v[84:85], v[84:85], v[148:149], v[216:217]
	v_pk_fma_f32 v[86:87], v[86:87], v[150:151], v[218:219]
	v_fmac_f32_e32 v210, v84, v84
	v_fmac_f32_e32 v210, v85, v85
	v_fmac_f32_e32 v210, v86, v86
	v_fmac_f32_e32 v210, v87, v87
	v_pk_fma_f32 v[80:81], v[80:81], v[156:157], v[220:221]
	v_pk_fma_f32 v[82:83], v[82:83], v[158:159], v[222:223]
	v_fmac_f32_e32 v210, v80, v80
	v_fmac_f32_e32 v210, v81, v81
	v_fmac_f32_e32 v210, v82, v82
	v_fmac_f32_e32 v210, v83, v83
	s_cmp_lg_u64 s[2:3], 0
	s_cbranch_scc1 .Lnoap_C_4
	v_pk_mul_f32 v[244:245], v[64:65], v[92:93]
	v_pk_mul_f32 v[246:247], v[66:67], v[94:95]
	v_pk_mul_f32 v[248:249], v[72:73], v[88:89]
	v_pk_mul_f32 v[250:251], v[74:75], v[90:91]
	v_pk_mul_f32 v[216:217], v[68:69], v[84:85]
	v_pk_mul_f32 v[218:219], v[70:71], v[86:87]
	v_pk_mul_f32 v[220:221], v[76:77], v[80:81]
	v_pk_mul_f32 v[222:223], v[78:79], v[82:83]
	v_cvt_pk_bf16_f32 v244, v244, v245
	v_cvt_pk_bf16_f32 v245, v246, v247
	v_cvt_pk_bf16_f32 v246, v248, v249
	v_cvt_pk_bf16_f32 v247, v250, v251
	global_store_dwordx4 v208, v[244:247], s[42:43]
	v_cvt_pk_bf16_f32 v216, v216, v217
	v_cvt_pk_bf16_f32 v217, v218, v219
	v_cvt_pk_bf16_f32 v218, v220, v221
	v_cvt_pk_bf16_f32 v219, v222, v223
	global_store_dwordx4 v208, v[216:219], s[42:43] offset:256
; DI u32x4 pack8(const float* v) { u32x4 w; w.x = pk2(v[0], v[1]); w.y = pk2(v[2], v[3]); w.z = pk2(v[4], v[5]); w.w = pk2(v[6], v[7]); return w; }
; #define xor16_32(s) xor16_32_l((s), fr + 16 * fq)
;     DI void operator()(AccRef acc, const Unit& u, int wr, int wc, int fr, int fq) const {
;     ...
;         for (int ai = 0; ai < 2; ++ai) {
;             const int rb = u.pm * 256 + ai * 128 + wr * 64 + fr;
;             int mb, pos0, kv0; row_info(rb, mb, pos0, kv0);
;             f32x4 gt[2][2], gs[2][2];
; #pragma unroll
;             for (int bj = 0; bj < 2; ++bj)
; #pragma unroll
;                 for (int n = 0; n < 2; ++n) {
;                     const int c = u.pn * 256 + bj * 128 + cl + 4 * n;
;                     gt[bj][n] = *(const f32x4*)(gate + (size_t)mb * 6144 + c);
;                     if (ap) { const f32x4 g = *(const f32x4*)(gn + c), s = *(const f32x4*)(scn + (size_t)mb * 6144 + c); gs[bj][n] = g * (s + 1.f); }
;                 }
;     ...
;                 float s = 0.f;
; #pragma unroll
;                 for (int bj = 0; bj < 2; ++bj) {
;                     const int c = u.pn * 256 + bj * 128 + cl;
;                     float v[8];
; #pragma unroll
;                     for (int n = 0; n < 2; ++n) {
;                         const f32x4 x = *(const f32x4*)(xi + c + 4 * n);
;                         const f32x4 y = x + gt[bj][n] * acc[ai][bj][m][n];
;                         *(f32x4*)(xout + (size_t)row * 1024 + c + 4 * n) = y;
; #pragma unroll
;                         for (int j = 0; j < 4; ++j) { s += y[j] * y[j]; v[4 * n + j] = ap ? y[j] * gs[bj][n][j] : 0.f; }
;                     }
;                     if (ap) *(u32x4*)(ap + (size_t)row * 1024 + c) = pack8(v);
;                 }
;                 s = xor16_32(s);
;                 if (fq == 0) ssq[(size_t)row * 16 + u.pn * 4 + wc] = s;
.Lnoap_C_4:
	ds_bpermute_b32 v211, v214, v210
	v_permlane16_swap_b32_e32 v92, v88
	v_permlane16_swap_b32_e32 v93, v89
	v_permlane16_swap_b32_e32 v94, v90
	v_permlane16_swap_b32_e32 v95, v91
	v_permlane16_swap_b32_e32 v84, v80
	v_permlane16_swap_b32_e32 v85, v81
	v_permlane16_swap_b32_e32 v86, v82
	v_permlane16_swap_b32_e32 v87, v83
	v_permlane32_swap_b32_e32 v92, v88
	v_permlane32_swap_b32_e32 v93, v89
	v_permlane32_swap_b32_e32 v94, v90
	v_permlane32_swap_b32_e32 v95, v91
	v_permlane32_swap_b32_e32 v84, v80
	v_permlane32_swap_b32_e32 v85, v81
	v_permlane32_swap_b32_e32 v86, v82
	v_permlane32_swap_b32_e32 v87, v83
	s_nop 1
	v_mov_b32_dpp v248, v88 row_ror:8 row_mask:0xf bank_mask:0xf
	v_mov_b32_dpp v249, v89 row_ror:8 row_mask:0xf bank_mask:0xf
	v_mov_b32_dpp v250, v90 row_ror:8 row_mask:0xf bank_mask:0xf
	v_mov_b32_dpp v251, v91 row_ror:8 row_mask:0xf bank_mask:0xf
	v_mov_b32_dpp v220, v80 row_ror:8 row_mask:0xf bank_mask:0xf
	v_mov_b32_dpp v221, v81 row_ror:8 row_mask:0xf bank_mask:0xf
	v_mov_b32_dpp v222, v82 row_ror:8 row_mask:0xf bank_mask:0xf
	v_mov_b32_dpp v223, v83 row_ror:8 row_mask:0xf bank_mask:0xf
	s_mov_b32 vcc_lo, 0xff00ff
	s_mov_b32 vcc_hi, 0xff00ff
	v_mov_b32_e32 v204, 0xffff8040
	v_mov_b32_e32 v205, 0x8040
	v_cndmask_b32_e64 v204, v204, 0, vcc
	v_cndmask_b32_e64 v205, 0, v205, vcc
	v_add_u32_e32 v204, v204, v207
	v_add_u32_e32 v205, v205, v207
	s_mov_b32 exec_lo, 0xff00ff00
	s_mov_b32 exec_hi, 0xff00ff00
	v_swap_b32 v92, v248
	v_swap_b32 v93, v249
	v_swap_b32 v94, v250
	v_swap_b32 v95, v251
	v_swap_b32 v84, v220
	v_swap_b32 v85, v221
	v_swap_b32 v86, v222
	v_swap_b32 v87, v223
	s_mov_b64 exec, -1
	global_store_dwordx4 v204, v[92:95], s[8:9]
	global_store_dwordx4 v204, v[84:87], s[8:9] offset:512
	global_store_dwordx4 v205, v[248:251], s[8:9]
	global_store_dwordx4 v205, v[220:223], s[8:9] offset:512
	v_add_u32_e32 v207, 0x50000, v207
	v_add_u32_e32 v206, 0x10000, v206
	global_load_dwordx4 v[248:251], v206, s[70:71] offset:64
	global_load_dwordx4 v[220:223], v206, s[70:71] offset:576
	global_load_dwordx4 v[244:247], v206, s[70:71]
	global_load_dwordx4 v[216:219], v206, s[70:71] offset:512
	s_waitcnt lgkmcnt(0)
	v_add_f32_e32 v211, v210, v211
	ds_bpermute_b32 v212, v215, v211
	v_add_u32_e32 v208, 0x28000, v208
	s_waitcnt lgkmcnt(0)
	v_add_f32_e32 v211, v211, v212
	s_mov_b64 exec, 0xffff
	global_store_dword v209, v211, s[72:73]
	s_mov_b64 exec, -1
	v_add_u32_e32 v209, 0x1400, v209
	v_add_u32_e32 v224, 0xffffc080, v176
	v_add_u32_e32 v96, 0x80, v176
	s_waitcnt lgkmcnt(0)
	v_lshrrev_b32_e32 v81, 6, v224
	v_cmp_gt_i32_e32 vcc, s94, v96
	v_ashrrev_i32_e32 v80, 11, v96
	v_add_u32_e32 v81, 8, v81
	v_cndmask_b32_e32 v84, v81, v80, vcc
	v_mov_b64_e32 v[80:81], s[28:29]
	v_mad_i64_i32 v[80:81], s[12:13], v84, s75, v[80:81]
	v_mov_b64_e32 v[82:83], s[30:31]
	v_lshl_add_u64 v[92:93], v[172:173], 2, v[80:81]
	v_mad_i64_i32 v[84:85], s[12:13], v84, s75, v[82:83]
	global_load_dwordx4 v[80:83], v[92:93], off
	s_movk_i32 s6, 0x3fff
	v_cmp_lt_i32_e64 s[6:7], s6, v96
	s_and_b64 vcc, exec, s[2:3]
	s_cbranch_vccnz .LBB0_1567
	v_lshl_add_u64 v[64:65], v[84:85], 0, v[174:175]
	global_load_dwordx4 v[64:67], v[64:65], off
	s_nop 0
	global_load_dwordx4 v[86:89], v[178:179], off
	s_waitcnt vmcnt(1)
	v_pk_add_f32 v[66:67], v[66:67], 1.0 op_sel_hi:[1,0]
	v_pk_add_f32 v[64:65], v[64:65], 1.0 op_sel_hi:[1,0]
	s_waitcnt vmcnt(0)
	v_pk_mul_f32 v[66:67], v[88:89], v[66:67]
	v_pk_mul_f32 v[64:65], v[86:87], v[64:65]
	global_load_dwordx4 v[88:91], v[92:93], off offset:16
	s_and_b64 vcc, exec, s[2:3]
	v_lshl_add_u64 v[98:99], v[172:173], 2, v[84:85]
	s_cbranch_vccz .LBB0_1568

; DI u32x4 pack8(const float* v) { u32x4 w; w.x = pk2(v[0], v[1]); w.y = pk2(v[2], v[3]); w.z = pk2(v[4], v[5]); w.w = pk2(v[6], v[7]); return w; }
; #define xor16_32(s) xor16_32_l((s), fr + 16 * fq)
;     DI void operator()(AccRef acc, const Unit& u, int wr, int wc, int fr, int fq) const {
;     ...
;                 float s = 0.f;
; #pragma unroll
;                 for (int bj = 0; bj < 2; ++bj) {
;                     const int c = u.pn * 256 + bj * 128 + cl;
;                     float v[8];
; #pragma unroll
;                     for (int n = 0; n < 2; ++n) {
;                         const f32x4 x = *(const f32x4*)(xi + c + 4 * n);
;                         const f32x4 y = x + gt[bj][n] * acc[ai][bj][m][n];
;                         *(f32x4*)(xout + (size_t)row * 1024 + c + 4 * n) = y;
; #pragma unroll
;                         for (int j = 0; j < 4; ++j) { s += y[j] * y[j]; v[4 * n + j] = ap ? y[j] * gs[bj][n][j] : 0.f; }
;                     }
;                     if (ap) *(u32x4*)(ap + (size_t)row * 1024 + c) = pack8(v);
;                 }
;                 s = xor16_32(s);
;                 if (fq == 0) ssq[(size_t)row * 16 + u.pn * 4 + wc] = s;
.Lnoap_C_5:
	ds_bpermute_b32 v211, v214, v210
	v_permlane16_swap_b32_e32 v60, v56
	v_permlane16_swap_b32_e32 v61, v57
	v_permlane16_swap_b32_e32 v62, v58
	v_permlane16_swap_b32_e32 v63, v59
	v_permlane16_swap_b32_e32 v52, v48
	v_permlane16_swap_b32_e32 v53, v49
	v_permlane16_swap_b32_e32 v54, v50
	v_permlane16_swap_b32_e32 v55, v51
	v_permlane32_swap_b32_e32 v60, v56
	v_permlane32_swap_b32_e32 v61, v57
	v_permlane32_swap_b32_e32 v62, v58
	v_permlane32_swap_b32_e32 v63, v59
	v_permlane32_swap_b32_e32 v52, v48
	v_permlane32_swap_b32_e32 v53, v49
	v_permlane32_swap_b32_e32 v54, v50
	v_permlane32_swap_b32_e32 v55, v51
	s_nop 1
	v_mov_b32_dpp v232, v56 row_ror:8 row_mask:0xf bank_mask:0xf
	v_mov_b32_dpp v233, v57 row_ror:8 row_mask:0xf bank_mask:0xf
	v_mov_b32_dpp v234, v58 row_ror:8 row_mask:0xf bank_mask:0xf
	v_mov_b32_dpp v235, v59 row_ror:8 row_mask:0xf bank_mask:0xf
	v_mov_b32_dpp v240, v48 row_ror:8 row_mask:0xf bank_mask:0xf
	v_mov_b32_dpp v241, v49 row_ror:8 row_mask:0xf bank_mask:0xf
	v_mov_b32_dpp v242, v50 row_ror:8 row_mask:0xf bank_mask:0xf
	v_mov_b32_dpp v243, v51 row_ror:8 row_mask:0xf bank_mask:0xf
	s_mov_b32 vcc_lo, 0xff00ff
	s_mov_b32 vcc_hi, 0xff00ff
	v_mov_b32_e32 v204, 0xffff8040
	v_mov_b32_e32 v205, 0x8040
	v_cndmask_b32_e64 v204, v204, 0, vcc
	v_cndmask_b32_e64 v205, 0, v205, vcc
	v_add_u32_e32 v204, v204, v207
	v_add_u32_e32 v205, v205, v207
	s_mov_b32 exec_lo, 0xff00ff00
	s_mov_b32 exec_hi, 0xff00ff00
	v_swap_b32 v60, v232
	v_swap_b32 v61, v233
	v_swap_b32 v62, v234
	v_swap_b32 v63, v235
	v_swap_b32 v52, v240
	v_swap_b32 v53, v241
	v_swap_b32 v54, v242
	v_swap_b32 v55, v243
	s_mov_b64 exec, -1
	global_store_dwordx4 v204, v[60:63], s[8:9]
	global_store_dwordx4 v204, v[52:55], s[8:9] offset:512
	global_store_dwordx4 v205, v[232:235], s[8:9]
	global_store_dwordx4 v205, v[240:243], s[8:9] offset:512
	v_add_u32_e32 v207, 0x10000, v207
	v_add_u32_e32 v206, 0x10000, v206
	global_load_dwordx4 v[232:235], v206, s[70:71] offset:64
	global_load_dwordx4 v[240:243], v206, s[70:71] offset:576
	global_load_dwordx4 v[228:231], v206, s[70:71]
	global_load_dwordx4 v[236:239], v206, s[70:71] offset:512
	s_waitcnt lgkmcnt(0)
	v_add_f32_e32 v211, v210, v211
	ds_bpermute_b32 v212, v215, v211
	v_add_u32_e32 v208, 0x8000, v208
	s_waitcnt lgkmcnt(0)
	v_add_f32_e32 v211, v211, v212
	s_mov_b64 exec, 0xffff
	global_store_dword v209, v211, s[72:73]
	s_mov_b64 exec, -1
	v_add_u32_e32 v209, 0x400, v209
	v_permlane32_swap_b32_e32 v244, v248
	v_permlane32_swap_b32_e32 v245, v249
	v_permlane32_swap_b32_e32 v246, v250
	v_permlane32_swap_b32_e32 v247, v251
	v_permlane32_swap_b32_e32 v216, v220
	v_permlane32_swap_b32_e32 v217, v221
	v_permlane32_swap_b32_e32 v218, v222
	v_permlane32_swap_b32_e32 v219, v223
	v_permlane16_swap_b32_e32 v244, v248
	v_permlane16_swap_b32_e32 v245, v249
	v_permlane16_swap_b32_e32 v246, v250
	v_permlane16_swap_b32_e32 v247, v251
	v_permlane16_swap_b32_e32 v216, v220
	v_permlane16_swap_b32_e32 v217, v221
	v_permlane16_swap_b32_e32 v218, v222
	v_permlane16_swap_b32_e32 v219, v223
	v_pk_fma_f32 v[44:45], v[44:45], v[80:81], v[244:245]
	v_pk_fma_f32 v[46:47], v[46:47], v[82:83], v[246:247]
	v_mul_f32_e32 v210, v45, v45
	v_fmac_f32_e32 v210, v44, v44
	v_fmac_f32_e32 v210, v46, v46
	v_fmac_f32_e32 v210, v47, v47
	v_pk_fma_f32 v[40:41], v[40:41], v[88:89], v[248:249]
	v_pk_fma_f32 v[42:43], v[42:43], v[90:91], v[250:251]
	v_fmac_f32_e32 v210, v40, v40
	v_fmac_f32_e32 v210, v41, v41
	v_fmac_f32_e32 v210, v42, v42
	v_fmac_f32_e32 v210, v43, v43
	v_pk_fma_f32 v[36:37], v[36:37], v[84:85], v[216:217]
	v_pk_fma_f32 v[38:39], v[38:39], v[86:87], v[218:219]
	v_fmac_f32_e32 v210, v36, v36
	v_fmac_f32_e32 v210, v37, v37
	v_fmac_f32_e32 v210, v38, v38
	v_fmac_f32_e32 v210, v39, v39
	v_pk_fma_f32 v[32:33], v[32:33], v[92:93], v[220:221]
	v_pk_fma_f32 v[34:35], v[34:35], v[94:95], v[222:223]
	v_fmac_f32_e32 v210, v32, v32
	v_fmac_f32_e32 v210, v33, v33
	v_fmac_f32_e32 v210, v34, v34
	v_fmac_f32_e32 v210, v35, v35
	s_cmp_lg_u64 s[2:3], 0
	s_cbranch_scc1 .Lnoap_C_6
	v_pk_mul_f32 v[244:245], v[64:65], v[44:45]
	v_pk_mul_f32 v[246:247], v[66:67], v[46:47]
	v_pk_mul_f32 v[248:249], v[72:73], v[40:41]
	v_pk_mul_f32 v[250:251], v[74:75], v[42:43]
	v_pk_mul_f32 v[216:217], v[68:69], v[36:37]
	v_pk_mul_f32 v[218:219], v[70:71], v[38:39]
	v_pk_mul_f32 v[220:221], v[76:77], v[32:33]
	v_pk_mul_f32 v[222:223], v[78:79], v[34:35]
	v_cvt_pk_bf16_f32 v244, v244, v245
	v_cvt_pk_bf16_f32 v245, v246, v247
	v_cvt_pk_bf16_f32 v246, v248, v249
	v_cvt_pk_bf16_f32 v247, v250, v251
	global_store_dwordx4 v208, v[244:247], s[42:43]
	v_cvt_pk_bf16_f32 v216, v216, v217
	v_cvt_pk_bf16_f32 v217, v218, v219
	v_cvt_pk_bf16_f32 v218, v220, v221
	v_cvt_pk_bf16_f32 v219, v222, v223
	global_store_dwordx4 v208, v[216:219], s[42:43] offset:256
; DI u32x4 pack8(const float* v) { u32x4 w; w.x = pk2(v[0], v[1]); w.y = pk2(v[2], v[3]); w.z = pk2(v[4], v[5]); w.w = pk2(v[6], v[7]); return w; }
; #define xor16_32(s) xor16_32_l((s), fr + 16 * fq)
;     DI void operator()(AccRef acc, const Unit& u, int wr, int wc, int fr, int fq) const {
;     ...
;                 float s = 0.f;
; #pragma unroll
;                 for (int bj = 0; bj < 2; ++bj) {
;                     const int c = u.pn * 256 + bj * 128 + cl;
;                     float v[8];
; #pragma unroll
;                     for (int n = 0; n < 2; ++n) {
;                         const f32x4 x = *(const f32x4*)(xi + c + 4 * n);
;                         const f32x4 y = x + gt[bj][n] * acc[ai][bj][m][n];
;                         *(f32x4*)(xout + (size_t)row * 1024 + c + 4 * n) = y;
; #pragma unroll
;                         for (int j = 0; j < 4; ++j) { s += y[j] * y[j]; v[4 * n + j] = ap ? y[j] * gs[bj][n][j] : 0.f; }
;                     }
;                     if (ap) *(u32x4*)(ap + (size_t)row * 1024 + c) = pack8(v);
;                 }
;                 s = xor16_32(s);
;                 if (fq == 0) ssq[(size_t)row * 16 + u.pn * 4 + wc] = s;
.Lnoap_C_6:
	ds_bpermute_b32 v211, v214, v210
	v_permlane16_swap_b32_e32 v44, v40
	v_permlane16_swap_b32_e32 v45, v41
	v_permlane16_swap_b32_e32 v46, v42
	v_permlane16_swap_b32_e32 v47, v43
	v_permlane16_swap_b32_e32 v36, v32
	v_permlane16_swap_b32_e32 v37, v33
	v_permlane16_swap_b32_e32 v38, v34
	v_permlane16_swap_b32_e32 v39, v35
	v_permlane32_swap_b32_e32 v44, v40
	v_permlane32_swap_b32_e32 v45, v41
	v_permlane32_swap_b32_e32 v46, v42
	v_permlane32_swap_b32_e32 v47, v43
	v_permlane32_swap_b32_e32 v36, v32
	v_permlane32_swap_b32_e32 v37, v33
	v_permlane32_swap_b32_e32 v38, v34
	v_permlane32_swap_b32_e32 v39, v35
	s_nop 1
	v_mov_b32_dpp v248, v40 row_ror:8 row_mask:0xf bank_mask:0xf
	v_mov_b32_dpp v249, v41 row_ror:8 row_mask:0xf bank_mask:0xf
	v_mov_b32_dpp v250, v42 row_ror:8 row_mask:0xf bank_mask:0xf
	v_mov_b32_dpp v251, v43 row_ror:8 row_mask:0xf bank_mask:0xf
	v_mov_b32_dpp v220, v32 row_ror:8 row_mask:0xf bank_mask:0xf
	v_mov_b32_dpp v221, v33 row_ror:8 row_mask:0xf bank_mask:0xf
	v_mov_b32_dpp v222, v34 row_ror:8 row_mask:0xf bank_mask:0xf
	v_mov_b32_dpp v223, v35 row_ror:8 row_mask:0xf bank_mask:0xf
	s_mov_b32 vcc_lo, 0xff00ff
	s_mov_b32 vcc_hi, 0xff00ff
	v_mov_b32_e32 v204, 0xffff8040
	v_mov_b32_e32 v205, 0x8040
	v_cndmask_b32_e64 v204, v204, 0, vcc
	v_cndmask_b32_e64 v205, 0, v205, vcc
	v_add_u32_e32 v204, v204, v207
	v_add_u32_e32 v205, v205, v207
	s_mov_b32 exec_lo, 0xff00ff00
	s_mov_b32 exec_hi, 0xff00ff00
	v_swap_b32 v44, v248
	v_swap_b32 v45, v249
	v_swap_b32 v46, v250
	v_swap_b32 v47, v251
	v_swap_b32 v36, v220
	v_swap_b32 v37, v221
	v_swap_b32 v38, v222
	v_swap_b32 v39, v223
	s_mov_b64 exec, -1
	global_store_dwordx4 v204, v[44:47], s[8:9]
	global_store_dwordx4 v204, v[36:39], s[8:9] offset:512
	global_store_dwordx4 v205, v[248:251], s[8:9]
	global_store_dwordx4 v205, v[220:223], s[8:9] offset:512
	v_add_u32_e32 v207, 0x10000, v207
	v_add_u32_e32 v206, 0x10000, v206
	global_load_dwordx4 v[248:251], v206, s[70:71] offset:64
	global_load_dwordx4 v[220:223], v206, s[70:71] offset:576
	global_load_dwordx4 v[244:247], v206, s[70:71]
	global_load_dwordx4 v[216:219], v206, s[70:71] offset:512
	s_waitcnt lgkmcnt(0)
	v_add_f32_e32 v211, v210, v211
	ds_bpermute_b32 v212, v215, v211
	v_add_u32_e32 v208, 0x8000, v208
	s_waitcnt lgkmcnt(0)
	v_add_f32_e32 v211, v211, v212
	s_mov_b64 exec, 0xffff
	global_store_dword v209, v211, s[72:73]
	s_mov_b64 exec, -1
	v_add_u32_e32 v209, 0x400, v209
	s_waitcnt vmcnt(10)
	v_permlane32_swap_b32_e32 v228, v232
	v_permlane32_swap_b32_e32 v229, v233
	v_permlane32_swap_b32_e32 v230, v234
	v_permlane32_swap_b32_e32 v231, v235
	v_permlane32_swap_b32_e32 v236, v240
	v_permlane32_swap_b32_e32 v237, v241
	v_permlane32_swap_b32_e32 v238, v242
	v_permlane32_swap_b32_e32 v239, v243
	v_permlane16_swap_b32_e32 v228, v232
	v_permlane16_swap_b32_e32 v229, v233
	v_permlane16_swap_b32_e32 v230, v234
	v_permlane16_swap_b32_e32 v231, v235
	v_permlane16_swap_b32_e32 v236, v240
	v_permlane16_swap_b32_e32 v237, v241
	v_permlane16_swap_b32_e32 v238, v242
	v_permlane16_swap_b32_e32 v239, v243
	v_pk_fma_f32 v[28:29], v[28:29], v[80:81], v[228:229]
	v_pk_fma_f32 v[30:31], v[30:31], v[82:83], v[230:231]
	v_mul_f32_e32 v210, v29, v29
	v_fmac_f32_e32 v210, v28, v28
	v_fmac_f32_e32 v210, v30, v30
	v_fmac_f32_e32 v210, v31, v31
	v_pk_fma_f32 v[24:25], v[24:25], v[88:89], v[232:233]
	v_pk_fma_f32 v[26:27], v[26:27], v[90:91], v[234:235]
	v_fmac_f32_e32 v210, v24, v24
	v_fmac_f32_e32 v210, v25, v25
	v_fmac_f32_e32 v210, v26, v26
	v_fmac_f32_e32 v210, v27, v27
	v_pk_fma_f32 v[20:21], v[20:21], v[84:85], v[236:237]
	v_pk_fma_f32 v[22:23], v[22:23], v[86:87], v[238:239]
	v_fmac_f32_e32 v210, v20, v20
	v_fmac_f32_e32 v210, v21, v21
	v_fmac_f32_e32 v210, v22, v22
	v_fmac_f32_e32 v210, v23, v23
	v_pk_fma_f32 v[16:17], v[16:17], v[92:93], v[240:241]
	v_pk_fma_f32 v[18:19], v[18:19], v[94:95], v[242:243]
	v_fmac_f32_e32 v210, v16, v16
	v_fmac_f32_e32 v210, v17, v17
	v_fmac_f32_e32 v210, v18, v18
	v_fmac_f32_e32 v210, v19, v19
	s_cmp_lg_u64 s[2:3], 0
	s_cbranch_scc1 .Lnoap_C_7
	v_pk_mul_f32 v[228:229], v[64:65], v[28:29]
	v_pk_mul_f32 v[230:231], v[66:67], v[30:31]
	v_pk_mul_f32 v[232:233], v[72:73], v[24:25]
	v_pk_mul_f32 v[234:235], v[74:75], v[26:27]
	v_pk_mul_f32 v[236:237], v[68:69], v[20:21]
	v_pk_mul_f32 v[238:239], v[70:71], v[22:23]
	v_pk_mul_f32 v[240:241], v[76:77], v[16:17]
	v_pk_mul_f32 v[242:243], v[78:79], v[18:19]
	v_cvt_pk_bf16_f32 v228, v228, v229
	v_cvt_pk_bf16_f32 v229, v230, v231
	v_cvt_pk_bf16_f32 v230, v232, v233
	v_cvt_pk_bf16_f32 v231, v234, v235
	global_store_dwordx4 v208, v[228:231], s[42:43]
	v_cvt_pk_bf16_f32 v236, v236, v237
	v_cvt_pk_bf16_f32 v237, v238, v239
	v_cvt_pk_bf16_f32 v238, v240, v241
	v_cvt_pk_bf16_f32 v239, v242, v243
	global_store_dwordx4 v208, v[236:239], s[42:43] offset:256
; DI u32x4 pack8(const float* v) { u32x4 w; w.x = pk2(v[0], v[1]); w.y = pk2(v[2], v[3]); w.z = pk2(v[4], v[5]); w.w = pk2(v[6], v[7]); return w; }
; #define xor16_32(s) xor16_32_l((s), fr + 16 * fq)
; #define PG8_BAR __builtin_amdgcn_s_barrier()
; template <class Epi, bool ALIGN_EPI, bool SP2>
; DI void gemm_phase(int g_wave, LAS unsigned char* lds, const Gemm g, const StaticOrder& S, const Epi& E) {
;     ...
;         if (!has_next) break;
; #pragma unroll
;         for (int a = 0; a < 2; ++a)
; #pragma unroll
;             for (int b = 0; b < 2; ++b)
; #pragma unroll
;                 for (int m = 0; m < 4; ++m)
; #pragma unroll
;                     for (int n = 0; n < 2; ++n) acc[a][b][m][n] = (f32x4){0.f, 0.f, 0.f, 0.f};
;         cur = nxt; cA = nA; cB = nB; ++ui;
;         if constexpr (ALIGN_EPI) { if (wr == 1) PG8_BAR; }
;     DI void operator()(AccRef acc, const Unit& u, int wr, int wc, int fr, int fq) const {
;     ...
;                 float s = 0.f;
; #pragma unroll
;                 for (int bj = 0; bj < 2; ++bj) {
;                     const int c = u.pn * 256 + bj * 128 + cl;
;                     float v[8];
; #pragma unroll
;                     for (int n = 0; n < 2; ++n) {
;                         const f32x4 x = *(const f32x4*)(xi + c + 4 * n);
;                         const f32x4 y = x + gt[bj][n] * acc[ai][bj][m][n];
;                         *(f32x4*)(xout + (size_t)row * 1024 + c + 4 * n) = y;
; #pragma unroll
;                         for (int j = 0; j < 4; ++j) { s += y[j] * y[j]; v[4 * n + j] = ap ? y[j] * gs[bj][n][j] : 0.f; }
;                     }
;                     if (ap) *(u32x4*)(ap + (size_t)row * 1024 + c) = pack8(v);
;                 }
;                 s = xor16_32(s);
;                 if (fq == 0) ssq[(size_t)row * 16 + u.pn * 4 + wc] = s;
.Lnoap_C_7:
	ds_bpermute_b32 v211, v214, v210
	v_permlane16_swap_b32_e32 v28, v24
	v_permlane16_swap_b32_e32 v29, v25
	v_permlane16_swap_b32_e32 v30, v26
	v_permlane16_swap_b32_e32 v31, v27
	v_permlane16_swap_b32_e32 v20, v16
	v_permlane16_swap_b32_e32 v21, v17
	v_permlane16_swap_b32_e32 v22, v18
	v_permlane16_swap_b32_e32 v23, v19
	v_permlane32_swap_b32_e32 v28, v24
	v_permlane32_swap_b32_e32 v29, v25
	v_permlane32_swap_b32_e32 v30, v26
	v_permlane32_swap_b32_e32 v31, v27
	v_permlane32_swap_b32_e32 v20, v16
	v_permlane32_swap_b32_e32 v21, v17
	v_permlane32_swap_b32_e32 v22, v18
	v_permlane32_swap_b32_e32 v23, v19
	s_nop 1
	v_mov_b32_dpp v232, v24 row_ror:8 row_mask:0xf bank_mask:0xf
	v_mov_b32_dpp v233, v25 row_ror:8 row_mask:0xf bank_mask:0xf
	v_mov_b32_dpp v234, v26 row_ror:8 row_mask:0xf bank_mask:0xf
	v_mov_b32_dpp v235, v27 row_ror:8 row_mask:0xf bank_mask:0xf
	v_mov_b32_dpp v240, v16 row_ror:8 row_mask:0xf bank_mask:0xf
	v_mov_b32_dpp v241, v17 row_ror:8 row_mask:0xf bank_mask:0xf
	v_mov_b32_dpp v242, v18 row_ror:8 row_mask:0xf bank_mask:0xf
	v_mov_b32_dpp v243, v19 row_ror:8 row_mask:0xf bank_mask:0xf
	s_mov_b32 vcc_lo, 0xff00ff
	s_mov_b32 vcc_hi, 0xff00ff
	v_mov_b32_e32 v204, 0xffff8040
	v_mov_b32_e32 v205, 0x8040
	v_cndmask_b32_e64 v204, v204, 0, vcc
	v_cndmask_b32_e64 v205, 0, v205, vcc
	v_add_u32_e32 v204, v204, v207
	v_add_u32_e32 v205, v205, v207
	s_mov_b32 exec_lo, 0xff00ff00
	s_mov_b32 exec_hi, 0xff00ff00
	v_swap_b32 v28, v232
	v_swap_b32 v29, v233
	v_swap_b32 v30, v234
	v_swap_b32 v31, v235
	v_swap_b32 v20, v240
	v_swap_b32 v21, v241
	v_swap_b32 v22, v242
	v_swap_b32 v23, v243
	s_mov_b64 exec, -1
	global_store_dwordx4 v204, v[28:31], s[8:9]
	global_store_dwordx4 v204, v[20:23], s[8:9] offset:512
	global_store_dwordx4 v205, v[232:235], s[8:9]
	global_store_dwordx4 v205, v[240:243], s[8:9] offset:512
	v_add_u32_e32 v207, 0x10000, v207
	s_waitcnt lgkmcnt(0)
	v_add_f32_e32 v211, v210, v211
	ds_bpermute_b32 v212, v215, v211
	v_add_u32_e32 v208, 0x8000, v208
	s_waitcnt lgkmcnt(0)
	v_add_f32_e32 v211, v211, v212
	s_mov_b64 exec, 0xffff
	global_store_dword v209, v211, s[72:73]
	s_mov_b64 exec, -1
	v_add_u32_e32 v209, 0x400, v209
	s_waitcnt vmcnt(6)
	v_permlane32_swap_b32_e32 v244, v248
	v_permlane32_swap_b32_e32 v245, v249
	v_permlane32_swap_b32_e32 v246, v250
	v_permlane32_swap_b32_e32 v247, v251
	v_permlane32_swap_b32_e32 v216, v220
	v_permlane32_swap_b32_e32 v217, v221
	v_permlane32_swap_b32_e32 v218, v222
	v_permlane32_swap_b32_e32 v219, v223
	v_permlane16_swap_b32_e32 v244, v248
	v_permlane16_swap_b32_e32 v245, v249
	v_permlane16_swap_b32_e32 v246, v250
	v_permlane16_swap_b32_e32 v247, v251
	v_permlane16_swap_b32_e32 v216, v220
	v_permlane16_swap_b32_e32 v217, v221
	v_permlane16_swap_b32_e32 v218, v222
	v_permlane16_swap_b32_e32 v219, v223
	v_pk_fma_f32 v[12:13], v[12:13], v[80:81], v[244:245]
	v_pk_fma_f32 v[14:15], v[14:15], v[82:83], v[246:247]
	v_mul_f32_e32 v210, v13, v13
	v_fmac_f32_e32 v210, v12, v12
	v_fmac_f32_e32 v210, v14, v14
	v_fmac_f32_e32 v210, v15, v15
	v_pk_fma_f32 v[8:9], v[8:9], v[88:89], v[248:249]
	v_pk_fma_f32 v[10:11], v[10:11], v[90:91], v[250:251]
	v_fmac_f32_e32 v210, v8, v8
	v_fmac_f32_e32 v210, v9, v9
	v_fmac_f32_e32 v210, v10, v10
	v_fmac_f32_e32 v210, v11, v11
	v_pk_fma_f32 v[4:5], v[4:5], v[84:85], v[216:217]
	v_pk_fma_f32 v[6:7], v[6:7], v[86:87], v[218:219]
	v_fmac_f32_e32 v210, v4, v4
	v_fmac_f32_e32 v210, v5, v5
	v_fmac_f32_e32 v210, v6, v6
	v_fmac_f32_e32 v210, v7, v7
	v_pk_fma_f32 v[0:1], v[0:1], v[92:93], v[220:221]
	v_pk_fma_f32 v[2:3], v[2:3], v[94:95], v[222:223]
	v_fmac_f32_e32 v210, v0, v0
	v_fmac_f32_e32 v210, v1, v1
	v_fmac_f32_e32 v210, v2, v2
	v_fmac_f32_e32 v210, v3, v3
	s_cmp_lg_u64 s[2:3], 0
	s_cbranch_scc1 .Lnoap_C_8
	v_pk_mul_f32 v[244:245], v[64:65], v[12:13]
	v_pk_mul_f32 v[246:247], v[66:67], v[14:15]
	v_pk_mul_f32 v[248:249], v[72:73], v[8:9]
	v_pk_mul_f32 v[250:251], v[74:75], v[10:11]
	v_pk_mul_f32 v[216:217], v[68:69], v[4:5]
	v_pk_mul_f32 v[218:219], v[70:71], v[6:7]
	v_pk_mul_f32 v[220:221], v[76:77], v[0:1]
	v_pk_mul_f32 v[222:223], v[78:79], v[2:3]
	v_cvt_pk_bf16_f32 v244, v244, v245
	v_cvt_pk_bf16_f32 v245, v246, v247
	v_cvt_pk_bf16_f32 v246, v248, v249
	v_cvt_pk_bf16_f32 v247, v250, v251
	global_store_dwordx4 v208, v[244:247], s[42:43]
	v_cvt_pk_bf16_f32 v216, v216, v217
	v_cvt_pk_bf16_f32 v217, v218, v219
	v_cvt_pk_bf16_f32 v218, v220, v221
	v_cvt_pk_bf16_f32 v219, v222, v223
	global_store_dwordx4 v208, v[216:219], s[42:43] offset:256
.Lnoap_C_8:
	ds_bpermute_b32 v211, v214, v210
	v_permlane16_swap_b32_e32 v12, v8
	v_permlane16_swap_b32_e32 v13, v9
	v_permlane16_swap_b32_e32 v14, v10
	v_permlane16_swap_b32_e32 v15, v11
	v_permlane16_swap_b32_e32 v4, v0
	v_permlane16_swap_b32_e32 v5, v1
	v_permlane16_swap_b32_e32 v6, v2
	v_permlane16_swap_b32_e32 v7, v3
	v_permlane32_swap_b32_e32 v12, v8
	v_permlane32_swap_b32_e32 v13, v9
	v_permlane32_swap_b32_e32 v14, v10
	v_permlane32_swap_b32_e32 v15, v11
	v_permlane32_swap_b32_e32 v4, v0
	v_permlane32_swap_b32_e32 v5, v1
	v_permlane32_swap_b32_e32 v6, v2
	v_permlane32_swap_b32_e32 v7, v3
	s_nop 1
	v_mov_b32_dpp v248, v8 row_ror:8 row_mask:0xf bank_mask:0xf
	v_mov_b32_dpp v249, v9 row_ror:8 row_mask:0xf bank_mask:0xf
	v_mov_b32_dpp v250, v10 row_ror:8 row_mask:0xf bank_mask:0xf
	v_mov_b32_dpp v251, v11 row_ror:8 row_mask:0xf bank_mask:0xf
	v_mov_b32_dpp v220, v0 row_ror:8 row_mask:0xf bank_mask:0xf
	v_mov_b32_dpp v221, v1 row_ror:8 row_mask:0xf bank_mask:0xf
	v_mov_b32_dpp v222, v2 row_ror:8 row_mask:0xf bank_mask:0xf
	v_mov_b32_dpp v223, v3 row_ror:8 row_mask:0xf bank_mask:0xf
	s_mov_b32 vcc_lo, 0xff00ff
	s_mov_b32 vcc_hi, 0xff00ff
	v_mov_b32_e32 v204, 0xffff8040
	v_mov_b32_e32 v205, 0x8040
	v_cndmask_b32_e64 v204, v204, 0, vcc
	v_cndmask_b32_e64 v205, 0, v205, vcc
	v_add_u32_e32 v204, v204, v207
	v_add_u32_e32 v205, v205, v207
	s_mov_b32 exec_lo, 0xff00ff00
	s_mov_b32 exec_hi, 0xff00ff00
	v_swap_b32 v12, v248
	v_swap_b32 v13, v249
	v_swap_b32 v14, v250
	v_swap_b32 v15, v251
	v_swap_b32 v4, v220
	v_swap_b32 v5, v221
	v_swap_b32 v6, v222
	v_swap_b32 v7, v223
	s_mov_b64 exec, -1
	global_store_dwordx4 v204, v[12:15], s[8:9]
	global_store_dwordx4 v204, v[4:7], s[8:9] offset:512
	global_store_dwordx4 v205, v[248:251], s[8:9]
	global_store_dwordx4 v205, v[220:223], s[8:9] offset:512
	s_waitcnt lgkmcnt(0)
	v_add_f32_e32 v211, v210, v211
	ds_bpermute_b32 v212, v215, v211
	s_waitcnt lgkmcnt(0)
	v_add_f32_e32 v211, v211, v212
	s_mov_b64 exec, 0xffff
	global_store_dword v209, v211, s[72:73]
	s_mov_b64 exec, -1
	s_and_b64 vcc, exec, s[0:1]
	s_mov_b64 s[0:1], -1
	s_cbranch_vccnz .LBB0_1500
	s_andn2_b64 vcc, exec, s[16:17]
	s_cbranch_vccnz .LBB0_1499
	s_barrier
	s_branch .LBB0_1499

; DI u32x4 pack8(const float* v) { u32x4 w; w.x = pk2(v[0], v[1]); w.y = pk2(v[2], v[3]); w.z = pk2(v[4], v[5]); w.w = pk2(v[6], v[7]); return w; }
; #define xor16_32(s) xor16_32_l((s), fr + 16 * fq)
;     DI void operator()(AccRef acc, const Unit& u, int wr, int wc, int fr, int fq) const {
;     ...
;                 float s = 0.f;
; #pragma unroll
;                 for (int bj = 0; bj < 2; ++bj) {
;                     const int c = u.pn * 256 + bj * 128 + cl;
;                     float v[8];
; #pragma unroll
;                     for (int n = 0; n < 2; ++n) {
;                         const f32x4 x = *(const f32x4*)(xi + c + 4 * n);
;                         const f32x4 y = x + gt[bj][n] * acc[ai][bj][m][n];
;                         *(f32x4*)(xout + (size_t)row * 1024 + c + 4 * n) = y;
; #pragma unroll
;                         for (int j = 0; j < 4; ++j) { s += y[j] * y[j]; v[4 * n + j] = ap ? y[j] * gs[bj][n][j] : 0.f; }
;                     }
;                     if (ap) *(u32x4*)(ap + (size_t)row * 1024 + c) = pack8(v);
;                 }
;                 s = xor16_32(s);
;                 if (fq == 0) ssq[(size_t)row * 16 + u.pn * 4 + wc] = s;
.Lnoap_D_1:
	ds_bpermute_b32 v211, v214, v210
	v_permlane16_swap_b32_e32 v140, v136
	v_permlane16_swap_b32_e32 v141, v137
	v_permlane16_swap_b32_e32 v142, v138
	v_permlane16_swap_b32_e32 v143, v139
	v_permlane16_swap_b32_e32 v132, v128
	v_permlane16_swap_b32_e32 v133, v129
	v_permlane16_swap_b32_e32 v134, v130
	v_permlane16_swap_b32_e32 v135, v131
	v_permlane32_swap_b32_e32 v140, v136
	v_permlane32_swap_b32_e32 v141, v137
	v_permlane32_swap_b32_e32 v142, v138
	v_permlane32_swap_b32_e32 v143, v139
	v_permlane32_swap_b32_e32 v132, v128
	v_permlane32_swap_b32_e32 v133, v129
	v_permlane32_swap_b32_e32 v134, v130
	v_permlane32_swap_b32_e32 v135, v131
	s_nop 1
	v_mov_b32_dpp v232, v136 row_ror:8 row_mask:0xf bank_mask:0xf
	v_mov_b32_dpp v233, v137 row_ror:8 row_mask:0xf bank_mask:0xf
	v_mov_b32_dpp v234, v138 row_ror:8 row_mask:0xf bank_mask:0xf
	v_mov_b32_dpp v235, v139 row_ror:8 row_mask:0xf bank_mask:0xf
	v_mov_b32_dpp v240, v128 row_ror:8 row_mask:0xf bank_mask:0xf
	v_mov_b32_dpp v241, v129 row_ror:8 row_mask:0xf bank_mask:0xf
	v_mov_b32_dpp v242, v130 row_ror:8 row_mask:0xf bank_mask:0xf
	v_mov_b32_dpp v243, v131 row_ror:8 row_mask:0xf bank_mask:0xf
	s_mov_b32 vcc_lo, 0xff00ff
	s_mov_b32 vcc_hi, 0xff00ff
	v_mov_b32_e32 v204, 0xffff8040
	v_mov_b32_e32 v205, 0x8040
	v_cndmask_b32_e64 v204, v204, 0, vcc
	v_cndmask_b32_e64 v205, 0, v205, vcc
	v_add_u32_e32 v204, v204, v207
	v_add_u32_e32 v205, v205, v207
	s_mov_b32 exec_lo, 0xff00ff00
	s_mov_b32 exec_hi, 0xff00ff00
	v_swap_b32 v140, v232
	v_swap_b32 v141, v233
	v_swap_b32 v142, v234
	v_swap_b32 v143, v235
	v_swap_b32 v132, v240
	v_swap_b32 v133, v241
	v_swap_b32 v134, v242
	v_swap_b32 v135, v243
	s_mov_b64 exec, -1
	global_store_dwordx4 v204, v[140:143], s[84:85]
	global_store_dwordx4 v204, v[132:135], s[84:85] offset:512
	global_store_dwordx4 v205, v[232:235], s[84:85]
	global_store_dwordx4 v205, v[240:243], s[84:85] offset:512
	v_add_u32_e32 v207, 0x10000, v207
	global_load_dwordx4 v[232:235], v206, s[70:71] offset:64
	global_load_dwordx4 v[240:243], v206, s[70:71] offset:576
	global_load_dwordx4 v[228:231], v206, s[70:71]
	global_load_dwordx4 v[236:239], v206, s[70:71] offset:512
	s_waitcnt lgkmcnt(0)
	v_add_f32_e32 v211, v210, v211
	ds_bpermute_b32 v212, v215, v211
	v_add_u32_e32 v208, 0x8000, v208
	s_waitcnt lgkmcnt(0)
	v_add_f32_e32 v211, v211, v212
	s_mov_b64 exec, 0xffff
	global_store_dword v209, v211, s[72:73]
	s_mov_b64 exec, -1
	v_add_u32_e32 v209, 0x400, v209
	s_waitcnt vmcnt(9)
	v_permlane32_swap_b32_e32 v244, v248
	v_permlane32_swap_b32_e32 v245, v249
	v_permlane32_swap_b32_e32 v246, v250
	v_permlane32_swap_b32_e32 v247, v251
	v_permlane32_swap_b32_e32 v216, v220
	v_permlane32_swap_b32_e32 v217, v221
	v_permlane32_swap_b32_e32 v218, v222
	v_permlane32_swap_b32_e32 v219, v223
	v_permlane16_swap_b32_e32 v244, v248
	v_permlane16_swap_b32_e32 v245, v249
	v_permlane16_swap_b32_e32 v246, v250
	v_permlane16_swap_b32_e32 v247, v251
	v_permlane16_swap_b32_e32 v216, v220
	v_permlane16_swap_b32_e32 v217, v221
	v_permlane16_swap_b32_e32 v218, v222
	v_permlane16_swap_b32_e32 v219, v223
	v_pk_fma_f32 v[124:125], v[124:125], v[144:145], v[244:245]
	v_pk_fma_f32 v[126:127], v[126:127], v[146:147], v[246:247]
	v_mul_f32_e32 v210, v125, v125
	v_fmac_f32_e32 v210, v124, v124
	v_fmac_f32_e32 v210, v126, v126
	v_fmac_f32_e32 v210, v127, v127
	v_pk_fma_f32 v[120:121], v[120:121], v[152:153], v[248:249]
	v_pk_fma_f32 v[122:123], v[122:123], v[154:155], v[250:251]
	v_fmac_f32_e32 v210, v120, v120
	v_fmac_f32_e32 v210, v121, v121
	v_fmac_f32_e32 v210, v122, v122
	v_fmac_f32_e32 v210, v123, v123
	v_pk_fma_f32 v[116:117], v[116:117], v[148:149], v[216:217]
	v_pk_fma_f32 v[118:119], v[118:119], v[150:151], v[218:219]
	v_fmac_f32_e32 v210, v116, v116
	v_fmac_f32_e32 v210, v117, v117
	v_fmac_f32_e32 v210, v118, v118
	v_fmac_f32_e32 v210, v119, v119
	v_pk_fma_f32 v[112:113], v[112:113], v[156:157], v[220:221]
	v_pk_fma_f32 v[114:115], v[114:115], v[158:159], v[222:223]
	v_fmac_f32_e32 v210, v112, v112
	v_fmac_f32_e32 v210, v113, v113
	v_fmac_f32_e32 v210, v114, v114
	v_fmac_f32_e32 v210, v115, v115
	s_cmp_lg_u64 s[0:1], 0
	s_cbranch_scc1 .Lnoap_D_2
	v_pk_mul_f32 v[244:245], v[64:65], v[124:125]
	v_pk_mul_f32 v[246:247], v[66:67], v[126:127]
	v_pk_mul_f32 v[248:249], v[72:73], v[120:121]
	v_pk_mul_f32 v[250:251], v[74:75], v[122:123]
	v_pk_mul_f32 v[216:217], v[68:69], v[116:117]
	v_pk_mul_f32 v[218:219], v[70:71], v[118:119]
	v_pk_mul_f32 v[220:221], v[76:77], v[112:113]
	v_pk_mul_f32 v[222:223], v[78:79], v[114:115]
	v_cvt_pk_bf16_f32 v244, v244, v245
	v_cvt_pk_bf16_f32 v245, v246, v247
	v_cvt_pk_bf16_f32 v246, v248, v249
	v_cvt_pk_bf16_f32 v247, v250, v251
	global_store_dwordx4 v208, v[244:247], s[28:29]
	v_cvt_pk_bf16_f32 v216, v216, v217
	v_cvt_pk_bf16_f32 v217, v218, v219
	v_cvt_pk_bf16_f32 v218, v220, v221
	v_cvt_pk_bf16_f32 v219, v222, v223
	global_store_dwordx4 v208, v[216:219], s[28:29] offset:256
; DI u32x4 pack8(const float* v) { u32x4 w; w.x = pk2(v[0], v[1]); w.y = pk2(v[2], v[3]); w.z = pk2(v[4], v[5]); w.w = pk2(v[6], v[7]); return w; }
; #define xor16_32(s) xor16_32_l((s), fr + 16 * fq)
;     DI void operator()(AccRef acc, const Unit& u, int wr, int wc, int fr, int fq) const {
;     ...
;                 float s = 0.f;
; #pragma unroll
;                 for (int bj = 0; bj < 2; ++bj) {
;                     const int c = u.pn * 256 + bj * 128 + cl;
;                     float v[8];
; #pragma unroll
;                     for (int n = 0; n < 2; ++n) {
;                         const f32x4 x = *(const f32x4*)(xi + c + 4 * n);
;                         const f32x4 y = x + gt[bj][n] * acc[ai][bj][m][n];
;                         *(f32x4*)(xout + (size_t)row * 1024 + c + 4 * n) = y;
; #pragma unroll
;                         for (int j = 0; j < 4; ++j) { s += y[j] * y[j]; v[4 * n + j] = ap ? y[j] * gs[bj][n][j] : 0.f; }
;                     }
;                     if (ap) *(u32x4*)(ap + (size_t)row * 1024 + c) = pack8(v);
;                 }
;                 s = xor16_32(s);
;                 if (fq == 0) ssq[(size_t)row * 16 + u.pn * 4 + wc] = s;
.Lnoap_D_2:
	ds_bpermute_b32 v211, v214, v210
	v_permlane16_swap_b32_e32 v124, v120
	v_permlane16_swap_b32_e32 v125, v121
	v_permlane16_swap_b32_e32 v126, v122
	v_permlane16_swap_b32_e32 v127, v123
	v_permlane16_swap_b32_e32 v116, v112
	v_permlane16_swap_b32_e32 v117, v113
	v_permlane16_swap_b32_e32 v118, v114
	v_permlane16_swap_b32_e32 v119, v115
	v_permlane32_swap_b32_e32 v124, v120
	v_permlane32_swap_b32_e32 v125, v121
	v_permlane32_swap_b32_e32 v126, v122
	v_permlane32_swap_b32_e32 v127, v123
	v_permlane32_swap_b32_e32 v116, v112
	v_permlane32_swap_b32_e32 v117, v113
	v_permlane32_swap_b32_e32 v118, v114
	v_permlane32_swap_b32_e32 v119, v115
	s_nop 1
	v_mov_b32_dpp v248, v120 row_ror:8 row_mask:0xf bank_mask:0xf
	v_mov_b32_dpp v249, v121 row_ror:8 row_mask:0xf bank_mask:0xf
	v_mov_b32_dpp v250, v122 row_ror:8 row_mask:0xf bank_mask:0xf
	v_mov_b32_dpp v251, v123 row_ror:8 row_mask:0xf bank_mask:0xf
	v_mov_b32_dpp v220, v112 row_ror:8 row_mask:0xf bank_mask:0xf
	v_mov_b32_dpp v221, v113 row_ror:8 row_mask:0xf bank_mask:0xf
	v_mov_b32_dpp v222, v114 row_ror:8 row_mask:0xf bank_mask:0xf
	v_mov_b32_dpp v223, v115 row_ror:8 row_mask:0xf bank_mask:0xf
	s_mov_b32 vcc_lo, 0xff00ff
	s_mov_b32 vcc_hi, 0xff00ff
	v_mov_b32_e32 v204, 0xffff8040
	v_mov_b32_e32 v205, 0x8040
	v_cndmask_b32_e64 v204, v204, 0, vcc
	v_cndmask_b32_e64 v205, 0, v205, vcc
	v_add_u32_e32 v204, v204, v207
	v_add_u32_e32 v205, v205, v207
	s_mov_b32 exec_lo, 0xff00ff00
	s_mov_b32 exec_hi, 0xff00ff00
	v_swap_b32 v124, v248
	v_swap_b32 v125, v249
	v_swap_b32 v126, v250
	v_swap_b32 v127, v251
	v_swap_b32 v116, v220
	v_swap_b32 v117, v221
	v_swap_b32 v118, v222
	v_swap_b32 v119, v223
	s_mov_b64 exec, -1
	global_store_dwordx4 v204, v[124:127], s[84:85]
	global_store_dwordx4 v204, v[116:119], s[84:85] offset:512
	global_store_dwordx4 v205, v[248:251], s[84:85]
	global_store_dwordx4 v205, v[220:223], s[84:85] offset:512
	v_add_u32_e32 v207, 0x10000, v207
	v_add_u32_e32 v206, 0x10000, v206
	global_load_dwordx4 v[248:251], v206, s[70:71] offset:64
	global_load_dwordx4 v[220:223], v206, s[70:71] offset:576
	global_load_dwordx4 v[244:247], v206, s[70:71]
	global_load_dwordx4 v[216:219], v206, s[70:71] offset:512
	s_waitcnt lgkmcnt(0)
	v_add_f32_e32 v211, v210, v211
	ds_bpermute_b32 v212, v215, v211
	v_add_u32_e32 v208, 0x8000, v208
	s_waitcnt lgkmcnt(0)
	v_add_f32_e32 v211, v211, v212
	s_mov_b64 exec, 0xffff
	global_store_dword v209, v211, s[72:73]
	s_mov_b64 exec, -1
	v_add_u32_e32 v209, 0x400, v209
	s_waitcnt vmcnt(10)
	v_permlane32_swap_b32_e32 v228, v232
	v_permlane32_swap_b32_e32 v229, v233
	v_permlane32_swap_b32_e32 v230, v234
	v_permlane32_swap_b32_e32 v231, v235
	v_permlane32_swap_b32_e32 v236, v240
	v_permlane32_swap_b32_e32 v237, v241
	v_permlane32_swap_b32_e32 v238, v242
	v_permlane32_swap_b32_e32 v239, v243
	v_permlane16_swap_b32_e32 v228, v232
	v_permlane16_swap_b32_e32 v229, v233
	v_permlane16_swap_b32_e32 v230, v234
	v_permlane16_swap_b32_e32 v231, v235
	v_permlane16_swap_b32_e32 v236, v240
	v_permlane16_swap_b32_e32 v237, v241
	v_permlane16_swap_b32_e32 v238, v242
	v_permlane16_swap_b32_e32 v239, v243
	v_pk_fma_f32 v[108:109], v[108:109], v[144:145], v[228:229]
	v_pk_fma_f32 v[110:111], v[110:111], v[146:147], v[230:231]
	v_mul_f32_e32 v210, v109, v109
	v_fmac_f32_e32 v210, v108, v108
	v_fmac_f32_e32 v210, v110, v110
	v_fmac_f32_e32 v210, v111, v111
	v_pk_fma_f32 v[104:105], v[104:105], v[152:153], v[232:233]
	v_pk_fma_f32 v[106:107], v[106:107], v[154:155], v[234:235]
	v_fmac_f32_e32 v210, v104, v104
	v_fmac_f32_e32 v210, v105, v105
	v_fmac_f32_e32 v210, v106, v106
	v_fmac_f32_e32 v210, v107, v107
	v_pk_fma_f32 v[100:101], v[100:101], v[148:149], v[236:237]
	v_pk_fma_f32 v[102:103], v[102:103], v[150:151], v[238:239]
	v_fmac_f32_e32 v210, v100, v100
	v_fmac_f32_e32 v210, v101, v101
	v_fmac_f32_e32 v210, v102, v102
	v_fmac_f32_e32 v210, v103, v103
	v_pk_fma_f32 v[96:97], v[96:97], v[156:157], v[240:241]
	v_pk_fma_f32 v[98:99], v[98:99], v[158:159], v[242:243]
	v_fmac_f32_e32 v210, v96, v96
	v_fmac_f32_e32 v210, v97, v97
	v_fmac_f32_e32 v210, v98, v98
	v_fmac_f32_e32 v210, v99, v99
	s_cmp_lg_u64 s[0:1], 0
	s_cbranch_scc1 .Lnoap_D_3
	v_pk_mul_f32 v[228:229], v[64:65], v[108:109]
	v_pk_mul_f32 v[230:231], v[66:67], v[110:111]
	v_pk_mul_f32 v[232:233], v[72:73], v[104:105]
	v_pk_mul_f32 v[234:235], v[74:75], v[106:107]
	v_pk_mul_f32 v[236:237], v[68:69], v[100:101]
	v_pk_mul_f32 v[238:239], v[70:71], v[102:103]
	v_pk_mul_f32 v[240:241], v[76:77], v[96:97]
	v_pk_mul_f32 v[242:243], v[78:79], v[98:99]
	v_cvt_pk_bf16_f32 v228, v228, v229
	v_cvt_pk_bf16_f32 v229, v230, v231
	v_cvt_pk_bf16_f32 v230, v232, v233
	v_cvt_pk_bf16_f32 v231, v234, v235
	global_store_dwordx4 v208, v[228:231], s[28:29]
	v_cvt_pk_bf16_f32 v236, v236, v237
	v_cvt_pk_bf16_f32 v237, v238, v239
	v_cvt_pk_bf16_f32 v238, v240, v241
	v_cvt_pk_bf16_f32 v239, v242, v243
	global_store_dwordx4 v208, v[236:239], s[28:29] offset:256
; DI u32x4 pack8(const float* v) { u32x4 w; w.x = pk2(v[0], v[1]); w.y = pk2(v[2], v[3]); w.z = pk2(v[4], v[5]); w.w = pk2(v[6], v[7]); return w; }
; #define xor16_32(s) xor16_32_l((s), fr + 16 * fq)
;     DI void operator()(AccRef acc, const Unit& u, int wr, int wc, int fr, int fq) const {
;     ...
;                 float s = 0.f;
; #pragma unroll
;                 for (int bj = 0; bj < 2; ++bj) {
;                     const int c = u.pn * 256 + bj * 128 + cl;
;                     float v[8];
; #pragma unroll
;                     for (int n = 0; n < 2; ++n) {
;                         const f32x4 x = *(const f32x4*)(xi + c + 4 * n);
;                         const f32x4 y = x + gt[bj][n] * acc[ai][bj][m][n];
;                         *(f32x4*)(xout + (size_t)row * 1024 + c + 4 * n) = y;
; #pragma unroll
;                         for (int j = 0; j < 4; ++j) { s += y[j] * y[j]; v[4 * n + j] = ap ? y[j] * gs[bj][n][j] : 0.f; }
;                     }
;                     if (ap) *(u32x4*)(ap + (size_t)row * 1024 + c) = pack8(v);
;                 }
;                 s = xor16_32(s);
;                 if (fq == 0) ssq[(size_t)row * 16 + u.pn * 4 + wc] = s;
.Lnoap_D_3:
	ds_bpermute_b32 v211, v214, v210
	v_permlane16_swap_b32_e32 v108, v104
	v_permlane16_swap_b32_e32 v109, v105
	v_permlane16_swap_b32_e32 v110, v106
	v_permlane16_swap_b32_e32 v111, v107
	v_permlane16_swap_b32_e32 v100, v96
	v_permlane16_swap_b32_e32 v101, v97
	v_permlane16_swap_b32_e32 v102, v98
	v_permlane16_swap_b32_e32 v103, v99
	v_permlane32_swap_b32_e32 v108, v104
	v_permlane32_swap_b32_e32 v109, v105
	v_permlane32_swap_b32_e32 v110, v106
	v_permlane32_swap_b32_e32 v111, v107
	v_permlane32_swap_b32_e32 v100, v96
	v_permlane32_swap_b32_e32 v101, v97
	v_permlane32_swap_b32_e32 v102, v98
	v_permlane32_swap_b32_e32 v103, v99
	s_nop 1
	v_mov_b32_dpp v232, v104 row_ror:8 row_mask:0xf bank_mask:0xf
	v_mov_b32_dpp v233, v105 row_ror:8 row_mask:0xf bank_mask:0xf
	v_mov_b32_dpp v234, v106 row_ror:8 row_mask:0xf bank_mask:0xf
	v_mov_b32_dpp v235, v107 row_ror:8 row_mask:0xf bank_mask:0xf
	v_mov_b32_dpp v240, v96 row_ror:8 row_mask:0xf bank_mask:0xf
	v_mov_b32_dpp v241, v97 row_ror:8 row_mask:0xf bank_mask:0xf
	v_mov_b32_dpp v242, v98 row_ror:8 row_mask:0xf bank_mask:0xf
	v_mov_b32_dpp v243, v99 row_ror:8 row_mask:0xf bank_mask:0xf
	s_mov_b32 vcc_lo, 0xff00ff
	s_mov_b32 vcc_hi, 0xff00ff
	v_mov_b32_e32 v204, 0xffff8040
	v_mov_b32_e32 v205, 0x8040
	v_cndmask_b32_e64 v204, v204, 0, vcc
	v_cndmask_b32_e64 v205, 0, v205, vcc
	v_add_u32_e32 v204, v204, v207
	v_add_u32_e32 v205, v205, v207
	s_mov_b32 exec_lo, 0xff00ff00
	s_mov_b32 exec_hi, 0xff00ff00
	v_swap_b32 v108, v232
	v_swap_b32 v109, v233
	v_swap_b32 v110, v234
	v_swap_b32 v111, v235
	v_swap_b32 v100, v240
	v_swap_b32 v101, v241
	v_swap_b32 v102, v242
	v_swap_b32 v103, v243
	s_mov_b64 exec, -1
	global_store_dwordx4 v204, v[108:111], s[84:85]
	global_store_dwordx4 v204, v[100:103], s[84:85] offset:512
	global_store_dwordx4 v205, v[232:235], s[84:85]
	global_store_dwordx4 v205, v[240:243], s[84:85] offset:512
	v_add_u32_e32 v207, 0x10000, v207
	v_add_u32_e32 v206, 0x50000, v206
	global_load_dwordx4 v[232:235], v206, s[70:71] offset:64
	global_load_dwordx4 v[240:243], v206, s[70:71] offset:576
	global_load_dwordx4 v[228:231], v206, s[70:71]
	global_load_dwordx4 v[236:239], v206, s[70:71] offset:512
	s_waitcnt lgkmcnt(0)
	v_add_f32_e32 v211, v210, v211
	ds_bpermute_b32 v212, v215, v211
	v_add_u32_e32 v208, 0x8000, v208
	s_waitcnt lgkmcnt(0)
	v_add_f32_e32 v211, v211, v212
	s_mov_b64 exec, 0xffff
	global_store_dword v209, v211, s[72:73]
	s_mov_b64 exec, -1
	v_add_u32_e32 v209, 0x400, v209
	s_waitcnt vmcnt(10)
	v_permlane32_swap_b32_e32 v244, v248
	v_permlane32_swap_b32_e32 v245, v249
	v_permlane32_swap_b32_e32 v246, v250
	v_permlane32_swap_b32_e32 v247, v251
	v_permlane32_swap_b32_e32 v216, v220
	v_permlane32_swap_b32_e32 v217, v221
	v_permlane32_swap_b32_e32 v218, v222
	v_permlane32_swap_b32_e32 v219, v223
	v_permlane16_swap_b32_e32 v244, v248
	v_permlane16_swap_b32_e32 v245, v249
	v_permlane16_swap_b32_e32 v246, v250
	v_permlane16_swap_b32_e32 v247, v251
	v_permlane16_swap_b32_e32 v216, v220
	v_permlane16_swap_b32_e32 v217, v221
	v_permlane16_swap_b32_e32 v218, v222
	v_permlane16_swap_b32_e32 v219, v223
	v_pk_fma_f32 v[92:93], v[92:93], v[144:145], v[244:245]
	v_pk_fma_f32 v[94:95], v[94:95], v[146:147], v[246:247]
	v_mul_f32_e32 v210, v93, v93
	v_fmac_f32_e32 v210, v92, v92
	v_fmac_f32_e32 v210, v94, v94
	v_fmac_f32_e32 v210, v95, v95
	v_pk_fma_f32 v[88:89], v[88:89], v[152:153], v[248:249]
	v_pk_fma_f32 v[90:91], v[90:91], v[154:155], v[250:251]
	v_fmac_f32_e32 v210, v88, v88
	v_fmac_f32_e32 v210, v89, v89
	v_fmac_f32_e32 v210, v90, v90
	v_fmac_f32_e32 v210, v91, v91
	v_pk_fma_f32 v[84:85], v[84:85], v[148:149], v[216:217]
	v_pk_fma_f32 v[86:87], v[86:87], v[150:151], v[218:219]
	v_fmac_f32_e32 v210, v84, v84
	v_fmac_f32_e32 v210, v85, v85
	v_fmac_f32_e32 v210, v86, v86
	v_fmac_f32_e32 v210, v87, v87
	v_pk_fma_f32 v[80:81], v[80:81], v[156:157], v[220:221]
	v_pk_fma_f32 v[82:83], v[82:83], v[158:159], v[222:223]
	v_fmac_f32_e32 v210, v80, v80
	v_fmac_f32_e32 v210, v81, v81
	v_fmac_f32_e32 v210, v82, v82
	v_fmac_f32_e32 v210, v83, v83
	s_cmp_lg_u64 s[0:1], 0
	s_cbranch_scc1 .Lnoap_D_4
	v_pk_mul_f32 v[244:245], v[64:65], v[92:93]
	v_pk_mul_f32 v[246:247], v[66:67], v[94:95]
	v_pk_mul_f32 v[248:249], v[72:73], v[88:89]
	v_pk_mul_f32 v[250:251], v[74:75], v[90:91]
	v_pk_mul_f32 v[216:217], v[68:69], v[84:85]
	v_pk_mul_f32 v[218:219], v[70:71], v[86:87]
	v_pk_mul_f32 v[220:221], v[76:77], v[80:81]
	v_pk_mul_f32 v[222:223], v[78:79], v[82:83]
	v_cvt_pk_bf16_f32 v244, v244, v245
	v_cvt_pk_bf16_f32 v245, v246, v247
	v_cvt_pk_bf16_f32 v246, v248, v249
	v_cvt_pk_bf16_f32 v247, v250, v251
	global_store_dwordx4 v208, v[244:247], s[28:29]
	v_cvt_pk_bf16_f32 v216, v216, v217
	v_cvt_pk_bf16_f32 v217, v218, v219
	v_cvt_pk_bf16_f32 v218, v220, v221
	v_cvt_pk_bf16_f32 v219, v222, v223
	global_store_dwordx4 v208, v[216:219], s[28:29] offset:256
; DI u32x4 pack8(const float* v) { u32x4 w; w.x = pk2(v[0], v[1]); w.y = pk2(v[2], v[3]); w.z = pk2(v[4], v[5]); w.w = pk2(v[6], v[7]); return w; }
; #define xor16_32(s) xor16_32_l((s), fr + 16 * fq)
;     DI void operator()(AccRef acc, const Unit& u, int wr, int wc, int fr, int fq) const {
;     ...
;         for (int ai = 0; ai < 2; ++ai) {
;             const int rb = u.pm * 256 + ai * 128 + wr * 64 + fr;
;             int mb, pos0, kv0; row_info(rb, mb, pos0, kv0);
;             f32x4 gt[2][2], gs[2][2];
; #pragma unroll
;             for (int bj = 0; bj < 2; ++bj)
; #pragma unroll
;                 for (int n = 0; n < 2; ++n) {
;                     const int c = u.pn * 256 + bj * 128 + cl + 4 * n;
;                     gt[bj][n] = *(const f32x4*)(gate + (size_t)mb * 6144 + c);
;                     if (ap) { const f32x4 g = *(const f32x4*)(gn + c), s = *(const f32x4*)(scn + (size_t)mb * 6144 + c); gs[bj][n] = g * (s + 1.f); }
;                 }
;     ...
;                 float s = 0.f;
; #pragma unroll
;                 for (int bj = 0; bj < 2; ++bj) {
;                     const int c = u.pn * 256 + bj * 128 + cl;
;                     float v[8];
; #pragma unroll
;                     for (int n = 0; n < 2; ++n) {
;                         const f32x4 x = *(const f32x4*)(xi + c + 4 * n);
;                         const f32x4 y = x + gt[bj][n] * acc[ai][bj][m][n];
;                         *(f32x4*)(xout + (size_t)row * 1024 + c + 4 * n) = y;
; #pragma unroll
;                         for (int j = 0; j < 4; ++j) { s += y[j] * y[j]; v[4 * n + j] = ap ? y[j] * gs[bj][n][j] : 0.f; }
;                     }
;                     if (ap) *(u32x4*)(ap + (size_t)row * 1024 + c) = pack8(v);
;                 }
;                 s = xor16_32(s);
;                 if (fq == 0) ssq[(size_t)row * 16 + u.pn * 4 + wc] = s;
.Lnoap_D_4:
	ds_bpermute_b32 v211, v214, v210
	v_permlane16_swap_b32_e32 v92, v88
	v_permlane16_swap_b32_e32 v93, v89
	v_permlane16_swap_b32_e32 v94, v90
	v_permlane16_swap_b32_e32 v95, v91
	v_permlane16_swap_b32_e32 v84, v80
	v_permlane16_swap_b32_e32 v85, v81
	v_permlane16_swap_b32_e32 v86, v82
	v_permlane16_swap_b32_e32 v87, v83
	v_permlane32_swap_b32_e32 v92, v88
	v_permlane32_swap_b32_e32 v93, v89
	v_permlane32_swap_b32_e32 v94, v90
	v_permlane32_swap_b32_e32 v95, v91
	v_permlane32_swap_b32_e32 v84, v80
	v_permlane32_swap_b32_e32 v85, v81
	v_permlane32_swap_b32_e32 v86, v82
	v_permlane32_swap_b32_e32 v87, v83
	s_nop 1
	v_mov_b32_dpp v248, v88 row_ror:8 row_mask:0xf bank_mask:0xf
	v_mov_b32_dpp v249, v89 row_ror:8 row_mask:0xf bank_mask:0xf
	v_mov_b32_dpp v250, v90 row_ror:8 row_mask:0xf bank_mask:0xf
	v_mov_b32_dpp v251, v91 row_ror:8 row_mask:0xf bank_mask:0xf
	v_mov_b32_dpp v220, v80 row_ror:8 row_mask:0xf bank_mask:0xf
	v_mov_b32_dpp v221, v81 row_ror:8 row_mask:0xf bank_mask:0xf
	v_mov_b32_dpp v222, v82 row_ror:8 row_mask:0xf bank_mask:0xf
	v_mov_b32_dpp v223, v83 row_ror:8 row_mask:0xf bank_mask:0xf
	s_mov_b32 vcc_lo, 0xff00ff
	s_mov_b32 vcc_hi, 0xff00ff
	v_mov_b32_e32 v204, 0xffff8040
	v_mov_b32_e32 v205, 0x8040
	v_cndmask_b32_e64 v204, v204, 0, vcc
	v_cndmask_b32_e64 v205, 0, v205, vcc
	v_add_u32_e32 v204, v204, v207
	v_add_u32_e32 v205, v205, v207
	s_mov_b32 exec_lo, 0xff00ff00
	s_mov_b32 exec_hi, 0xff00ff00
	v_swap_b32 v92, v248
	v_swap_b32 v93, v249
	v_swap_b32 v94, v250
	v_swap_b32 v95, v251
	v_swap_b32 v84, v220
	v_swap_b32 v85, v221
	v_swap_b32 v86, v222
	v_swap_b32 v87, v223
	s_mov_b64 exec, -1
	global_store_dwordx4 v204, v[92:95], s[84:85]
	global_store_dwordx4 v204, v[84:87], s[84:85] offset:512
	global_store_dwordx4 v205, v[248:251], s[84:85]
	global_store_dwordx4 v205, v[220:223], s[84:85] offset:512
	v_add_u32_e32 v207, 0x50000, v207
	v_add_u32_e32 v206, 0x10000, v206
	global_load_dwordx4 v[248:251], v206, s[70:71] offset:64
	global_load_dwordx4 v[220:223], v206, s[70:71] offset:576
	global_load_dwordx4 v[244:247], v206, s[70:71]
	global_load_dwordx4 v[216:219], v206, s[70:71] offset:512
	s_waitcnt lgkmcnt(0)
	v_add_f32_e32 v211, v210, v211
	ds_bpermute_b32 v212, v215, v211
	v_add_u32_e32 v208, 0x28000, v208
	s_waitcnt lgkmcnt(0)
	v_add_f32_e32 v211, v211, v212
	s_mov_b64 exec, 0xffff
	global_store_dword v209, v211, s[72:73]
	s_mov_b64 exec, -1
	v_add_u32_e32 v209, 0x1400, v209
	v_add_u32_e32 v224, 0xffffc080, v176
	v_add_u32_e32 v96, 0x80, v176
	s_waitcnt lgkmcnt(0)
	v_lshrrev_b32_e32 v81, 6, v224
	v_cmp_gt_i32_e32 vcc, s94, v96
	v_ashrrev_i32_e32 v80, 11, v96
	v_add_u32_e32 v81, 8, v81
	v_cndmask_b32_e32 v84, v81, v80, vcc
	v_mov_b64_e32 v[80:81], s[18:19]
	v_mad_i64_i32 v[80:81], s[12:13], v84, s75, v[80:81]
	v_mov_b64_e32 v[82:83], s[26:27]
	v_lshl_add_u64 v[92:93], v[172:173], 2, v[80:81]
	v_mad_i64_i32 v[84:85], s[12:13], v84, s75, v[82:83]
	global_load_dwordx4 v[80:83], v[92:93], off
	s_movk_i32 s6, 0x3fff
	v_cmp_lt_i32_e64 s[6:7], s6, v96
	s_and_b64 vcc, exec, s[0:1]
	s_cbranch_vccnz .LBB0_2101
	v_lshl_add_u64 v[64:65], v[84:85], 0, v[174:175]
	global_load_dwordx4 v[64:67], v[64:65], off
	s_nop 0
	global_load_dwordx4 v[86:89], v[178:179], off
	s_waitcnt vmcnt(1)
	v_pk_add_f32 v[66:67], v[66:67], 1.0 op_sel_hi:[1,0]
	v_pk_add_f32 v[64:65], v[64:65], 1.0 op_sel_hi:[1,0]
	s_waitcnt vmcnt(0)
	v_pk_mul_f32 v[66:67], v[88:89], v[66:67]
	v_pk_mul_f32 v[64:65], v[86:87], v[64:65]
	global_load_dwordx4 v[88:91], v[92:93], off offset:16
	s_and_b64 vcc, exec, s[0:1]
	v_lshl_add_u64 v[98:99], v[172:173], 2, v[84:85]
	s_cbranch_vccz .LBB0_2102

; DI u32x4 pack8(const float* v) { u32x4 w; w.x = pk2(v[0], v[1]); w.y = pk2(v[2], v[3]); w.z = pk2(v[4], v[5]); w.w = pk2(v[6], v[7]); return w; }
; #define xor16_32(s) xor16_32_l((s), fr + 16 * fq)
;     DI void operator()(AccRef acc, const Unit& u, int wr, int wc, int fr, int fq) const {
;     ...
;                 float s = 0.f;
; #pragma unroll
;                 for (int bj = 0; bj < 2; ++bj) {
;                     const int c = u.pn * 256 + bj * 128 + cl;
;                     float v[8];
; #pragma unroll
;                     for (int n = 0; n < 2; ++n) {
;                         const f32x4 x = *(const f32x4*)(xi + c + 4 * n);
;                         const f32x4 y = x + gt[bj][n] * acc[ai][bj][m][n];
;                         *(f32x4*)(xout + (size_t)row * 1024 + c + 4 * n) = y;
; #pragma unroll
;                         for (int j = 0; j < 4; ++j) { s += y[j] * y[j]; v[4 * n + j] = ap ? y[j] * gs[bj][n][j] : 0.f; }
;                     }
;                     if (ap) *(u32x4*)(ap + (size_t)row * 1024 + c) = pack8(v);
;                 }
;                 s = xor16_32(s);
;                 if (fq == 0) ssq[(size_t)row * 16 + u.pn * 4 + wc] = s;
.Lnoap_D_5:
	ds_bpermute_b32 v211, v214, v210
	v_permlane16_swap_b32_e32 v60, v56
	v_permlane16_swap_b32_e32 v61, v57
	v_permlane16_swap_b32_e32 v62, v58
	v_permlane16_swap_b32_e32 v63, v59
	v_permlane16_swap_b32_e32 v52, v48
	v_permlane16_swap_b32_e32 v53, v49
	v_permlane16_swap_b32_e32 v54, v50
	v_permlane16_swap_b32_e32 v55, v51
	v_permlane32_swap_b32_e32 v60, v56
	v_permlane32_swap_b32_e32 v61, v57
	v_permlane32_swap_b32_e32 v62, v58
	v_permlane32_swap_b32_e32 v63, v59
	v_permlane32_swap_b32_e32 v52, v48
	v_permlane32_swap_b32_e32 v53, v49
	v_permlane32_swap_b32_e32 v54, v50
	v_permlane32_swap_b32_e32 v55, v51
	s_nop 1
	v_mov_b32_dpp v232, v56 row_ror:8 row_mask:0xf bank_mask:0xf
	v_mov_b32_dpp v233, v57 row_ror:8 row_mask:0xf bank_mask:0xf
	v_mov_b32_dpp v234, v58 row_ror:8 row_mask:0xf bank_mask:0xf
	v_mov_b32_dpp v235, v59 row_ror:8 row_mask:0xf bank_mask:0xf
	v_mov_b32_dpp v240, v48 row_ror:8 row_mask:0xf bank_mask:0xf
	v_mov_b32_dpp v241, v49 row_ror:8 row_mask:0xf bank_mask:0xf
	v_mov_b32_dpp v242, v50 row_ror:8 row_mask:0xf bank_mask:0xf
	v_mov_b32_dpp v243, v51 row_ror:8 row_mask:0xf bank_mask:0xf
	s_mov_b32 vcc_lo, 0xff00ff
	s_mov_b32 vcc_hi, 0xff00ff
	v_mov_b32_e32 v204, 0xffff8040
	v_mov_b32_e32 v205, 0x8040
	v_cndmask_b32_e64 v204, v204, 0, vcc
	v_cndmask_b32_e64 v205, 0, v205, vcc
	v_add_u32_e32 v204, v204, v207
	v_add_u32_e32 v205, v205, v207
	s_mov_b32 exec_lo, 0xff00ff00
	s_mov_b32 exec_hi, 0xff00ff00
	v_swap_b32 v60, v232
	v_swap_b32 v61, v233
	v_swap_b32 v62, v234
	v_swap_b32 v63, v235
	v_swap_b32 v52, v240
	v_swap_b32 v53, v241
	v_swap_b32 v54, v242
	v_swap_b32 v55, v243
	s_mov_b64 exec, -1
	global_store_dwordx4 v204, v[60:63], s[84:85]
	global_store_dwordx4 v204, v[52:55], s[84:85] offset:512
	global_store_dwordx4 v205, v[232:235], s[84:85]
	global_store_dwordx4 v205, v[240:243], s[84:85] offset:512
	v_add_u32_e32 v207, 0x10000, v207
	v_add_u32_e32 v206, 0x10000, v206
	global_load_dwordx4 v[232:235], v206, s[70:71] offset:64
	global_load_dwordx4 v[240:243], v206, s[70:71] offset:576
	global_load_dwordx4 v[228:231], v206, s[70:71]
	global_load_dwordx4 v[236:239], v206, s[70:71] offset:512
	s_waitcnt lgkmcnt(0)
	v_add_f32_e32 v211, v210, v211
	ds_bpermute_b32 v212, v215, v211
	v_add_u32_e32 v208, 0x8000, v208
	s_waitcnt lgkmcnt(0)
	v_add_f32_e32 v211, v211, v212
	s_mov_b64 exec, 0xffff
	global_store_dword v209, v211, s[72:73]
	s_mov_b64 exec, -1
	v_add_u32_e32 v209, 0x400, v209
	v_permlane32_swap_b32_e32 v244, v248
	v_permlane32_swap_b32_e32 v245, v249
	v_permlane32_swap_b32_e32 v246, v250
	v_permlane32_swap_b32_e32 v247, v251
	v_permlane32_swap_b32_e32 v216, v220
	v_permlane32_swap_b32_e32 v217, v221
	v_permlane32_swap_b32_e32 v218, v222
	v_permlane32_swap_b32_e32 v219, v223
	v_permlane16_swap_b32_e32 v244, v248
	v_permlane16_swap_b32_e32 v245, v249
	v_permlane16_swap_b32_e32 v246, v250
	v_permlane16_swap_b32_e32 v247, v251
	v_permlane16_swap_b32_e32 v216, v220
	v_permlane16_swap_b32_e32 v217, v221
	v_permlane16_swap_b32_e32 v218, v222
	v_permlane16_swap_b32_e32 v219, v223
	v_pk_fma_f32 v[44:45], v[44:45], v[80:81], v[244:245]
	v_pk_fma_f32 v[46:47], v[46:47], v[82:83], v[246:247]
	v_mul_f32_e32 v210, v45, v45
	v_fmac_f32_e32 v210, v44, v44
	v_fmac_f32_e32 v210, v46, v46
	v_fmac_f32_e32 v210, v47, v47
	v_pk_fma_f32 v[40:41], v[40:41], v[88:89], v[248:249]
	v_pk_fma_f32 v[42:43], v[42:43], v[90:91], v[250:251]
	v_fmac_f32_e32 v210, v40, v40
	v_fmac_f32_e32 v210, v41, v41
	v_fmac_f32_e32 v210, v42, v42
	v_fmac_f32_e32 v210, v43, v43
	v_pk_fma_f32 v[36:37], v[36:37], v[84:85], v[216:217]
	v_pk_fma_f32 v[38:39], v[38:39], v[86:87], v[218:219]
	v_fmac_f32_e32 v210, v36, v36
	v_fmac_f32_e32 v210, v37, v37
	v_fmac_f32_e32 v210, v38, v38
	v_fmac_f32_e32 v210, v39, v39
	v_pk_fma_f32 v[32:33], v[32:33], v[92:93], v[220:221]
	v_pk_fma_f32 v[34:35], v[34:35], v[94:95], v[222:223]
	v_fmac_f32_e32 v210, v32, v32
	v_fmac_f32_e32 v210, v33, v33
	v_fmac_f32_e32 v210, v34, v34
	v_fmac_f32_e32 v210, v35, v35
	s_cmp_lg_u64 s[0:1], 0
	s_cbranch_scc1 .Lnoap_D_6
	v_pk_mul_f32 v[244:245], v[64:65], v[44:45]
	v_pk_mul_f32 v[246:247], v[66:67], v[46:47]
	v_pk_mul_f32 v[248:249], v[72:73], v[40:41]
	v_pk_mul_f32 v[250:251], v[74:75], v[42:43]
	v_pk_mul_f32 v[216:217], v[68:69], v[36:37]
	v_pk_mul_f32 v[218:219], v[70:71], v[38:39]
	v_pk_mul_f32 v[220:221], v[76:77], v[32:33]
	v_pk_mul_f32 v[222:223], v[78:79], v[34:35]
	v_cvt_pk_bf16_f32 v244, v244, v245
	v_cvt_pk_bf16_f32 v245, v246, v247
	v_cvt_pk_bf16_f32 v246, v248, v249
	v_cvt_pk_bf16_f32 v247, v250, v251
	global_store_dwordx4 v208, v[244:247], s[28:29]
	v_cvt_pk_bf16_f32 v216, v216, v217
	v_cvt_pk_bf16_f32 v217, v218, v219
	v_cvt_pk_bf16_f32 v218, v220, v221
	v_cvt_pk_bf16_f32 v219, v222, v223
	global_store_dwordx4 v208, v[216:219], s[28:29] offset:256
; DI u32x4 pack8(const float* v) { u32x4 w; w.x = pk2(v[0], v[1]); w.y = pk2(v[2], v[3]); w.z = pk2(v[4], v[5]); w.w = pk2(v[6], v[7]); return w; }
; #define xor16_32(s) xor16_32_l((s), fr + 16 * fq)
;     DI void operator()(AccRef acc, const Unit& u, int wr, int wc, int fr, int fq) const {
;     ...
;                 float s = 0.f;
; #pragma unroll
;                 for (int bj = 0; bj < 2; ++bj) {
;                     const int c = u.pn * 256 + bj * 128 + cl;
;                     float v[8];
; #pragma unroll
;                     for (int n = 0; n < 2; ++n) {
;                         const f32x4 x = *(const f32x4*)(xi + c + 4 * n);
;                         const f32x4 y = x + gt[bj][n] * acc[ai][bj][m][n];
;                         *(f32x4*)(xout + (size_t)row * 1024 + c + 4 * n) = y;
; #pragma unroll
;                         for (int j = 0; j < 4; ++j) { s += y[j] * y[j]; v[4 * n + j] = ap ? y[j] * gs[bj][n][j] : 0.f; }
;                     }
;                     if (ap) *(u32x4*)(ap + (size_t)row * 1024 + c) = pack8(v);
;                 }
;                 s = xor16_32(s);
;                 if (fq == 0) ssq[(size_t)row * 16 + u.pn * 4 + wc] = s;
.Lnoap_D_6:
	ds_bpermute_b32 v211, v214, v210
	v_permlane16_swap_b32_e32 v44, v40
	v_permlane16_swap_b32_e32 v45, v41
	v_permlane16_swap_b32_e32 v46, v42
	v_permlane16_swap_b32_e32 v47, v43
	v_permlane16_swap_b32_e32 v36, v32
	v_permlane16_swap_b32_e32 v37, v33
	v_permlane16_swap_b32_e32 v38, v34
	v_permlane16_swap_b32_e32 v39, v35
	v_permlane32_swap_b32_e32 v44, v40
	v_permlane32_swap_b32_e32 v45, v41
	v_permlane32_swap_b32_e32 v46, v42
	v_permlane32_swap_b32_e32 v47, v43
	v_permlane32_swap_b32_e32 v36, v32
	v_permlane32_swap_b32_e32 v37, v33
	v_permlane32_swap_b32_e32 v38, v34
	v_permlane32_swap_b32_e32 v39, v35
	s_nop 1
	v_mov_b32_dpp v248, v40 row_ror:8 row_mask:0xf bank_mask:0xf
	v_mov_b32_dpp v249, v41 row_ror:8 row_mask:0xf bank_mask:0xf
	v_mov_b32_dpp v250, v42 row_ror:8 row_mask:0xf bank_mask:0xf
	v_mov_b32_dpp v251, v43 row_ror:8 row_mask:0xf bank_mask:0xf
	v_mov_b32_dpp v220, v32 row_ror:8 row_mask:0xf bank_mask:0xf
	v_mov_b32_dpp v221, v33 row_ror:8 row_mask:0xf bank_mask:0xf
	v_mov_b32_dpp v222, v34 row_ror:8 row_mask:0xf bank_mask:0xf
	v_mov_b32_dpp v223, v35 row_ror:8 row_mask:0xf bank_mask:0xf
	s_mov_b32 vcc_lo, 0xff00ff
	s_mov_b32 vcc_hi, 0xff00ff
	v_mov_b32_e32 v204, 0xffff8040
	v_mov_b32_e32 v205, 0x8040
	v_cndmask_b32_e64 v204, v204, 0, vcc
	v_cndmask_b32_e64 v205, 0, v205, vcc
	v_add_u32_e32 v204, v204, v207
	v_add_u32_e32 v205, v205, v207
	s_mov_b32 exec_lo, 0xff00ff00
	s_mov_b32 exec_hi, 0xff00ff00
	v_swap_b32 v44, v248
	v_swap_b32 v45, v249
	v_swap_b32 v46, v250
	v_swap_b32 v47, v251
	v_swap_b32 v36, v220
	v_swap_b32 v37, v221
	v_swap_b32 v38, v222
	v_swap_b32 v39, v223
	s_mov_b64 exec, -1
	global_store_dwordx4 v204, v[44:47], s[84:85]
	global_store_dwordx4 v204, v[36:39], s[84:85] offset:512
	global_store_dwordx4 v205, v[248:251], s[84:85]
	global_store_dwordx4 v205, v[220:223], s[84:85] offset:512
	v_add_u32_e32 v207, 0x10000, v207
	v_add_u32_e32 v206, 0x10000, v206
	global_load_dwordx4 v[248:251], v206, s[70:71] offset:64
	global_load_dwordx4 v[220:223], v206, s[70:71] offset:576
	global_load_dwordx4 v[244:247], v206, s[70:71]
	global_load_dwordx4 v[216:219], v206, s[70:71] offset:512
	s_waitcnt lgkmcnt(0)
	v_add_f32_e32 v211, v210, v211
	ds_bpermute_b32 v212, v215, v211
	v_add_u32_e32 v208, 0x8000, v208
	s_waitcnt lgkmcnt(0)
	v_add_f32_e32 v211, v211, v212
	s_mov_b64 exec, 0xffff
	global_store_dword v209, v211, s[72:73]
	s_mov_b64 exec, -1
	v_add_u32_e32 v209, 0x400, v209
	s_waitcnt vmcnt(10)
	v_permlane32_swap_b32_e32 v228, v232
	v_permlane32_swap_b32_e32 v229, v233
	v_permlane32_swap_b32_e32 v230, v234
	v_permlane32_swap_b32_e32 v231, v235
	v_permlane32_swap_b32_e32 v236, v240
	v_permlane32_swap_b32_e32 v237, v241
	v_permlane32_swap_b32_e32 v238, v242
	v_permlane32_swap_b32_e32 v239, v243
	v_permlane16_swap_b32_e32 v228, v232
	v_permlane16_swap_b32_e32 v229, v233
	v_permlane16_swap_b32_e32 v230, v234
	v_permlane16_swap_b32_e32 v231, v235
	v_permlane16_swap_b32_e32 v236, v240
	v_permlane16_swap_b32_e32 v237, v241
	v_permlane16_swap_b32_e32 v238, v242
	v_permlane16_swap_b32_e32 v239, v243
	v_pk_fma_f32 v[28:29], v[28:29], v[80:81], v[228:229]
	v_pk_fma_f32 v[30:31], v[30:31], v[82:83], v[230:231]
	v_mul_f32_e32 v210, v29, v29
	v_fmac_f32_e32 v210, v28, v28
	v_fmac_f32_e32 v210, v30, v30
	v_fmac_f32_e32 v210, v31, v31
	v_pk_fma_f32 v[24:25], v[24:25], v[88:89], v[232:233]
	v_pk_fma_f32 v[26:27], v[26:27], v[90:91], v[234:235]
	v_fmac_f32_e32 v210, v24, v24
	v_fmac_f32_e32 v210, v25, v25
	v_fmac_f32_e32 v210, v26, v26
	v_fmac_f32_e32 v210, v27, v27
	v_pk_fma_f32 v[20:21], v[20:21], v[84:85], v[236:237]
	v_pk_fma_f32 v[22:23], v[22:23], v[86:87], v[238:239]
	v_fmac_f32_e32 v210, v20, v20
	v_fmac_f32_e32 v210, v21, v21
	v_fmac_f32_e32 v210, v22, v22
	v_fmac_f32_e32 v210, v23, v23
	v_pk_fma_f32 v[16:17], v[16:17], v[92:93], v[240:241]
	v_pk_fma_f32 v[18:19], v[18:19], v[94:95], v[242:243]
	v_fmac_f32_e32 v210, v16, v16
	v_fmac_f32_e32 v210, v17, v17
	v_fmac_f32_e32 v210, v18, v18
	v_fmac_f32_e32 v210, v19, v19
	s_cmp_lg_u64 s[0:1], 0
	s_cbranch_scc1 .Lnoap_D_7
	v_pk_mul_f32 v[228:229], v[64:65], v[28:29]
	v_pk_mul_f32 v[230:231], v[66:67], v[30:31]
	v_pk_mul_f32 v[232:233], v[72:73], v[24:25]
	v_pk_mul_f32 v[234:235], v[74:75], v[26:27]
	v_pk_mul_f32 v[236:237], v[68:69], v[20:21]
	v_pk_mul_f32 v[238:239], v[70:71], v[22:23]
	v_pk_mul_f32 v[240:241], v[76:77], v[16:17]
	v_pk_mul_f32 v[242:243], v[78:79], v[18:19]
	v_cvt_pk_bf16_f32 v228, v228, v229
	v_cvt_pk_bf16_f32 v229, v230, v231
	v_cvt_pk_bf16_f32 v230, v232, v233
	v_cvt_pk_bf16_f32 v231, v234, v235
	global_store_dwordx4 v208, v[228:231], s[28:29]
	v_cvt_pk_bf16_f32 v236, v236, v237
	v_cvt_pk_bf16_f32 v237, v238, v239
	v_cvt_pk_bf16_f32 v238, v240, v241
	v_cvt_pk_bf16_f32 v239, v242, v243
	global_store_dwordx4 v208, v[236:239], s[28:29] offset:256
; DI u32x4 pack8(const float* v) { u32x4 w; w.x = pk2(v[0], v[1]); w.y = pk2(v[2], v[3]); w.z = pk2(v[4], v[5]); w.w = pk2(v[6], v[7]); return w; }
; #define xor16_32(s) xor16_32_l((s), fr + 16 * fq)
; #define PG8_BAR __builtin_amdgcn_s_barrier()
; template <class Epi, bool ALIGN_EPI, bool SP2>
; DI void gemm_phase(int g_wave, LAS unsigned char* lds, const Gemm g, const StaticOrder& S, const Epi& E) {
;     ...
;         if (!has_next) break;
; #pragma unroll
;         for (int a = 0; a < 2; ++a)
; #pragma unroll
;             for (int b = 0; b < 2; ++b)
; #pragma unroll
;                 for (int m = 0; m < 4; ++m)
; #pragma unroll
;                     for (int n = 0; n < 2; ++n) acc[a][b][m][n] = (f32x4){0.f, 0.f, 0.f, 0.f};
;         cur = nxt; cA = nA; cB = nB; ++ui;
;         if constexpr (ALIGN_EPI) { if (wr == 1) PG8_BAR; }
;     DI void operator()(AccRef acc, const Unit& u, int wr, int wc, int fr, int fq) const {
;     ...
;                 float s = 0.f;
; #pragma unroll
;                 for (int bj = 0; bj < 2; ++bj) {
;                     const int c = u.pn * 256 + bj * 128 + cl;
;                     float v[8];
; #pragma unroll
;                     for (int n = 0; n < 2; ++n) {
;                         const f32x4 x = *(const f32x4*)(xi + c + 4 * n);
;                         const f32x4 y = x + gt[bj][n] * acc[ai][bj][m][n];
;                         *(f32x4*)(xout + (size_t)row * 1024 + c + 4 * n) = y;
; #pragma unroll
;                         for (int j = 0; j < 4; ++j) { s += y[j] * y[j]; v[4 * n + j] = ap ? y[j] * gs[bj][n][j] : 0.f; }
;                     }
;                     if (ap) *(u32x4*)(ap + (size_t)row * 1024 + c) = pack8(v);
;                 }
;                 s = xor16_32(s);
;                 if (fq == 0) ssq[(size_t)row * 16 + u.pn * 4 + wc] = s;
.Lnoap_D_7:
	ds_bpermute_b32 v211, v214, v210
	v_permlane16_swap_b32_e32 v28, v24
	v_permlane16_swap_b32_e32 v29, v25
	v_permlane16_swap_b32_e32 v30, v26
	v_permlane16_swap_b32_e32 v31, v27
	v_permlane16_swap_b32_e32 v20, v16
	v_permlane16_swap_b32_e32 v21, v17
	v_permlane16_swap_b32_e32 v22, v18
	v_permlane16_swap_b32_e32 v23, v19
	v_permlane32_swap_b32_e32 v28, v24
	v_permlane32_swap_b32_e32 v29, v25
	v_permlane32_swap_b32_e32 v30, v26
	v_permlane32_swap_b32_e32 v31, v27
	v_permlane32_swap_b32_e32 v20, v16
	v_permlane32_swap_b32_e32 v21, v17
	v_permlane32_swap_b32_e32 v22, v18
	v_permlane32_swap_b32_e32 v23, v19
	s_nop 1
	v_mov_b32_dpp v232, v24 row_ror:8 row_mask:0xf bank_mask:0xf
	v_mov_b32_dpp v233, v25 row_ror:8 row_mask:0xf bank_mask:0xf
	v_mov_b32_dpp v234, v26 row_ror:8 row_mask:0xf bank_mask:0xf
	v_mov_b32_dpp v235, v27 row_ror:8 row_mask:0xf bank_mask:0xf
	v_mov_b32_dpp v240, v16 row_ror:8 row_mask:0xf bank_mask:0xf
	v_mov_b32_dpp v241, v17 row_ror:8 row_mask:0xf bank_mask:0xf
	v_mov_b32_dpp v242, v18 row_ror:8 row_mask:0xf bank_mask:0xf
	v_mov_b32_dpp v243, v19 row_ror:8 row_mask:0xf bank_mask:0xf
	s_mov_b32 vcc_lo, 0xff00ff
	s_mov_b32 vcc_hi, 0xff00ff
	v_mov_b32_e32 v204, 0xffff8040
	v_mov_b32_e32 v205, 0x8040
	v_cndmask_b32_e64 v204, v204, 0, vcc
	v_cndmask_b32_e64 v205, 0, v205, vcc
	v_add_u32_e32 v204, v204, v207
	v_add_u32_e32 v205, v205, v207
	s_mov_b32 exec_lo, 0xff00ff00
	s_mov_b32 exec_hi, 0xff00ff00
	v_swap_b32 v28, v232
	v_swap_b32 v29, v233
	v_swap_b32 v30, v234
	v_swap_b32 v31, v235
	v_swap_b32 v20, v240
	v_swap_b32 v21, v241
	v_swap_b32 v22, v242
	v_swap_b32 v23, v243
	s_mov_b64 exec, -1
	global_store_dwordx4 v204, v[28:31], s[84:85]
	global_store_dwordx4 v204, v[20:23], s[84:85] offset:512
	global_store_dwordx4 v205, v[232:235], s[84:85]
	global_store_dwordx4 v205, v[240:243], s[84:85] offset:512
	v_add_u32_e32 v207, 0x10000, v207
	s_waitcnt lgkmcnt(0)
	v_add_f32_e32 v211, v210, v211
	ds_bpermute_b32 v212, v215, v211
	v_add_u32_e32 v208, 0x8000, v208
	s_waitcnt lgkmcnt(0)
	v_add_f32_e32 v211, v211, v212
	s_mov_b64 exec, 0xffff
	global_store_dword v209, v211, s[72:73]
	s_mov_b64 exec, -1
	v_add_u32_e32 v209, 0x400, v209
	s_waitcnt vmcnt(6)
	v_permlane32_swap_b32_e32 v244, v248
	v_permlane32_swap_b32_e32 v245, v249
	v_permlane32_swap_b32_e32 v246, v250
	v_permlane32_swap_b32_e32 v247, v251
	v_permlane32_swap_b32_e32 v216, v220
	v_permlane32_swap_b32_e32 v217, v221
	v_permlane32_swap_b32_e32 v218, v222
	v_permlane32_swap_b32_e32 v219, v223
	v_permlane16_swap_b32_e32 v244, v248
	v_permlane16_swap_b32_e32 v245, v249
	v_permlane16_swap_b32_e32 v246, v250
	v_permlane16_swap_b32_e32 v247, v251
	v_permlane16_swap_b32_e32 v216, v220
	v_permlane16_swap_b32_e32 v217, v221
	v_permlane16_swap_b32_e32 v218, v222
	v_permlane16_swap_b32_e32 v219, v223
	v_pk_fma_f32 v[12:13], v[12:13], v[80:81], v[244:245]
	v_pk_fma_f32 v[14:15], v[14:15], v[82:83], v[246:247]
	v_mul_f32_e32 v210, v13, v13
	v_fmac_f32_e32 v210, v12, v12
	v_fmac_f32_e32 v210, v14, v14
	v_fmac_f32_e32 v210, v15, v15
	v_pk_fma_f32 v[8:9], v[8:9], v[88:89], v[248:249]
	v_pk_fma_f32 v[10:11], v[10:11], v[90:91], v[250:251]
	v_fmac_f32_e32 v210, v8, v8
	v_fmac_f32_e32 v210, v9, v9
	v_fmac_f32_e32 v210, v10, v10
	v_fmac_f32_e32 v210, v11, v11
	v_pk_fma_f32 v[4:5], v[4:5], v[84:85], v[216:217]
	v_pk_fma_f32 v[6:7], v[6:7], v[86:87], v[218:219]
	v_fmac_f32_e32 v210, v4, v4
	v_fmac_f32_e32 v210, v5, v5
	v_fmac_f32_e32 v210, v6, v6
	v_fmac_f32_e32 v210, v7, v7
	v_pk_fma_f32 v[0:1], v[0:1], v[92:93], v[220:221]
	v_pk_fma_f32 v[2:3], v[2:3], v[94:95], v[222:223]
	v_fmac_f32_e32 v210, v0, v0
	v_fmac_f32_e32 v210, v1, v1
	v_fmac_f32_e32 v210, v2, v2
	v_fmac_f32_e32 v210, v3, v3
	s_cmp_lg_u64 s[0:1], 0
	s_cbranch_scc1 .Lnoap_D_8
	v_pk_mul_f32 v[244:245], v[64:65], v[12:13]
	v_pk_mul_f32 v[246:247], v[66:67], v[14:15]
	v_pk_mul_f32 v[248:249], v[72:73], v[8:9]
	v_pk_mul_f32 v[250:251], v[74:75], v[10:11]
	v_pk_mul_f32 v[216:217], v[68:69], v[4:5]
	v_pk_mul_f32 v[218:219], v[70:71], v[6:7]
	v_pk_mul_f32 v[220:221], v[76:77], v[0:1]
	v_pk_mul_f32 v[222:223], v[78:79], v[2:3]
	v_cvt_pk_bf16_f32 v244, v244, v245
	v_cvt_pk_bf16_f32 v245, v246, v247
	v_cvt_pk_bf16_f32 v246, v248, v249
	v_cvt_pk_bf16_f32 v247, v250, v251
	global_store_dwordx4 v208, v[244:247], s[28:29]
	v_cvt_pk_bf16_f32 v216, v216, v217
	v_cvt_pk_bf16_f32 v217, v218, v219
	v_cvt_pk_bf16_f32 v218, v220, v221
	v_cvt_pk_bf16_f32 v219, v222, v223
	global_store_dwordx4 v208, v[216:219], s[28:29] offset:256
.Lnoap_D_8:
	ds_bpermute_b32 v211, v214, v210
	v_permlane16_swap_b32_e32 v12, v8
	v_permlane16_swap_b32_e32 v13, v9
	v_permlane16_swap_b32_e32 v14, v10
	v_permlane16_swap_b32_e32 v15, v11
	v_permlane16_swap_b32_e32 v4, v0
	v_permlane16_swap_b32_e32 v5, v1
	v_permlane16_swap_b32_e32 v6, v2
	v_permlane16_swap_b32_e32 v7, v3
	v_permlane32_swap_b32_e32 v12, v8
	v_permlane32_swap_b32_e32 v13, v9
	v_permlane32_swap_b32_e32 v14, v10
	v_permlane32_swap_b32_e32 v15, v11
	v_permlane32_swap_b32_e32 v4, v0
	v_permlane32_swap_b32_e32 v5, v1
	v_permlane32_swap_b32_e32 v6, v2
	v_permlane32_swap_b32_e32 v7, v3
	s_nop 1
	v_mov_b32_dpp v248, v8 row_ror:8 row_mask:0xf bank_mask:0xf
	v_mov_b32_dpp v249, v9 row_ror:8 row_mask:0xf bank_mask:0xf
	v_mov_b32_dpp v250, v10 row_ror:8 row_mask:0xf bank_mask:0xf
	v_mov_b32_dpp v251, v11 row_ror:8 row_mask:0xf bank_mask:0xf
	v_mov_b32_dpp v220, v0 row_ror:8 row_mask:0xf bank_mask:0xf
	v_mov_b32_dpp v221, v1 row_ror:8 row_mask:0xf bank_mask:0xf
	v_mov_b32_dpp v222, v2 row_ror:8 row_mask:0xf bank_mask:0xf
	v_mov_b32_dpp v223, v3 row_ror:8 row_mask:0xf bank_mask:0xf
	s_mov_b32 vcc_lo, 0xff00ff
	s_mov_b32 vcc_hi, 0xff00ff
	v_mov_b32_e32 v204, 0xffff8040
	v_mov_b32_e32 v205, 0x8040
	v_cndmask_b32_e64 v204, v204, 0, vcc
	v_cndmask_b32_e64 v205, 0, v205, vcc
	v_add_u32_e32 v204, v204, v207
	v_add_u32_e32 v205, v205, v207
	s_mov_b32 exec_lo, 0xff00ff00
	s_mov_b32 exec_hi, 0xff00ff00
	v_swap_b32 v12, v248
	v_swap_b32 v13, v249
	v_swap_b32 v14, v250
	v_swap_b32 v15, v251
	v_swap_b32 v4, v220
	v_swap_b32 v5, v221
	v_swap_b32 v6, v222
	v_swap_b32 v7, v223
	s_mov_b64 exec, -1
	global_store_dwordx4 v204, v[12:15], s[84:85]
	global_store_dwordx4 v204, v[4:7], s[84:85] offset:512
	global_store_dwordx4 v205, v[248:251], s[84:85]
	global_store_dwordx4 v205, v[220:223], s[84:85] offset:512
	s_waitcnt lgkmcnt(0)
	v_add_f32_e32 v211, v210, v211
	ds_bpermute_b32 v212, v215, v211
	s_waitcnt lgkmcnt(0)
	v_add_f32_e32 v211, v211, v212
	s_mov_b64 exec, 0xffff
	global_store_dword v209, v211, s[72:73]
	s_mov_b64 exec, -1
	s_and_b64 vcc, exec, s[2:3]
	s_mov_b64 s[2:3], -1
	s_cbranch_vccnz .LBB0_2034
	s_andn2_b64 vcc, exec, s[8:9]
	s_cbranch_vccnz .LBB0_2033
	s_barrier
	s_branch .LBB0_2033
